# v31 + packed f32 VALU ops in GEMM epilogues split into scalar f32 pairs (bit-identical)
# speedup vs baseline: 1.0202x; 1.0089x over previous
; __device__ __forceinline__ unsigned cvt_pk_bf16(float lo, float hi) { unsigned r; asm volatile("v_cvt_pk_bf16_f32 %0, %1, %2" : "=v"(r) : "v"(lo), "v"(hi)); return r; }
; DI float shx(float v, int mask, int lane) { return __int_as_float(__builtin_amdgcn_ds_bpermute((lane ^ mask) << 2, __float_as_int(v))); }
;     DI void operator()(const f32x4 (&acc)[2][2][4][2], const Unit& u, int wr, int wc, int fr, int fq) const {
;     ...
;             for (int m = 0; m < 4; ++m) { const int row = row0 + ai * 128 + m * 16; const float s = rs[row]; bf16_t* rowp = O + (size_t)row * 2048 + col0;
;                 f32x4 v[2][2];
; #pragma unroll
;                 for (int bj = 0; bj < 2; ++bj) { v[bj][0] = acc[ai][bj][m][0] * s; v[bj][1] = acc[ai][bj][m][1] * s; u32x4 w;
;                     w.x = cvt_pk_bf16(v[bj][0][0], v[bj][0][1]); w.y = cvt_pk_bf16(v[bj][0][2], v[bj][0][3]); w.z = cvt_pk_bf16(v[bj][1][0], v[bj][1][1]); w.w = cvt_pk_bf16(v[bj][1][2], v[bj][1][3]);
;                     *(u32x4*)(rowp + bj * 128) = w; }
;                 if (pn < 2) {
;                     float s0 = 0.f, s1 = 0.f;
; #pragma unroll
;                     for (int n = 0; n < 2; ++n) { s0 += (v[0][n][0] * v[0][n][0] + v[0][n][1] * v[0][n][1]) + (v[0][n][2] * v[0][n][2] + v[0][n][3] * v[0][n][3]);
;                                                   s1 += (v[1][n][0] * v[1][n][0] + v[1][n][1] * v[1][n][1]) + (v[1][n][2] * v[1][n][2] + v[1][n][3] * v[1][n][3]); }
;                     if (pn == 0) { float ss = s0 + s1; ss += shx(ss, 16, ln); ss += shx(ss, 32, ln); if (fq == 0) ssq4[(size_t)row * 4 + wc] = ss; }
;                     else { s0 += shx(s0, 16, ln); s0 += shx(s0, 32, ln); if (fq == 0) sskv4[(size_t)row * 4 + wc] = s0;
;                         if (wc < 2) { s1 += shx(s1, 16, ln); s1 += shx(s1, 32, ln); if (fq == 0) sskr2[(size_t)row * 2 + wc] = s1;
.LBB0_1651:
	v_lshl_add_u64 v[158:159], v[154:155], 2, s[18:19]
	global_load_dword v136, v[158:159], off
	v_lshl_or_b32 v156, s48, 8, v181
	s_cmp_lt_i32 s48, 2
	v_lshlrev_b64 v[160:161], 12, v[154:155]
	v_ashrrev_i32_e32 v157, 31, v156
	s_cselect_b64 s[6:7], -1, 0
	s_cmp_lg_u32 s48, 0
	v_lshl_add_u64 v[160:161], s[14:15], 0, v[160:161]
	s_cselect_b64 s[8:9], -1, 0
	s_cmp_gt_i32 s48, 1
	v_lshl_add_u64 v[176:177], v[156:157], 1, v[160:161]
	s_waitcnt vmcnt(0)
	v_mul_f32_e32 v172, v126, v136
	v_mul_f32_e32 v173, v127, v136
	v_mul_f32_e32 v174, v124, v136
	v_mul_f32_e32 v175, v125, v136
	v_mul_f32_e32 v168, v122, v136
	v_mul_f32_e32 v169, v123, v136
	v_mul_f32_e32 v170, v120, v136
	v_mul_f32_e32 v171, v121, v136
	v_mul_f32_e32 v160, v118, v136
	v_mul_f32_e32 v161, v119, v136
	v_mul_f32_e32 v162, v116, v136
	v_mul_f32_e32 v163, v117, v136
	v_mul_f32_e32 v164, v114, v136
	v_mul_f32_e32 v165, v115, v136
	v_mul_f32_e32 v166, v112, v136
	v_mul_f32_e32 v167, v113, v136
	v_cvt_pk_bf16_f32 v188, v174, v175
	v_cvt_pk_bf16_f32 v189, v172, v173
	v_cvt_pk_bf16_f32 v190, v170, v171
	v_cvt_pk_bf16_f32 v191, v168, v169
	global_store_dwordx4 v[176:177], v[188:191], off
	s_nop 1
	v_cvt_pk_bf16_f32 v188, v162, v163
	v_cvt_pk_bf16_f32 v189, v160, v161
	v_cvt_pk_bf16_f32 v190, v166, v167
	v_cvt_pk_bf16_f32 v191, v164, v165
	global_store_dwordx4 v[176:177], v[188:191], off offset:256
	s_cbranch_scc1 .LBB0_1664
	v_mul_f32_e32 v136, v175, v175
	v_mul_f32_e32 v173, v173, v173
	v_mul_f32_e32 v171, v171, v171
	v_mul_f32_e32 v169, v169, v169
	v_fmac_f32_e32 v136, v174, v174
	v_fmac_f32_e32 v173, v172, v172
	v_fmac_f32_e32 v171, v170, v170
	v_fmac_f32_e32 v169, v168, v168
	v_add_f32_e32 v136, v136, v173
	v_add_f32_e32 v168, v171, v169
	v_mul_f32_e32 v172, v163, v163
	v_mul_f32_e32 v173, v161, v161
	v_add_f32_e32 v168, v136, v168
	v_mul_f32_e32 v136, v167, v167
	v_mul_f32_e32 v169, v165, v165
	v_fmac_f32_e32 v172, v162, v162
	v_fmac_f32_e32 v173, v160, v160
	v_fmac_f32_e32 v136, v166, v166
	v_fmac_f32_e32 v169, v164, v164
	v_add_f32_e32 v172, v172, v173
	v_add_f32_e32 v136, v136, v169
	v_add_f32_e32 v169, v172, v136
	s_and_b64 vcc, exec, s[8:9]
	s_cbranch_vccz .LBB0_1660
	ds_bpermute_b32 v136, v179, v168
	s_waitcnt lgkmcnt(0)
	v_add_f32_e32 v136, v168, v136
	ds_bpermute_b32 v170, v180, v136
	s_and_saveexec_b64 s[76:77], s[0:1]
	s_cbranch_execz .LBB0_1655
	v_lshl_add_u64 v[172:173], v[154:155], 4, s[60:61]
	s_waitcnt lgkmcnt(0)
	v_add_f32_e32 v136, v136, v170
	global_store_dword v[172:173], v136, off

;     DI void operator()(const f32x4 (&acc)[2][2][4][2], const Unit& u, int wr, int wc, int fr, int fq) const {
;     ...
;                             const int i0 = 16 * wc + 4 * fq, pos = row & (SEQ - 1); const f32x4 c = *(const f32x4*)(cs + pos * 32 + i0), sv = *(const f32x4*)(sn + pos * 32 + i0);
;                             *(f32x4*)(KR + (size_t)row * 64 + i0) = v[1][0] * c - v[1][1] * sv; *(f32x4*)(KR + (size_t)row * 64 + 32 + i0) = v[1][1] * c + v[1][0] * sv; } } } }
.LBB0_1658:
	s_or_b64 exec, exec, s[76:77]
	v_lshlrev_b32_e32 v136, 7, v154
	v_and_b32_e32 v136, 0x7e780, v136
	s_waitcnt lgkmcnt(0)
	v_lshl_add_u64 v[170:171], v[142:143], 0, v[136:137]
	global_load_dwordx4 v[170:173], v[170:171], off
	v_lshl_add_u64 v[174:175], v[140:141], 0, v[136:137]
	global_load_dwordx4 v[174:177], v[174:175], off
	v_lshlrev_b64 v[188:189], 8, v[154:155]
	v_lshl_add_u64 v[188:189], v[144:145], 0, v[188:189]
	s_waitcnt vmcnt(1)
	v_mul_f32_e32 v190, v164, v172
	v_mul_f32_e32 v191, v165, v173
	v_mul_f32_e32 v192, v166, v170
	v_mul_f32_e32 v193, v167, v171
	v_mul_f32_e32 v194, v160, v172
	v_mul_f32_e32 v195, v161, v173
	v_mul_f32_e32 v196, v162, v170
	v_mul_f32_e32 v197, v163, v171
	s_waitcnt vmcnt(0)
	v_pk_fma_f32 v[172:173], v[160:161], v[176:177], v[190:191] neg_lo:[0,0,1] neg_hi:[0,0,1]
	v_pk_fma_f32 v[170:171], v[162:163], v[174:175], v[192:193] neg_lo:[0,0,1] neg_hi:[0,0,1]
	v_fma_f32 v162, v164, v176, v194
	v_fma_f32 v163, v165, v177, v195
	v_fma_f32 v160, v166, v174, v196
	v_fma_f32 v161, v167, v175, v197
	global_store_dwordx4 v[188:189], v[170:173], off
	global_store_dwordx4 v[188:189], v[160:163], off offset:128

; __device__ __forceinline__ unsigned cvt_pk_bf16(float lo, float hi) { unsigned r; asm volatile("v_cvt_pk_bf16_f32 %0, %1, %2" : "=v"(r) : "v"(lo), "v"(hi)); return r; }
; DI float shx(float v, int mask, int lane) { return __int_as_float(__builtin_amdgcn_ds_bpermute((lane ^ mask) << 2, __float_as_int(v))); }
;     DI void operator()(const f32x4 (&acc)[2][2][4][2], const Unit& u, int wr, int wc, int fr, int fq) const {
;     ...
;             for (int m = 0; m < 4; ++m) { const int row = row0 + ai * 128 + m * 16; const float s = rs[row]; bf16_t* rowp = O + (size_t)row * 2048 + col0;
;                 f32x4 v[2][2];
; #pragma unroll
;                 for (int bj = 0; bj < 2; ++bj) { v[bj][0] = acc[ai][bj][m][0] * s; v[bj][1] = acc[ai][bj][m][1] * s; u32x4 w;
;                     w.x = cvt_pk_bf16(v[bj][0][0], v[bj][0][1]); w.y = cvt_pk_bf16(v[bj][0][2], v[bj][0][3]); w.z = cvt_pk_bf16(v[bj][1][0], v[bj][1][1]); w.w = cvt_pk_bf16(v[bj][1][2], v[bj][1][3]);
;                     *(u32x4*)(rowp + bj * 128) = w; }
;                 if (pn < 2) {
;                     float s0 = 0.f, s1 = 0.f;
; #pragma unroll
;                     for (int n = 0; n < 2; ++n) { s0 += (v[0][n][0] * v[0][n][0] + v[0][n][1] * v[0][n][1]) + (v[0][n][2] * v[0][n][2] + v[0][n][3] * v[0][n][3]);
;                                                   s1 += (v[1][n][0] * v[1][n][0] + v[1][n][1] * v[1][n][1]) + (v[1][n][2] * v[1][n][2] + v[1][n][3] * v[1][n][3]); }
;                     if (pn == 0) { float ss = s0 + s1; ss += shx(ss, 16, ln); ss += shx(ss, 32, ln); if (fq == 0) ssq4[(size_t)row * 4 + wc] = ss; }
;                     else { s0 += shx(s0, 16, ln); s0 += shx(s0, 32, ln); if (fq == 0) sskv4[(size_t)row * 4 + wc] = s0;
;                         if (wc < 2) { s1 += shx(s1, 16, ln); s1 += shx(s1, 32, ln); if (fq == 0) sskr2[(size_t)row * 2 + wc] = s1;
.LBB0_1664:
	s_waitcnt lgkmcnt(0)
	v_or_b32_e32 v160, 16, v154
	v_ashrrev_i32_e32 v161, 31, v160
	v_lshl_add_u64 v[162:163], v[160:161], 2, s[18:19]
	global_load_dword v136, v[162:163], off
	v_cndmask_b32_e64 v162, 0, 1, s[6:7]
	v_cndmask_b32_e64 v187, 0, 1, s[8:9]
	v_cmp_ne_u32_e64 s[8:9], 1, v162
	v_lshlrev_b64 v[162:163], 12, v[160:161]
	v_lshl_add_u64 v[162:163], s[14:15], 0, v[162:163]
	s_andn2_b64 vcc, exec, s[6:7]
	v_lshl_add_u64 v[192:193], v[156:157], 1, v[162:163]
	v_cmp_ne_u32_e64 s[6:7], 1, v187
	s_waitcnt vmcnt(0)
	v_mul_f32_e32 v174, v110, v136
	v_mul_f32_e32 v175, v111, v136
	v_mul_f32_e32 v176, v108, v136
	v_mul_f32_e32 v177, v109, v136
	v_mul_f32_e32 v170, v106, v136
	v_mul_f32_e32 v171, v107, v136
	v_mul_f32_e32 v172, v104, v136
	v_mul_f32_e32 v173, v105, v136
	v_mul_f32_e32 v162, v102, v136
	v_mul_f32_e32 v163, v103, v136
	v_mul_f32_e32 v168, v100, v136
	v_mul_f32_e32 v169, v101, v136
	v_mul_f32_e32 v164, v98, v136
	v_mul_f32_e32 v165, v99, v136
	v_mul_f32_e32 v166, v96, v136
	v_mul_f32_e32 v167, v97, v136
	v_cvt_pk_bf16_f32 v188, v176, v177
	v_cvt_pk_bf16_f32 v189, v174, v175
	v_cvt_pk_bf16_f32 v190, v172, v173
	v_cvt_pk_bf16_f32 v191, v170, v171
	global_store_dwordx4 v[192:193], v[188:191], off
	s_nop 1
	v_cvt_pk_bf16_f32 v188, v168, v169
	v_cvt_pk_bf16_f32 v189, v162, v163
	v_cvt_pk_bf16_f32 v190, v166, v167
	v_cvt_pk_bf16_f32 v191, v164, v165
	global_store_dwordx4 v[192:193], v[188:191], off offset:256
	s_cbranch_vccnz .LBB0_1677
	v_mul_f32_e32 v136, v177, v177
	v_mul_f32_e32 v175, v175, v175
	v_mul_f32_e32 v173, v173, v173
	v_mul_f32_e32 v171, v171, v171
	v_fmac_f32_e32 v136, v176, v176
	v_fmac_f32_e32 v175, v174, v174
	v_fmac_f32_e32 v173, v172, v172
	v_fmac_f32_e32 v171, v170, v170
	v_add_f32_e32 v136, v136, v175
	v_add_f32_e32 v170, v173, v171
	v_mul_f32_e32 v174, v169, v169
	v_mul_f32_e32 v175, v163, v163
	v_add_f32_e32 v170, v136, v170
	v_mul_f32_e32 v136, v167, v167
	v_mul_f32_e32 v171, v165, v165
	v_fmac_f32_e32 v174, v168, v168
	v_fmac_f32_e32 v175, v162, v162
	v_fmac_f32_e32 v136, v166, v166
	v_fmac_f32_e32 v171, v164, v164
	v_add_f32_e32 v174, v174, v175
	v_add_f32_e32 v136, v136, v171
	s_and_b64 vcc, exec, s[6:7]
	v_add_f32_e32 v171, v174, v136
	s_cbranch_vccnz .LBB0_1673
	ds_bpermute_b32 v136, v179, v170
	s_waitcnt lgkmcnt(0)
	v_add_f32_e32 v136, v170, v136
	ds_bpermute_b32 v172, v180, v136
	s_and_saveexec_b64 s[76:77], s[0:1]
	s_cbranch_execz .LBB0_1668
	v_lshl_add_u64 v[174:175], v[160:161], 4, s[60:61]
	s_waitcnt lgkmcnt(0)
	v_add_f32_e32 v136, v136, v172
	global_store_dword v[174:175], v136, off

;     DI void operator()(const f32x4 (&acc)[2][2][4][2], const Unit& u, int wr, int wc, int fr, int fq) const {
;     ...
;                             const int i0 = 16 * wc + 4 * fq, pos = row & (SEQ - 1); const f32x4 c = *(const f32x4*)(cs + pos * 32 + i0), sv = *(const f32x4*)(sn + pos * 32 + i0);
;                             *(f32x4*)(KR + (size_t)row * 64 + i0) = v[1][0] * c - v[1][1] * sv; *(f32x4*)(KR + (size_t)row * 64 + 32 + i0) = v[1][1] * c + v[1][0] * sv; } } } }
.LBB0_1671:
	s_or_b64 exec, exec, s[76:77]
	v_lshlrev_b32_e32 v136, 7, v160
	v_and_b32_e32 v136, 0x7ef80, v136
	s_waitcnt lgkmcnt(0)
	v_lshl_add_u64 v[172:173], v[142:143], 0, v[136:137]
	global_load_dwordx4 v[172:175], v[172:173], off
	v_lshl_add_u64 v[176:177], v[140:141], 0, v[136:137]
	global_load_dwordx4 v[188:191], v[176:177], off
	v_lshlrev_b64 v[176:177], 8, v[160:161]
	v_lshl_add_u64 v[176:177], v[144:145], 0, v[176:177]
	s_waitcnt vmcnt(1)
	v_mul_f32_e32 v192, v164, v174
	v_mul_f32_e32 v193, v165, v175
	v_mul_f32_e32 v194, v166, v172
	v_mul_f32_e32 v195, v167, v173
	v_mul_f32_e32 v196, v162, v174
	v_mul_f32_e32 v197, v163, v175
	v_mul_f32_e32 v198, v168, v172
	v_mul_f32_e32 v199, v169, v173
	s_waitcnt vmcnt(0)
	v_pk_fma_f32 v[174:175], v[162:163], v[190:191], v[192:193] neg_lo:[0,0,1] neg_hi:[0,0,1]
	v_pk_fma_f32 v[172:173], v[168:169], v[188:189], v[194:195] neg_lo:[0,0,1] neg_hi:[0,0,1]
	v_fma_f32 v164, v164, v190, v196
	v_fma_f32 v165, v165, v191, v197
	v_fma_f32 v162, v166, v188, v198
	v_fma_f32 v163, v167, v189, v199
	global_store_dwordx4 v[176:177], v[172:175], off
	global_store_dwordx4 v[176:177], v[162:165], off offset:128

; __device__ __forceinline__ unsigned cvt_pk_bf16(float lo, float hi) { unsigned r; asm volatile("v_cvt_pk_bf16_f32 %0, %1, %2" : "=v"(r) : "v"(lo), "v"(hi)); return r; }
; DI float shx(float v, int mask, int lane) { return __int_as_float(__builtin_amdgcn_ds_bpermute((lane ^ mask) << 2, __float_as_int(v))); }
;     DI void operator()(const f32x4 (&acc)[2][2][4][2], const Unit& u, int wr, int wc, int fr, int fq) const {
;     ...
;             for (int m = 0; m < 4; ++m) { const int row = row0 + ai * 128 + m * 16; const float s = rs[row]; bf16_t* rowp = O + (size_t)row * 2048 + col0;
;                 f32x4 v[2][2];
; #pragma unroll
;                 for (int bj = 0; bj < 2; ++bj) { v[bj][0] = acc[ai][bj][m][0] * s; v[bj][1] = acc[ai][bj][m][1] * s; u32x4 w;
;                     w.x = cvt_pk_bf16(v[bj][0][0], v[bj][0][1]); w.y = cvt_pk_bf16(v[bj][0][2], v[bj][0][3]); w.z = cvt_pk_bf16(v[bj][1][0], v[bj][1][1]); w.w = cvt_pk_bf16(v[bj][1][2], v[bj][1][3]);
;                     *(u32x4*)(rowp + bj * 128) = w; }
;                 if (pn < 2) {
;                     float s0 = 0.f, s1 = 0.f;
; #pragma unroll
;                     for (int n = 0; n < 2; ++n) { s0 += (v[0][n][0] * v[0][n][0] + v[0][n][1] * v[0][n][1]) + (v[0][n][2] * v[0][n][2] + v[0][n][3] * v[0][n][3]);
;                                                   s1 += (v[1][n][0] * v[1][n][0] + v[1][n][1] * v[1][n][1]) + (v[1][n][2] * v[1][n][2] + v[1][n][3] * v[1][n][3]); }
;                     if (pn == 0) { float ss = s0 + s1; ss += shx(ss, 16, ln); ss += shx(ss, 32, ln); if (fq == 0) ssq4[(size_t)row * 4 + wc] = ss; }
;                     else { s0 += shx(s0, 16, ln); s0 += shx(s0, 32, ln); if (fq == 0) sskv4[(size_t)row * 4 + wc] = s0;
;                         if (wc < 2) { s1 += shx(s1, 16, ln); s1 += shx(s1, 32, ln); if (fq == 0) sskr2[(size_t)row * 2 + wc] = s1;
.LBB0_1677:
	v_or_b32_e32 v160, 32, v154
	v_ashrrev_i32_e32 v161, 31, v160
	s_waitcnt lgkmcnt(0)
	v_lshl_add_u64 v[162:163], v[160:161], 2, s[18:19]
	global_load_dword v136, v[162:163], off
	v_lshlrev_b64 v[162:163], 12, v[160:161]
	v_lshl_add_u64 v[162:163], s[14:15], 0, v[162:163]
	v_lshl_add_u64 v[192:193], v[156:157], 1, v[162:163]
	s_and_b64 vcc, exec, s[8:9]
	s_waitcnt vmcnt(0)
	v_mul_f32_e32 v174, v94, v136
	v_mul_f32_e32 v175, v95, v136
	v_mul_f32_e32 v176, v92, v136
	v_mul_f32_e32 v177, v93, v136
	v_mul_f32_e32 v170, v90, v136
	v_mul_f32_e32 v171, v91, v136
	v_mul_f32_e32 v172, v88, v136
	v_mul_f32_e32 v173, v89, v136
	v_mul_f32_e32 v162, v86, v136
	v_mul_f32_e32 v163, v87, v136
	v_mul_f32_e32 v164, v84, v136
	v_mul_f32_e32 v165, v85, v136
	v_mul_f32_e32 v166, v82, v136
	v_mul_f32_e32 v167, v83, v136
	v_mul_f32_e32 v168, v80, v136
	v_mul_f32_e32 v169, v81, v136
	v_cvt_pk_bf16_f32 v188, v176, v177
	v_cvt_pk_bf16_f32 v189, v174, v175
	v_cvt_pk_bf16_f32 v190, v172, v173
	v_cvt_pk_bf16_f32 v191, v170, v171
	global_store_dwordx4 v[192:193], v[188:191], off
	s_nop 1
	v_cvt_pk_bf16_f32 v188, v164, v165
	v_cvt_pk_bf16_f32 v189, v162, v163
	v_cvt_pk_bf16_f32 v190, v168, v169
	v_cvt_pk_bf16_f32 v191, v166, v167
	global_store_dwordx4 v[192:193], v[188:191], off offset:256
	s_cbranch_vccnz .LBB0_1690
	v_mul_f32_e32 v136, v177, v177
	v_mul_f32_e32 v175, v175, v175
	v_mul_f32_e32 v173, v173, v173
	v_mul_f32_e32 v171, v171, v171
	v_fmac_f32_e32 v136, v176, v176
	v_fmac_f32_e32 v175, v174, v174
	v_fmac_f32_e32 v173, v172, v172
	v_fmac_f32_e32 v171, v170, v170
	v_add_f32_e32 v136, v136, v175
	v_add_f32_e32 v170, v173, v171
	v_mul_f32_e32 v174, v165, v165
	v_mul_f32_e32 v175, v163, v163
	v_add_f32_e32 v170, v136, v170
	v_mul_f32_e32 v136, v169, v169
	v_mul_f32_e32 v171, v167, v167
	v_fmac_f32_e32 v174, v164, v164
	v_fmac_f32_e32 v175, v162, v162
	v_fmac_f32_e32 v136, v168, v168
	v_fmac_f32_e32 v171, v166, v166
	v_add_f32_e32 v174, v174, v175
	v_add_f32_e32 v136, v136, v171
	s_and_b64 vcc, exec, s[6:7]
	v_add_f32_e32 v171, v174, v136
	s_cbranch_vccnz .LBB0_1686
	ds_bpermute_b32 v136, v179, v170
	s_waitcnt lgkmcnt(0)
	v_add_f32_e32 v136, v170, v136
	ds_bpermute_b32 v172, v180, v136
	s_and_saveexec_b64 s[76:77], s[0:1]
	s_cbranch_execz .LBB0_1681
	v_lshl_add_u64 v[174:175], v[160:161], 4, s[60:61]
	s_waitcnt lgkmcnt(0)
	v_add_f32_e32 v136, v136, v172
	global_store_dword v[174:175], v136, off

;     DI void operator()(const f32x4 (&acc)[2][2][4][2], const Unit& u, int wr, int wc, int fr, int fq) const {
;     ...
;                             const int i0 = 16 * wc + 4 * fq, pos = row & (SEQ - 1); const f32x4 c = *(const f32x4*)(cs + pos * 32 + i0), sv = *(const f32x4*)(sn + pos * 32 + i0);
;                             *(f32x4*)(KR + (size_t)row * 64 + i0) = v[1][0] * c - v[1][1] * sv; *(f32x4*)(KR + (size_t)row * 64 + 32 + i0) = v[1][1] * c + v[1][0] * sv; } } } }
.LBB0_1684:
	s_or_b64 exec, exec, s[76:77]
	v_lshlrev_b32_e32 v136, 7, v160
	v_and_b32_e32 v136, 0x7f780, v136
	s_waitcnt lgkmcnt(0)
	v_lshl_add_u64 v[172:173], v[142:143], 0, v[136:137]
	global_load_dwordx4 v[172:175], v[172:173], off
	v_lshl_add_u64 v[176:177], v[140:141], 0, v[136:137]
	global_load_dwordx4 v[188:191], v[176:177], off
	v_lshlrev_b64 v[176:177], 8, v[160:161]
	v_lshl_add_u64 v[176:177], v[144:145], 0, v[176:177]
	s_waitcnt vmcnt(1)
	v_mul_f32_e32 v192, v166, v174
	v_mul_f32_e32 v193, v167, v175
	v_mul_f32_e32 v194, v168, v172
	v_mul_f32_e32 v195, v169, v173
	v_mul_f32_e32 v196, v162, v174
	v_mul_f32_e32 v197, v163, v175
	v_mul_f32_e32 v198, v164, v172
	v_mul_f32_e32 v199, v165, v173
	s_waitcnt vmcnt(0)
	v_pk_fma_f32 v[174:175], v[162:163], v[190:191], v[192:193] neg_lo:[0,0,1] neg_hi:[0,0,1]
	v_pk_fma_f32 v[172:173], v[164:165], v[188:189], v[194:195] neg_lo:[0,0,1] neg_hi:[0,0,1]
	v_fma_f32 v164, v166, v190, v196
	v_fma_f32 v165, v167, v191, v197
	v_fma_f32 v162, v168, v188, v198
	v_fma_f32 v163, v169, v189, v199
	global_store_dwordx4 v[176:177], v[172:175], off
	global_store_dwordx4 v[176:177], v[162:165], off offset:128

; __device__ __forceinline__ unsigned cvt_pk_bf16(float lo, float hi) { unsigned r; asm volatile("v_cvt_pk_bf16_f32 %0, %1, %2" : "=v"(r) : "v"(lo), "v"(hi)); return r; }
; DI float shx(float v, int mask, int lane) { return __int_as_float(__builtin_amdgcn_ds_bpermute((lane ^ mask) << 2, __float_as_int(v))); }
;     DI void operator()(const f32x4 (&acc)[2][2][4][2], const Unit& u, int wr, int wc, int fr, int fq) const {
;     ...
;             for (int m = 0; m < 4; ++m) { const int row = row0 + ai * 128 + m * 16; const float s = rs[row]; bf16_t* rowp = O + (size_t)row * 2048 + col0;
;                 f32x4 v[2][2];
; #pragma unroll
;                 for (int bj = 0; bj < 2; ++bj) { v[bj][0] = acc[ai][bj][m][0] * s; v[bj][1] = acc[ai][bj][m][1] * s; u32x4 w;
;                     w.x = cvt_pk_bf16(v[bj][0][0], v[bj][0][1]); w.y = cvt_pk_bf16(v[bj][0][2], v[bj][0][3]); w.z = cvt_pk_bf16(v[bj][1][0], v[bj][1][1]); w.w = cvt_pk_bf16(v[bj][1][2], v[bj][1][3]);
;                     *(u32x4*)(rowp + bj * 128) = w; }
;                 if (pn < 2) {
;                     float s0 = 0.f, s1 = 0.f;
; #pragma unroll
;                     for (int n = 0; n < 2; ++n) { s0 += (v[0][n][0] * v[0][n][0] + v[0][n][1] * v[0][n][1]) + (v[0][n][2] * v[0][n][2] + v[0][n][3] * v[0][n][3]);
;                                                   s1 += (v[1][n][0] * v[1][n][0] + v[1][n][1] * v[1][n][1]) + (v[1][n][2] * v[1][n][2] + v[1][n][3] * v[1][n][3]); }
;                     if (pn == 0) { float ss = s0 + s1; ss += shx(ss, 16, ln); ss += shx(ss, 32, ln); if (fq == 0) ssq4[(size_t)row * 4 + wc] = ss; }
;                     else { s0 += shx(s0, 16, ln); s0 += shx(s0, 32, ln); if (fq == 0) sskv4[(size_t)row * 4 + wc] = s0;
;                         if (wc < 2) { s1 += shx(s1, 16, ln); s1 += shx(s1, 32, ln); if (fq == 0) sskr2[(size_t)row * 2 + wc] = s1;
.LBB0_1690:
	v_or_b32_e32 v160, 48, v154
	v_ashrrev_i32_e32 v161, 31, v160
	s_waitcnt lgkmcnt(0)
	v_lshl_add_u64 v[162:163], v[160:161], 2, s[18:19]
	global_load_dword v136, v[162:163], off
	v_lshlrev_b64 v[162:163], 12, v[160:161]
	v_lshl_add_u64 v[162:163], s[14:15], 0, v[162:163]
	v_lshl_add_u64 v[192:193], v[156:157], 1, v[162:163]
	s_and_b64 vcc, exec, s[8:9]
	s_waitcnt vmcnt(0)
	v_mul_f32_e32 v174, v78, v136
	v_mul_f32_e32 v175, v79, v136
	v_mul_f32_e32 v176, v76, v136
	v_mul_f32_e32 v177, v77, v136
	v_mul_f32_e32 v170, v74, v136
	v_mul_f32_e32 v171, v75, v136
	v_mul_f32_e32 v172, v72, v136
	v_mul_f32_e32 v173, v73, v136
	v_mul_f32_e32 v162, v70, v136
	v_mul_f32_e32 v163, v71, v136
	v_mul_f32_e32 v164, v68, v136
	v_mul_f32_e32 v165, v69, v136
	v_mul_f32_e32 v166, v66, v136
	v_mul_f32_e32 v167, v67, v136
	v_mul_f32_e32 v168, v64, v136
	v_mul_f32_e32 v169, v65, v136
	v_cvt_pk_bf16_f32 v188, v176, v177
	v_cvt_pk_bf16_f32 v189, v174, v175
	v_cvt_pk_bf16_f32 v190, v172, v173
	v_cvt_pk_bf16_f32 v191, v170, v171
	global_store_dwordx4 v[192:193], v[188:191], off
	s_nop 1
	v_cvt_pk_bf16_f32 v188, v164, v165
	v_cvt_pk_bf16_f32 v189, v162, v163
	v_cvt_pk_bf16_f32 v190, v168, v169
	v_cvt_pk_bf16_f32 v191, v166, v167
	global_store_dwordx4 v[192:193], v[188:191], off offset:256
	s_cbranch_vccnz .LBB0_1703
	v_mul_f32_e32 v136, v177, v177
	v_mul_f32_e32 v175, v175, v175
	v_mul_f32_e32 v173, v173, v173
	v_mul_f32_e32 v171, v171, v171
	v_fmac_f32_e32 v136, v176, v176
	v_fmac_f32_e32 v175, v174, v174
	v_fmac_f32_e32 v173, v172, v172
	v_fmac_f32_e32 v171, v170, v170
	v_add_f32_e32 v136, v136, v175
	v_add_f32_e32 v170, v173, v171
	v_mul_f32_e32 v174, v165, v165
	v_mul_f32_e32 v175, v163, v163
	v_add_f32_e32 v170, v136, v170
	v_mul_f32_e32 v136, v169, v169
	v_mul_f32_e32 v171, v167, v167
	v_fmac_f32_e32 v174, v164, v164
	v_fmac_f32_e32 v175, v162, v162
	v_fmac_f32_e32 v136, v168, v168
	v_fmac_f32_e32 v171, v166, v166
	v_add_f32_e32 v174, v174, v175
	v_add_f32_e32 v136, v136, v171
	s_and_b64 vcc, exec, s[6:7]
	v_add_f32_e32 v171, v174, v136
	s_cbranch_vccnz .LBB0_1699
	ds_bpermute_b32 v136, v179, v170
	s_waitcnt lgkmcnt(0)
	v_add_f32_e32 v136, v170, v136
	ds_bpermute_b32 v172, v180, v136
	s_and_saveexec_b64 s[76:77], s[0:1]
	s_cbranch_execz .LBB0_1694
	v_lshl_add_u64 v[174:175], v[160:161], 4, s[60:61]
	s_waitcnt lgkmcnt(0)
	v_add_f32_e32 v136, v136, v172
	global_store_dword v[174:175], v136, off

;     DI void operator()(const f32x4 (&acc)[2][2][4][2], const Unit& u, int wr, int wc, int fr, int fq) const {
;     ...
;                             const int i0 = 16 * wc + 4 * fq, pos = row & (SEQ - 1); const f32x4 c = *(const f32x4*)(cs + pos * 32 + i0), sv = *(const f32x4*)(sn + pos * 32 + i0);
;                             *(f32x4*)(KR + (size_t)row * 64 + i0) = v[1][0] * c - v[1][1] * sv; *(f32x4*)(KR + (size_t)row * 64 + 32 + i0) = v[1][1] * c + v[1][0] * sv; } } } }
.LBB0_1697:
	s_or_b64 exec, exec, s[76:77]
	v_lshlrev_b32_e32 v136, 7, v160
	v_and_b32_e32 v136, 0x7ff80, v136
	s_waitcnt lgkmcnt(0)
	v_lshl_add_u64 v[172:173], v[142:143], 0, v[136:137]
	global_load_dwordx4 v[172:175], v[172:173], off
	v_lshl_add_u64 v[176:177], v[140:141], 0, v[136:137]
	global_load_dwordx4 v[188:191], v[176:177], off
	v_lshlrev_b64 v[176:177], 8, v[160:161]
	v_lshl_add_u64 v[176:177], v[144:145], 0, v[176:177]
	s_waitcnt vmcnt(1)
	v_mul_f32_e32 v192, v166, v174
	v_mul_f32_e32 v193, v167, v175
	v_mul_f32_e32 v194, v168, v172
	v_mul_f32_e32 v195, v169, v173
	v_mul_f32_e32 v196, v162, v174
	v_mul_f32_e32 v197, v163, v175
	v_mul_f32_e32 v198, v164, v172
	v_mul_f32_e32 v199, v165, v173
	s_waitcnt vmcnt(0)
	v_pk_fma_f32 v[174:175], v[162:163], v[190:191], v[192:193] neg_lo:[0,0,1] neg_hi:[0,0,1]
	v_pk_fma_f32 v[172:173], v[164:165], v[188:189], v[194:195] neg_lo:[0,0,1] neg_hi:[0,0,1]
	v_fma_f32 v164, v166, v190, v196
	v_fma_f32 v165, v167, v191, v197
	v_fma_f32 v162, v168, v188, v198
	v_fma_f32 v163, v169, v189, v199
	global_store_dwordx4 v[176:177], v[172:175], off
	global_store_dwordx4 v[176:177], v[162:165], off offset:128

; __device__ __forceinline__ unsigned cvt_pk_bf16(float lo, float hi) { unsigned r; asm volatile("v_cvt_pk_bf16_f32 %0, %1, %2" : "=v"(r) : "v"(lo), "v"(hi)); return r; }
; DI float shx(float v, int mask, int lane) { return __int_as_float(__builtin_amdgcn_ds_bpermute((lane ^ mask) << 2, __float_as_int(v))); }
;     DI void operator()(const f32x4 (&acc)[2][2][4][2], const Unit& u, int wr, int wc, int fr, int fq) const {
;     ...
;             for (int m = 0; m < 4; ++m) { const int row = row0 + ai * 128 + m * 16; const float s = rs[row]; bf16_t* rowp = O + (size_t)row * 2048 + col0;
;                 f32x4 v[2][2];
; #pragma unroll
;                 for (int bj = 0; bj < 2; ++bj) { v[bj][0] = acc[ai][bj][m][0] * s; v[bj][1] = acc[ai][bj][m][1] * s; u32x4 w;
;                     w.x = cvt_pk_bf16(v[bj][0][0], v[bj][0][1]); w.y = cvt_pk_bf16(v[bj][0][2], v[bj][0][3]); w.z = cvt_pk_bf16(v[bj][1][0], v[bj][1][1]); w.w = cvt_pk_bf16(v[bj][1][2], v[bj][1][3]);
;                     *(u32x4*)(rowp + bj * 128) = w; }
;                 if (pn < 2) {
;                     float s0 = 0.f, s1 = 0.f;
; #pragma unroll
;                     for (int n = 0; n < 2; ++n) { s0 += (v[0][n][0] * v[0][n][0] + v[0][n][1] * v[0][n][1]) + (v[0][n][2] * v[0][n][2] + v[0][n][3] * v[0][n][3]);
;                                                   s1 += (v[1][n][0] * v[1][n][0] + v[1][n][1] * v[1][n][1]) + (v[1][n][2] * v[1][n][2] + v[1][n][3] * v[1][n][3]); }
;                     if (pn == 0) { float ss = s0 + s1; ss += shx(ss, 16, ln); ss += shx(ss, 32, ln); if (fq == 0) ssq4[(size_t)row * 4 + wc] = ss; }
;                     else { s0 += shx(s0, 16, ln); s0 += shx(s0, 32, ln); if (fq == 0) sskv4[(size_t)row * 4 + wc] = s0;
;                         if (wc < 2) { s1 += shx(s1, 16, ln); s1 += shx(s1, 32, ln); if (fq == 0) sskr2[(size_t)row * 2 + wc] = s1;
.LBB0_1703:
	global_load_dword v136, v[158:159], off offset:512
	v_add_u32_e32 v160, 0x80, v154
	v_ashrrev_i32_e32 v161, 31, v160
	s_waitcnt lgkmcnt(0)
	v_lshlrev_b64 v[162:163], 12, v[160:161]
	v_lshl_add_u64 v[162:163], s[14:15], 0, v[162:163]
	v_lshl_add_u64 v[192:193], v[156:157], 1, v[162:163]
	s_and_b64 vcc, exec, s[8:9]
	s_waitcnt vmcnt(0)
	v_mul_f32_e32 v174, v62, v136
	v_mul_f32_e32 v175, v63, v136
	v_mul_f32_e32 v176, v60, v136
	v_mul_f32_e32 v177, v61, v136
	v_mul_f32_e32 v170, v58, v136
	v_mul_f32_e32 v171, v59, v136
	v_mul_f32_e32 v172, v56, v136
	v_mul_f32_e32 v173, v57, v136
	v_mul_f32_e32 v162, v54, v136
	v_mul_f32_e32 v163, v55, v136
	v_mul_f32_e32 v164, v52, v136
	v_mul_f32_e32 v165, v53, v136
	v_mul_f32_e32 v166, v50, v136
	v_mul_f32_e32 v167, v51, v136
	v_mul_f32_e32 v168, v48, v136
	v_mul_f32_e32 v169, v49, v136
	v_cvt_pk_bf16_f32 v188, v176, v177
	v_cvt_pk_bf16_f32 v189, v174, v175
	v_cvt_pk_bf16_f32 v190, v172, v173
	v_cvt_pk_bf16_f32 v191, v170, v171
	global_store_dwordx4 v[192:193], v[188:191], off
	s_nop 1
	v_cvt_pk_bf16_f32 v188, v164, v165
	v_cvt_pk_bf16_f32 v189, v162, v163
	v_cvt_pk_bf16_f32 v190, v168, v169
	v_cvt_pk_bf16_f32 v191, v166, v167
	global_store_dwordx4 v[192:193], v[188:191], off offset:256
	s_cbranch_vccnz .LBB0_1716
	v_mul_f32_e32 v136, v177, v177
	v_mul_f32_e32 v175, v175, v175
	v_mul_f32_e32 v173, v173, v173
	v_mul_f32_e32 v171, v171, v171
	v_fmac_f32_e32 v136, v176, v176
	v_fmac_f32_e32 v175, v174, v174
	v_fmac_f32_e32 v173, v172, v172
	v_fmac_f32_e32 v171, v170, v170
	v_add_f32_e32 v136, v136, v175
	v_add_f32_e32 v170, v173, v171
	v_mul_f32_e32 v174, v165, v165
	v_mul_f32_e32 v175, v163, v163
	v_add_f32_e32 v170, v136, v170
	v_mul_f32_e32 v136, v169, v169
	v_mul_f32_e32 v171, v167, v167
	v_fmac_f32_e32 v174, v164, v164
	v_fmac_f32_e32 v175, v162, v162
	v_fmac_f32_e32 v136, v168, v168
	v_fmac_f32_e32 v171, v166, v166
	v_add_f32_e32 v174, v174, v175
	v_add_f32_e32 v136, v136, v171
	s_and_b64 vcc, exec, s[6:7]
	v_add_f32_e32 v171, v174, v136
	s_cbranch_vccnz .LBB0_1712
	ds_bpermute_b32 v136, v179, v170
	s_waitcnt lgkmcnt(0)
	v_add_f32_e32 v136, v170, v136
	ds_bpermute_b32 v172, v180, v136
	s_and_saveexec_b64 s[76:77], s[0:1]
	s_cbranch_execz .LBB0_1707
	v_lshl_add_u64 v[174:175], v[160:161], 4, s[60:61]
	s_waitcnt lgkmcnt(0)
	v_add_f32_e32 v136, v136, v172
	global_store_dword v[174:175], v136, off

;     DI void operator()(const f32x4 (&acc)[2][2][4][2], const Unit& u, int wr, int wc, int fr, int fq) const {
;     ...
;                             const int i0 = 16 * wc + 4 * fq, pos = row & (SEQ - 1); const f32x4 c = *(const f32x4*)(cs + pos * 32 + i0), sv = *(const f32x4*)(sn + pos * 32 + i0);
;                             *(f32x4*)(KR + (size_t)row * 64 + i0) = v[1][0] * c - v[1][1] * sv; *(f32x4*)(KR + (size_t)row * 64 + 32 + i0) = v[1][1] * c + v[1][0] * sv; } } } }
.LBB0_1710:
	s_or_b64 exec, exec, s[76:77]
	v_lshlrev_b32_e32 v136, 7, v160
	v_and_b32_e32 v136, 0x7e780, v136
	s_waitcnt lgkmcnt(0)
	v_lshl_add_u64 v[172:173], v[142:143], 0, v[136:137]
	global_load_dwordx4 v[172:175], v[172:173], off
	v_lshl_add_u64 v[176:177], v[140:141], 0, v[136:137]
	global_load_dwordx4 v[188:191], v[176:177], off
	v_lshlrev_b64 v[176:177], 8, v[160:161]
	v_lshl_add_u64 v[176:177], v[144:145], 0, v[176:177]
	s_waitcnt vmcnt(1)
	v_mul_f32_e32 v192, v166, v174
	v_mul_f32_e32 v193, v167, v175
	v_mul_f32_e32 v194, v168, v172
	v_mul_f32_e32 v195, v169, v173
	v_mul_f32_e32 v196, v162, v174
	v_mul_f32_e32 v197, v163, v175
	v_mul_f32_e32 v198, v164, v172
	v_mul_f32_e32 v199, v165, v173
	s_waitcnt vmcnt(0)
	v_pk_fma_f32 v[174:175], v[162:163], v[190:191], v[192:193] neg_lo:[0,0,1] neg_hi:[0,0,1]
	v_pk_fma_f32 v[172:173], v[164:165], v[188:189], v[194:195] neg_lo:[0,0,1] neg_hi:[0,0,1]
	v_fma_f32 v164, v166, v190, v196
	v_fma_f32 v165, v167, v191, v197
	v_fma_f32 v162, v168, v188, v198
	v_fma_f32 v163, v169, v189, v199
	global_store_dwordx4 v[176:177], v[172:175], off
	global_store_dwordx4 v[176:177], v[162:165], off offset:128

; __device__ __forceinline__ unsigned cvt_pk_bf16(float lo, float hi) { unsigned r; asm volatile("v_cvt_pk_bf16_f32 %0, %1, %2" : "=v"(r) : "v"(lo), "v"(hi)); return r; }
; DI float shx(float v, int mask, int lane) { return __int_as_float(__builtin_amdgcn_ds_bpermute((lane ^ mask) << 2, __float_as_int(v))); }
;     DI void operator()(const f32x4 (&acc)[2][2][4][2], const Unit& u, int wr, int wc, int fr, int fq) const {
;     ...
;             for (int m = 0; m < 4; ++m) { const int row = row0 + ai * 128 + m * 16; const float s = rs[row]; bf16_t* rowp = O + (size_t)row * 2048 + col0;
;                 f32x4 v[2][2];
; #pragma unroll
;                 for (int bj = 0; bj < 2; ++bj) { v[bj][0] = acc[ai][bj][m][0] * s; v[bj][1] = acc[ai][bj][m][1] * s; u32x4 w;
;                     w.x = cvt_pk_bf16(v[bj][0][0], v[bj][0][1]); w.y = cvt_pk_bf16(v[bj][0][2], v[bj][0][3]); w.z = cvt_pk_bf16(v[bj][1][0], v[bj][1][1]); w.w = cvt_pk_bf16(v[bj][1][2], v[bj][1][3]);
;                     *(u32x4*)(rowp + bj * 128) = w; }
;                 if (pn < 2) {
;                     float s0 = 0.f, s1 = 0.f;
; #pragma unroll
;                     for (int n = 0; n < 2; ++n) { s0 += (v[0][n][0] * v[0][n][0] + v[0][n][1] * v[0][n][1]) + (v[0][n][2] * v[0][n][2] + v[0][n][3] * v[0][n][3]);
;                                                   s1 += (v[1][n][0] * v[1][n][0] + v[1][n][1] * v[1][n][1]) + (v[1][n][2] * v[1][n][2] + v[1][n][3] * v[1][n][3]); }
;                     if (pn == 0) { float ss = s0 + s1; ss += shx(ss, 16, ln); ss += shx(ss, 32, ln); if (fq == 0) ssq4[(size_t)row * 4 + wc] = ss; }
;                     else { s0 += shx(s0, 16, ln); s0 += shx(s0, 32, ln); if (fq == 0) sskv4[(size_t)row * 4 + wc] = s0;
;                         if (wc < 2) { s1 += shx(s1, 16, ln); s1 += shx(s1, 32, ln); if (fq == 0) sskr2[(size_t)row * 2 + wc] = s1;
.LBB0_1716:
	global_load_dword v136, v[158:159], off offset:576
	v_add_u32_e32 v160, 0x90, v154
	v_ashrrev_i32_e32 v161, 31, v160
	s_waitcnt lgkmcnt(0)
	v_lshlrev_b64 v[162:163], 12, v[160:161]
	v_lshl_add_u64 v[162:163], s[14:15], 0, v[162:163]
	v_lshl_add_u64 v[192:193], v[156:157], 1, v[162:163]
	s_and_b64 vcc, exec, s[8:9]
	s_waitcnt vmcnt(0)
	v_mul_f32_e32 v174, v46, v136
	v_mul_f32_e32 v175, v47, v136
	v_mul_f32_e32 v176, v44, v136
	v_mul_f32_e32 v177, v45, v136
	v_mul_f32_e32 v170, v42, v136
	v_mul_f32_e32 v171, v43, v136
	v_mul_f32_e32 v172, v40, v136
	v_mul_f32_e32 v173, v41, v136
	v_mul_f32_e32 v162, v38, v136
	v_mul_f32_e32 v163, v39, v136
	v_mul_f32_e32 v164, v36, v136
	v_mul_f32_e32 v165, v37, v136
	v_mul_f32_e32 v166, v34, v136
	v_mul_f32_e32 v167, v35, v136
	v_mul_f32_e32 v168, v32, v136
	v_mul_f32_e32 v169, v33, v136
	v_cvt_pk_bf16_f32 v188, v176, v177
	v_cvt_pk_bf16_f32 v189, v174, v175
	v_cvt_pk_bf16_f32 v190, v172, v173
	v_cvt_pk_bf16_f32 v191, v170, v171
	global_store_dwordx4 v[192:193], v[188:191], off
	s_nop 1
	v_cvt_pk_bf16_f32 v188, v164, v165
	v_cvt_pk_bf16_f32 v189, v162, v163
	v_cvt_pk_bf16_f32 v190, v168, v169
	v_cvt_pk_bf16_f32 v191, v166, v167
	global_store_dwordx4 v[192:193], v[188:191], off offset:256
	s_cbranch_vccnz .LBB0_1729
	v_mul_f32_e32 v136, v177, v177
	v_mul_f32_e32 v175, v175, v175
	v_mul_f32_e32 v173, v173, v173
	v_mul_f32_e32 v171, v171, v171
	v_fmac_f32_e32 v136, v176, v176
	v_fmac_f32_e32 v175, v174, v174
	v_fmac_f32_e32 v173, v172, v172
	v_fmac_f32_e32 v171, v170, v170
	v_add_f32_e32 v136, v136, v175
	v_add_f32_e32 v170, v173, v171
	v_mul_f32_e32 v174, v165, v165
	v_mul_f32_e32 v175, v163, v163
	v_add_f32_e32 v170, v136, v170
	v_mul_f32_e32 v136, v169, v169
	v_mul_f32_e32 v171, v167, v167
	v_fmac_f32_e32 v174, v164, v164
	v_fmac_f32_e32 v175, v162, v162
	v_fmac_f32_e32 v136, v168, v168
	v_fmac_f32_e32 v171, v166, v166
	v_add_f32_e32 v174, v174, v175
	v_add_f32_e32 v136, v136, v171
	s_and_b64 vcc, exec, s[6:7]
	v_add_f32_e32 v171, v174, v136
	s_cbranch_vccnz .LBB0_1725
	ds_bpermute_b32 v136, v179, v170
	s_waitcnt lgkmcnt(0)
	v_add_f32_e32 v136, v170, v136
	ds_bpermute_b32 v172, v180, v136
	s_and_saveexec_b64 s[76:77], s[0:1]
	s_cbranch_execz .LBB0_1720
	v_lshl_add_u64 v[174:175], v[160:161], 4, s[60:61]
	s_waitcnt lgkmcnt(0)
	v_add_f32_e32 v136, v136, v172
	global_store_dword v[174:175], v136, off

;     DI void operator()(const f32x4 (&acc)[2][2][4][2], const Unit& u, int wr, int wc, int fr, int fq) const {
;     ...
;                             const int i0 = 16 * wc + 4 * fq, pos = row & (SEQ - 1); const f32x4 c = *(const f32x4*)(cs + pos * 32 + i0), sv = *(const f32x4*)(sn + pos * 32 + i0);
;                             *(f32x4*)(KR + (size_t)row * 64 + i0) = v[1][0] * c - v[1][1] * sv; *(f32x4*)(KR + (size_t)row * 64 + 32 + i0) = v[1][1] * c + v[1][0] * sv; } } } }
.LBB0_1723:
	s_or_b64 exec, exec, s[76:77]
	v_lshlrev_b32_e32 v136, 7, v160
	v_and_b32_e32 v136, 0x7ef80, v136
	s_waitcnt lgkmcnt(0)
	v_lshl_add_u64 v[172:173], v[142:143], 0, v[136:137]
	global_load_dwordx4 v[172:175], v[172:173], off
	v_lshl_add_u64 v[176:177], v[140:141], 0, v[136:137]
	global_load_dwordx4 v[188:191], v[176:177], off
	v_lshlrev_b64 v[176:177], 8, v[160:161]
	v_lshl_add_u64 v[176:177], v[144:145], 0, v[176:177]
	s_waitcnt vmcnt(1)
	v_mul_f32_e32 v192, v166, v174
	v_mul_f32_e32 v193, v167, v175
	v_mul_f32_e32 v194, v168, v172
	v_mul_f32_e32 v195, v169, v173
	v_mul_f32_e32 v196, v162, v174
	v_mul_f32_e32 v197, v163, v175
	v_mul_f32_e32 v198, v164, v172
	v_mul_f32_e32 v199, v165, v173
	s_waitcnt vmcnt(0)
	v_pk_fma_f32 v[174:175], v[162:163], v[190:191], v[192:193] neg_lo:[0,0,1] neg_hi:[0,0,1]
	v_pk_fma_f32 v[172:173], v[164:165], v[188:189], v[194:195] neg_lo:[0,0,1] neg_hi:[0,0,1]
	v_fma_f32 v164, v166, v190, v196
	v_fma_f32 v165, v167, v191, v197
	v_fma_f32 v162, v168, v188, v198
	v_fma_f32 v163, v169, v189, v199
	global_store_dwordx4 v[176:177], v[172:175], off
	global_store_dwordx4 v[176:177], v[162:165], off offset:128

; __device__ __forceinline__ unsigned cvt_pk_bf16(float lo, float hi) { unsigned r; asm volatile("v_cvt_pk_bf16_f32 %0, %1, %2" : "=v"(r) : "v"(lo), "v"(hi)); return r; }
; DI float shx(float v, int mask, int lane) { return __int_as_float(__builtin_amdgcn_ds_bpermute((lane ^ mask) << 2, __float_as_int(v))); }
;     DI void operator()(const f32x4 (&acc)[2][2][4][2], const Unit& u, int wr, int wc, int fr, int fq) const {
;     ...
;             for (int m = 0; m < 4; ++m) { const int row = row0 + ai * 128 + m * 16; const float s = rs[row]; bf16_t* rowp = O + (size_t)row * 2048 + col0;
;                 f32x4 v[2][2];
; #pragma unroll
;                 for (int bj = 0; bj < 2; ++bj) { v[bj][0] = acc[ai][bj][m][0] * s; v[bj][1] = acc[ai][bj][m][1] * s; u32x4 w;
;                     w.x = cvt_pk_bf16(v[bj][0][0], v[bj][0][1]); w.y = cvt_pk_bf16(v[bj][0][2], v[bj][0][3]); w.z = cvt_pk_bf16(v[bj][1][0], v[bj][1][1]); w.w = cvt_pk_bf16(v[bj][1][2], v[bj][1][3]);
;                     *(u32x4*)(rowp + bj * 128) = w; }
;                 if (pn < 2) {
;                     float s0 = 0.f, s1 = 0.f;
; #pragma unroll
;                     for (int n = 0; n < 2; ++n) { s0 += (v[0][n][0] * v[0][n][0] + v[0][n][1] * v[0][n][1]) + (v[0][n][2] * v[0][n][2] + v[0][n][3] * v[0][n][3]);
;                                                   s1 += (v[1][n][0] * v[1][n][0] + v[1][n][1] * v[1][n][1]) + (v[1][n][2] * v[1][n][2] + v[1][n][3] * v[1][n][3]); }
;                     if (pn == 0) { float ss = s0 + s1; ss += shx(ss, 16, ln); ss += shx(ss, 32, ln); if (fq == 0) ssq4[(size_t)row * 4 + wc] = ss; }
;                     else { s0 += shx(s0, 16, ln); s0 += shx(s0, 32, ln); if (fq == 0) sskv4[(size_t)row * 4 + wc] = s0;
;                         if (wc < 2) { s1 += shx(s1, 16, ln); s1 += shx(s1, 32, ln); if (fq == 0) sskr2[(size_t)row * 2 + wc] = s1;
.LBB0_1729:
	global_load_dword v136, v[158:159], off offset:640
	v_add_u32_e32 v160, 0xa0, v154
	v_ashrrev_i32_e32 v161, 31, v160
	s_waitcnt lgkmcnt(0)
	v_lshlrev_b64 v[162:163], 12, v[160:161]
	v_lshl_add_u64 v[162:163], s[14:15], 0, v[162:163]
	v_lshl_add_u64 v[192:193], v[156:157], 1, v[162:163]
	s_and_b64 vcc, exec, s[8:9]
	s_waitcnt vmcnt(0)
	v_mul_f32_e32 v174, v30, v136
	v_mul_f32_e32 v175, v31, v136
	v_mul_f32_e32 v176, v28, v136
	v_mul_f32_e32 v177, v29, v136
	v_mul_f32_e32 v170, v26, v136
	v_mul_f32_e32 v171, v27, v136
	v_mul_f32_e32 v172, v24, v136
	v_mul_f32_e32 v173, v25, v136
	v_mul_f32_e32 v162, v22, v136
	v_mul_f32_e32 v163, v23, v136
	v_mul_f32_e32 v164, v20, v136
	v_mul_f32_e32 v165, v21, v136
	v_mul_f32_e32 v166, v18, v136
	v_mul_f32_e32 v167, v19, v136
	v_mul_f32_e32 v168, v16, v136
	v_mul_f32_e32 v169, v17, v136
	v_cvt_pk_bf16_f32 v188, v176, v177
	v_cvt_pk_bf16_f32 v189, v174, v175
	v_cvt_pk_bf16_f32 v190, v172, v173
	v_cvt_pk_bf16_f32 v191, v170, v171
	global_store_dwordx4 v[192:193], v[188:191], off
	s_nop 1
	v_cvt_pk_bf16_f32 v188, v164, v165
	v_cvt_pk_bf16_f32 v189, v162, v163
	v_cvt_pk_bf16_f32 v190, v168, v169
	v_cvt_pk_bf16_f32 v191, v166, v167
	global_store_dwordx4 v[192:193], v[188:191], off offset:256
	s_cbranch_vccnz .LBB0_1742
	v_mul_f32_e32 v136, v177, v177
	v_mul_f32_e32 v175, v175, v175
	v_mul_f32_e32 v173, v173, v173
	v_mul_f32_e32 v171, v171, v171
	v_fmac_f32_e32 v136, v176, v176
	v_fmac_f32_e32 v175, v174, v174
	v_fmac_f32_e32 v173, v172, v172
	v_fmac_f32_e32 v171, v170, v170
	v_add_f32_e32 v136, v136, v175
	v_add_f32_e32 v170, v173, v171
	v_mul_f32_e32 v174, v165, v165
	v_mul_f32_e32 v175, v163, v163
	v_add_f32_e32 v170, v136, v170
	v_mul_f32_e32 v136, v169, v169
	v_mul_f32_e32 v171, v167, v167
	v_fmac_f32_e32 v174, v164, v164
	v_fmac_f32_e32 v175, v162, v162
	v_fmac_f32_e32 v136, v168, v168
	v_fmac_f32_e32 v171, v166, v166
	v_add_f32_e32 v174, v174, v175
	v_add_f32_e32 v136, v136, v171
	s_and_b64 vcc, exec, s[6:7]
	v_add_f32_e32 v171, v174, v136
	s_cbranch_vccnz .LBB0_1738
	ds_bpermute_b32 v136, v179, v170
	s_waitcnt lgkmcnt(0)
	v_add_f32_e32 v136, v170, v136
	ds_bpermute_b32 v172, v180, v136
	s_and_saveexec_b64 s[76:77], s[0:1]
	s_cbranch_execz .LBB0_1733
	v_lshl_add_u64 v[174:175], v[160:161], 4, s[60:61]
	s_waitcnt lgkmcnt(0)
	v_add_f32_e32 v136, v136, v172
	global_store_dword v[174:175], v136, off

; __device__ __forceinline__ unsigned cvt_pk_bf16(float lo, float hi) { unsigned r; asm volatile("v_cvt_pk_bf16_f32 %0, %1, %2" : "=v"(r) : "v"(lo), "v"(hi)); return r; }
; DI float shx(float v, int mask, int lane) { return __int_as_float(__builtin_amdgcn_ds_bpermute((lane ^ mask) << 2, __float_as_int(v))); }
;     DI void operator()(const f32x4 (&acc)[2][2][4][2], const Unit& u, int wr, int wc, int fr, int fq) const {
;     ...
;             for (int m = 0; m < 4; ++m) { const int row = row0 + ai * 128 + m * 16; const float s = rs[row]; bf16_t* rowp = O + (size_t)row * 2048 + col0;
;                 f32x4 v[2][2];
; #pragma unroll
;                 for (int bj = 0; bj < 2; ++bj) { v[bj][0] = acc[ai][bj][m][0] * s; v[bj][1] = acc[ai][bj][m][1] * s; u32x4 w;
;                     w.x = cvt_pk_bf16(v[bj][0][0], v[bj][0][1]); w.y = cvt_pk_bf16(v[bj][0][2], v[bj][0][3]); w.z = cvt_pk_bf16(v[bj][1][0], v[bj][1][1]); w.w = cvt_pk_bf16(v[bj][1][2], v[bj][1][3]);
;                     *(u32x4*)(rowp + bj * 128) = w; }
;                 if (pn < 2) {
;                     float s0 = 0.f, s1 = 0.f;
; #pragma unroll
;                     for (int n = 0; n < 2; ++n) { s0 += (v[0][n][0] * v[0][n][0] + v[0][n][1] * v[0][n][1]) + (v[0][n][2] * v[0][n][2] + v[0][n][3] * v[0][n][3]);
;                                                   s1 += (v[1][n][0] * v[1][n][0] + v[1][n][1] * v[1][n][1]) + (v[1][n][2] * v[1][n][2] + v[1][n][3] * v[1][n][3]); }
;                     if (pn == 0) { float ss = s0 + s1; ss += shx(ss, 16, ln); ss += shx(ss, 32, ln); if (fq == 0) ssq4[(size_t)row * 4 + wc] = ss; }
;                     else { s0 += shx(s0, 16, ln); s0 += shx(s0, 32, ln); if (fq == 0) sskv4[(size_t)row * 4 + wc] = s0;
;                         if (wc < 2) { s1 += shx(s1, 16, ln); s1 += shx(s1, 32, ln); if (fq == 0) sskr2[(size_t)row * 2 + wc] = s1;
.LBB0_1742:
	global_load_dword v136, v[158:159], off offset:704
	v_add_u32_e32 v158, 0xb0, v154
	v_ashrrev_i32_e32 v159, 31, v158
	v_lshlrev_b64 v[160:161], 12, v[158:159]
	v_lshl_add_u64 v[160:161], s[14:15], 0, v[160:161]
	v_lshl_add_u64 v[188:189], v[156:157], 1, v[160:161]
	s_and_b64 vcc, exec, s[8:9]
	s_waitcnt vmcnt(0)
	v_mul_f32_e32 v170, v14, v136
	v_mul_f32_e32 v171, v15, v136
	s_waitcnt lgkmcnt(0)
	v_mul_f32_e32 v172, v12, v136
	v_mul_f32_e32 v173, v13, v136
	v_mul_f32_e32 v166, v10, v136
	v_mul_f32_e32 v167, v11, v136
	v_mul_f32_e32 v168, v8, v136
	v_mul_f32_e32 v169, v9, v136
	v_mul_f32_e32 v156, v6, v136
	v_mul_f32_e32 v157, v7, v136
	v_mul_f32_e32 v160, v4, v136
	v_mul_f32_e32 v161, v5, v136
	v_mul_f32_e32 v162, v2, v136
	v_mul_f32_e32 v163, v3, v136
	v_mul_f32_e32 v164, v0, v136
	v_mul_f32_e32 v165, v1, v136
	v_cvt_pk_bf16_f32 v174, v172, v173
	v_cvt_pk_bf16_f32 v175, v170, v171
	v_cvt_pk_bf16_f32 v176, v168, v169
	v_cvt_pk_bf16_f32 v177, v166, v167
	global_store_dwordx4 v[188:189], v[174:177], off
	s_nop 1
	v_cvt_pk_bf16_f32 v174, v160, v161
	v_cvt_pk_bf16_f32 v175, v156, v157
	v_cvt_pk_bf16_f32 v176, v164, v165
	v_cvt_pk_bf16_f32 v177, v162, v163
	global_store_dwordx4 v[188:189], v[174:177], off offset:256
	s_cbranch_vccnz .LBB0_1751
	v_mul_f32_e32 v136, v173, v173
	v_mul_f32_e32 v171, v171, v171
	v_mul_f32_e32 v169, v169, v169
	v_mul_f32_e32 v167, v167, v167
	v_fmac_f32_e32 v136, v172, v172
	v_fmac_f32_e32 v171, v170, v170
	v_fmac_f32_e32 v169, v168, v168
	v_fmac_f32_e32 v167, v166, v166
	v_add_f32_e32 v136, v136, v171
	v_add_f32_e32 v166, v169, v167
	v_mul_f32_e32 v170, v161, v161
	v_mul_f32_e32 v171, v157, v157
	v_add_f32_e32 v166, v136, v166
	v_mul_f32_e32 v136, v165, v165
	v_mul_f32_e32 v167, v163, v163
	v_fmac_f32_e32 v170, v160, v160
	v_fmac_f32_e32 v171, v156, v156
	v_fmac_f32_e32 v136, v164, v164
	v_fmac_f32_e32 v167, v162, v162
	v_add_f32_e32 v170, v170, v171
	v_add_f32_e32 v136, v136, v167
	s_and_b64 vcc, exec, s[6:7]
	v_add_f32_e32 v167, v170, v136
	s_cbranch_vccnz .LBB0_1755
	ds_bpermute_b32 v136, v179, v166
	s_waitcnt lgkmcnt(0)
	v_add_f32_e32 v136, v166, v136
	ds_bpermute_b32 v168, v180, v136
	s_and_saveexec_b64 s[6:7], s[0:1]
	s_cbranch_execz .LBB0_1746
	v_lshl_add_u64 v[170:171], v[158:159], 4, s[60:61]
	s_waitcnt lgkmcnt(0)
	v_add_f32_e32 v136, v136, v168
	global_store_dword v[170:171], v136, off

;     DI void operator()(const f32x4 (&acc)[2][2][4][2], const Unit& u, int wr, int wc, int fr, int fq) const {
;     ...
;                             const int i0 = 16 * wc + 4 * fq, pos = row & (SEQ - 1); const f32x4 c = *(const f32x4*)(cs + pos * 32 + i0), sv = *(const f32x4*)(sn + pos * 32 + i0);
;                             *(f32x4*)(KR + (size_t)row * 64 + i0) = v[1][0] * c - v[1][1] * sv; *(f32x4*)(KR + (size_t)row * 64 + 32 + i0) = v[1][1] * c + v[1][0] * sv; } } } }
.LBB0_1749:
	s_or_b64 exec, exec, s[6:7]
	v_lshlrev_b32_e32 v136, 7, v158
	v_and_b32_e32 v136, 0x7ff80, v136
	s_waitcnt lgkmcnt(0)
	v_lshl_add_u64 v[168:169], v[142:143], 0, v[136:137]
	global_load_dwordx4 v[168:171], v[168:169], off
	v_lshl_add_u64 v[172:173], v[140:141], 0, v[136:137]
	global_load_dwordx4 v[172:175], v[172:173], off
	v_lshlrev_b64 v[176:177], 8, v[158:159]
	v_lshl_add_u64 v[176:177], v[144:145], 0, v[176:177]
	s_waitcnt vmcnt(1)
	v_mul_f32_e32 v188, v162, v170
	v_mul_f32_e32 v189, v163, v171
	v_mul_f32_e32 v190, v164, v168
	v_mul_f32_e32 v191, v165, v169
	v_mul_f32_e32 v192, v156, v170
	v_mul_f32_e32 v193, v157, v171
	v_mul_f32_e32 v194, v160, v168
	v_mul_f32_e32 v195, v161, v169
	s_waitcnt vmcnt(0)
	v_pk_fma_f32 v[170:171], v[156:157], v[174:175], v[188:189] neg_lo:[0,0,1] neg_hi:[0,0,1]
	v_pk_fma_f32 v[168:169], v[160:161], v[172:173], v[190:191] neg_lo:[0,0,1] neg_hi:[0,0,1]
	v_fma_f32 v162, v162, v174, v192
	v_fma_f32 v163, v163, v175, v193
	v_fma_f32 v160, v164, v172, v194
	v_fma_f32 v161, v165, v173, v195
	global_store_dwordx4 v[176:177], v[168:171], off
	global_store_dwordx4 v[176:177], v[160:163], off offset:128

; __device__ __forceinline__ unsigned cvt_pk_bf16(float lo, float hi) { unsigned r; asm volatile("v_cvt_pk_bf16_f32 %0, %1, %2" : "=v"(r) : "v"(lo), "v"(hi)); return r; }
; DI float shx(float v, int mask, int lane) { return __int_as_float(__builtin_amdgcn_ds_bpermute((lane ^ mask) << 2, __float_as_int(v))); }
;     DI void operator()(const f32x4 (&acc)[2][2][4][2], const Unit& u, int wr, int wc, int fr, int fq) const {
;     ...
;         if (pn >= 2 && pn < 6) {
;             const float* gp = pn < 4 ? gdq : gdk; const float gsc = pn < 4 ? 0.125f * LOG2E : 1.f;
;             f32x4 g[2][2];
; #pragma unroll
;             for (int bj = 0; bj < 2; ++bj)
; #pragma unroll
;                 for (int n = 0; n < 2; ++n) g[bj][n] = *(const f32x4*)(gp + 32 * bj + 8 * fq + 4 * n) * gsc;
; #pragma unroll
;             for (int ai = 0; ai < 2; ++ai)
; #pragma unroll
;                 for (int m = 0; m < 4; ++m) { const int row = row0 + ai * 128 + m * 16; const float s = rs[row]; float ss = 0.f;
; #pragma unroll
;                     for (int bj = 0; bj < 2; ++bj)
; #pragma unroll
;                         for (int n = 0; n < 2; ++n) { const f32x4 v = acc[ai][bj][m][n]; ss += (v[0] * v[0] + v[1] * v[1]) + (v[2] * v[2] + v[3] * v[3]); }
;                     ss += shx(ss, 16, ln); ss += shx(ss, 32, ln);
;                     const float r = s * rsqrtf(ss * s * s * (1.f / 64.f) + EPS);
;                     bf16_t* rowp = O + (size_t)row * 2048 + pn * 256 + 64 * wc + 8 * fq;
; #pragma unroll
;                     for (int bj = 0; bj < 2; ++bj) { const f32x4 v0 = acc[ai][bj][m][0] * r * g[bj][0], v1 = acc[ai][bj][m][1] * r * g[bj][1]; u32x4 w;
;                         w.x = cvt_pk_bf16(v0[0], v0[1]); w.y = cvt_pk_bf16(v0[2], v0[3]); w.z = cvt_pk_bf16(v1[0], v1[1]); w.w = cvt_pk_bf16(v1[2], v1[3]);
;                         *(u32x4*)(rowp + 32 * bj) = w; } }
.LBB0_1752:
	s_waitcnt lgkmcnt(0)
	v_lshl_add_u64 v[156:157], v[154:155], 2, s[18:19]
	s_cmp_lt_u32 s48, 4
	global_load_dword v187, v[156:157], off
	s_cselect_b64 vcc, -1, 0
	s_and_b64 s[2:3], vcc, exec
	s_cselect_b32 s3, s39, s41
	s_cselect_b32 s2, s38, s40
	v_lshlrev_b32_e32 v136, 2, v138
	global_load_dwordx4 v[160:163], v136, s[2:3]
	global_load_dwordx4 v[164:167], v136, s[2:3] offset:16
	global_load_dwordx4 v[168:171], v136, s[2:3] offset:128
	global_load_dwordx4 v[188:191], v136, s[2:3] offset:144
	v_mul_f32_e32 v158, v126, v126
	v_mul_f32_e32 v159, v127, v127
	v_mul_f32_e32 v174, v124, v124
	v_mul_f32_e32 v175, v125, v125
	v_mul_f32_e32 v176, v122, v122
	v_mul_f32_e32 v177, v123, v123
	v_mul_f32_e32 v192, v120, v120
	v_mul_f32_e32 v193, v121, v121
	v_pk_mov_b32 v[198:199], v[174:175], v[158:159] op_sel:[1,0]
	v_mov_b32_e32 v175, v159
	v_pk_mov_b32 v[158:159], v[192:193], v[176:177] op_sel:[1,0]
	v_mov_b32_e32 v193, v177
	v_mul_f32_e32 v136, v117, v117
	v_mul_f32_e32 v194, v119, v119
	v_add_f32_e32 v174, v198, v174
	v_add_f32_e32 v175, v199, v175
	v_add_f32_e32 v158, v158, v192
	v_add_f32_e32 v159, v159, v193
	v_mul_f32_e32 v173, v112, v112
	v_mul_f32_e32 v200, v113, v113
	v_mul_f32_e32 v201, v114, v114
	v_mul_f32_e32 v202, v115, v115
	v_pk_fma_f32 v[176:177], v[116:117], v[116:117], v[136:137] op_sel_hi:[1,1,0]
	v_pk_fma_f32 v[194:195], v[118:119], v[118:119], v[194:195] op_sel_hi:[1,1,0]
	v_pk_add_f32 v[174:175], v[174:175], v[174:175] op_sel:[0,1] op_sel_hi:[1,0]
	v_pk_add_f32 v[158:159], v[158:159], v[158:159] op_sel:[0,1] op_sel_hi:[1,0]
	v_mov_b32_e32 v177, v201
	v_mov_b32_e32 v195, v202
	v_mov_b32_e32 v175, v173
	v_mov_b32_e32 v159, v200
	v_add_f32_e32 v176, v176, v194
	v_add_f32_e32 v177, v177, v195
	v_add_f32_e32 v158, v174, v158
	v_add_f32_e32 v159, v175, v159
	v_lshlrev_b64 v[196:197], 12, v[154:155]
	v_add_f32_e32 v158, v158, v176
	v_add_f32_e32 v159, v159, v177
	s_lshl_b32 s48, s48, 9
	v_add_f32_e32 v155, v158, v159
	ds_bpermute_b32 v173, v179, v155
	v_lshl_add_u64 v[158:159], s[14:15], 0, v[196:197]
	s_mov_b32 s67, s49
	v_lshl_add_u64 v[158:159], v[158:159], 0, s[48:49]
	v_cndmask_b32_e32 v172, 1.0, v186, vcc
	s_waitcnt lgkmcnt(0)
	v_add_f32_e32 v155, v155, v173
	ds_bpermute_b32 v173, v180, v155
	v_lshlrev_b32_e32 v136, 1, v138
	v_lshl_add_u64 v[158:159], v[158:159], 0, s[66:67]
	v_lshl_add_u64 v[174:175], v[158:159], 0, v[136:137]
	v_or_b32_e32 v176, 16, v154
	s_waitcnt lgkmcnt(0)
	v_add_f32_e32 v155, v155, v173
	s_mov_b32 s6, 0x80000
	s_mov_b64 s[2:3], 0x80000
	s_waitcnt vmcnt(0)
	v_mul_f32_e32 v155, v187, v155
	v_mul_f32_e32 v155, v187, v155
	v_fmamk_f32 v155, v155, 0x3c800000, v185
	v_mul_f32_e32 v158, v172, v162
	v_mul_f32_e32 v159, v172, v163
	v_mul_f32_e32 v162, v172, v166
	v_mul_f32_e32 v163, v172, v167
	v_mul_f32_e32 v166, v172, v170
	v_mul_f32_e32 v167, v172, v171
	v_mul_f32_e32 v170, 0x4b800000, v155
	v_cmp_gt_f32_e32 vcc, s93, v155
	v_mul_f32_e32 v160, v172, v160
	v_mul_f32_e32 v161, v172, v161
	v_mul_f32_e32 v164, v172, v164
	v_mul_f32_e32 v165, v172, v165
	v_cndmask_b32_e32 v155, v155, v170, vcc
	v_rsq_f32_e32 v155, v155
	v_mul_f32_e32 v168, v172, v168
	v_mul_f32_e32 v169, v172, v169
	v_mul_f32_e32 v170, v172, v190
	v_mul_f32_e32 v171, v172, v191
	v_mul_f32_e32 v173, v172, v189
	v_mul_f32_e32 v172, v172, v188
	v_mul_f32_e32 v177, 0x45800000, v155
	v_cndmask_b32_e32 v155, v155, v177, vcc
	v_mul_f32_e32 v188, v187, v155
	v_mul_f32_e32 v124, v124, v188
	v_mul_f32_e32 v125, v125, v188
	v_mul_f32_e32 v126, v126, v188
	v_mul_f32_e32 v127, v127, v188
	v_mul_f32_e32 v112, v112, v188
	v_mul_f32_e32 v113, v113, v188
	v_mul_f32_e32 v120, v120, v188
	v_mul_f32_e32 v121, v121, v188
	v_mul_f32_e32 v122, v122, v188
	v_mul_f32_e32 v123, v123, v188
	v_mul_f32_e32 v116, v116, v188
	v_mul_f32_e32 v117, v117, v188
	v_mul_f32_e32 v118, v118, v188
	v_mul_f32_e32 v119, v119, v188
	v_mul_f32_e32 v114, v114, v188
	v_mul_f32_e32 v115, v115, v188
	v_mul_f32_e32 v126, v158, v126
	v_mul_f32_e32 v127, v159, v127
	v_mul_f32_e32 v124, v160, v124
	v_mul_f32_e32 v125, v161, v125
	v_mul_f32_e32 v190, v172, v112
	v_mul_f32_e32 v191, v173, v113
	v_cvt_pk_bf16_f32 v112, v124, v125
	v_cvt_pk_bf16_f32 v113, v126, v127
	v_mul_f32_e32 v122, v162, v122
	v_mul_f32_e32 v123, v163, v123
	v_mul_f32_e32 v120, v164, v120
	v_mul_f32_e32 v121, v165, v121
	v_mul_f32_e32 v118, v166, v118
	v_mul_f32_e32 v119, v167, v119
	v_mul_f32_e32 v116, v168, v116
	v_mul_f32_e32 v117, v169, v117
	v_mul_f32_e32 v188, v170, v114
	v_mul_f32_e32 v189, v171, v115
	v_cvt_pk_bf16_f32 v114, v120, v121
	v_cvt_pk_bf16_f32 v115, v122, v123
	global_store_dwordx4 v[174:175], v[112:115], off
	v_ashrrev_i32_e32 v177, 31, v176
	v_mul_f32_e32 v120, v101, v101
	v_cvt_pk_bf16_f32 v112, v116, v117
	v_cvt_pk_bf16_f32 v113, v118, v119
	v_cvt_pk_bf16_f32 v114, v190, v191
	v_cvt_pk_bf16_f32 v115, v188, v189
	global_store_dwordx4 v[174:175], v[112:115], off offset:64
	v_mul_f32_e32 v116, v106, v106
	v_mul_f32_e32 v117, v107, v107
	v_mul_f32_e32 v118, v104, v104
	v_mul_f32_e32 v119, v105, v105
	v_lshl_add_u64 v[112:113], v[176:177], 2, s[18:19]
	global_load_dword v123, v[112:113], off
	v_mul_f32_e32 v112, v110, v110
	v_mul_f32_e32 v113, v111, v111
	v_mul_f32_e32 v114, v108, v108
	v_mul_f32_e32 v115, v109, v109
	v_mul_f32_e32 v122, v103, v103
	v_pk_mov_b32 v[124:125], v[114:115], v[112:113] op_sel:[1,0]
	v_mov_b32_e32 v115, v113
	v_pk_mov_b32 v[112:113], v[118:119], v[116:117] op_sel:[1,0]
	v_mov_b32_e32 v119, v117
	v_add_f32_e32 v114, v124, v114
	v_add_f32_e32 v115, v125, v115
	v_add_f32_e32 v112, v112, v118
	v_add_f32_e32 v113, v113, v119
	v_mul_f32_e32 v126, v96, v96
	v_mul_f32_e32 v127, v97, v97
	v_mul_f32_e32 v155, v98, v98
	v_mul_f32_e32 v187, v99, v99
	v_pk_fma_f32 v[116:117], v[100:101], v[100:101], v[120:121] op_sel_hi:[1,1,0]
	v_pk_add_f32 v[114:115], v[114:115], v[114:115] op_sel:[0,1] op_sel_hi:[1,0]
	v_pk_add_f32 v[112:113], v[112:113], v[112:113] op_sel:[0,1] op_sel_hi:[1,0]
	v_mov_b32_e32 v117, v155
	v_mov_b32_e32 v115, v126
	v_mov_b32_e32 v113, v127
	v_add_f32_e32 v112, v114, v112
	v_add_f32_e32 v113, v115, v113
	s_waitcnt vmcnt(0)
; __device__ __forceinline__ unsigned cvt_pk_bf16(float lo, float hi) { unsigned r; asm volatile("v_cvt_pk_bf16_f32 %0, %1, %2" : "=v"(r) : "v"(lo), "v"(hi)); return r; }
; DI float shx(float v, int mask, int lane) { return __int_as_float(__builtin_amdgcn_ds_bpermute((lane ^ mask) << 2, __float_as_int(v))); }
;     DI void operator()(const f32x4 (&acc)[2][2][4][2], const Unit& u, int wr, int wc, int fr, int fq) const {
;     ...
;                 for (int m = 0; m < 4; ++m) { const int row = row0 + ai * 128 + m * 16; const float s = rs[row]; float ss = 0.f;
; #pragma unroll
;                     for (int bj = 0; bj < 2; ++bj)
; #pragma unroll
;                         for (int n = 0; n < 2; ++n) { const f32x4 v = acc[ai][bj][m][n]; ss += (v[0] * v[0] + v[1] * v[1]) + (v[2] * v[2] + v[3] * v[3]); }
;                     ss += shx(ss, 16, ln); ss += shx(ss, 32, ln);
;                     const float r = s * rsqrtf(ss * s * s * (1.f / 64.f) + EPS);
;                     bf16_t* rowp = O + (size_t)row * 2048 + pn * 256 + 64 * wc + 8 * fq;
; #pragma unroll
;                     for (int bj = 0; bj < 2; ++bj) { const f32x4 v0 = acc[ai][bj][m][0] * r * g[bj][0], v1 = acc[ai][bj][m][1] * r * g[bj][1]; u32x4 w;
;                         w.x = cvt_pk_bf16(v0[0], v0[1]); w.y = cvt_pk_bf16(v0[2], v0[3]); w.z = cvt_pk_bf16(v1[0], v1[1]); w.w = cvt_pk_bf16(v1[2], v1[3]);
;                         *(u32x4*)(rowp + 32 * bj) = w; } }
	v_pk_fma_f32 v[120:121], v[102:103], v[102:103], v[122:123] op_sel_hi:[1,1,0]
	s_nop 0
	v_mov_b32_e32 v121, v187
	v_add_f32_e32 v116, v116, v120
	v_add_f32_e32 v117, v117, v121
	s_nop 0
	v_add_f32_e32 v112, v112, v116
	v_add_f32_e32 v113, v113, v117
	s_nop 0
	v_add_f32_e32 v113, v112, v113
	ds_bpermute_b32 v114, v179, v113
	v_or_b32_e32 v112, 32, v154
	s_waitcnt lgkmcnt(0)
	v_add_f32_e32 v118, v113, v114
	ds_bpermute_b32 v119, v180, v118
	v_lshlrev_b64 v[114:115], 12, v[176:177]
	v_lshl_add_u64 v[114:115], s[14:15], 0, v[114:115]
	v_lshl_add_u64 v[114:115], v[114:115], 0, s[48:49]
	v_lshl_add_u64 v[114:115], v[114:115], 0, s[66:67]
	s_waitcnt lgkmcnt(0)
	v_add_f32_e32 v118, v118, v119
	v_mul_f32_e32 v118, v123, v118
	v_mul_f32_e32 v118, v123, v118
	v_fmamk_f32 v118, v118, 0x3c800000, v185
	v_mul_f32_e32 v119, 0x4b800000, v118
	v_cmp_gt_f32_e32 vcc, s93, v118
	v_ashrrev_i32_e32 v113, 31, v112
	v_lshl_add_u64 v[114:115], v[114:115], 0, v[136:137]
	v_cndmask_b32_e32 v118, v118, v119, vcc
	v_rsq_f32_e32 v118, v118
	v_lshl_add_u64 v[116:117], v[112:113], 2, s[18:19]
	v_mul_f32_e32 v119, 0x45800000, v118
	v_cndmask_b32_e32 v118, v118, v119, vcc
	v_mul_f32_e32 v118, v123, v118
	v_mul_f32_e32 v108, v108, v118
	v_mul_f32_e32 v109, v109, v118
	v_mul_f32_e32 v110, v110, v118
	v_mul_f32_e32 v111, v111, v118
	v_mul_f32_e32 v104, v104, v118
	v_mul_f32_e32 v105, v105, v118
	v_mul_f32_e32 v106, v106, v118
	v_mul_f32_e32 v107, v107, v118
	v_mul_f32_e32 v96, v96, v118
	v_mul_f32_e32 v97, v97, v118
	v_mul_f32_e32 v98, v98, v118
	v_mul_f32_e32 v99, v99, v118
	v_mul_f32_e32 v100, v100, v118
	v_mul_f32_e32 v101, v101, v118
	v_mul_f32_e32 v102, v102, v118
	v_mul_f32_e32 v103, v103, v118
	v_mul_f32_e32 v110, v158, v110
	v_mul_f32_e32 v111, v159, v111
	v_mul_f32_e32 v108, v160, v108
	v_mul_f32_e32 v109, v161, v109
	v_mul_f32_e32 v106, v162, v106
	v_mul_f32_e32 v107, v163, v107
	v_mul_f32_e32 v104, v164, v104
	v_mul_f32_e32 v105, v165, v105
	v_mul_f32_e32 v118, v170, v98
	v_mul_f32_e32 v119, v171, v99
	v_mul_f32_e32 v120, v172, v96
	v_mul_f32_e32 v121, v173, v97
	v_cvt_pk_bf16_f32 v96, v108, v109
	v_cvt_pk_bf16_f32 v97, v110, v111
	v_cvt_pk_bf16_f32 v98, v104, v105
	v_cvt_pk_bf16_f32 v99, v106, v107
	v_mul_f32_e32 v102, v166, v102
	v_mul_f32_e32 v103, v167, v103
	v_mul_f32_e32 v100, v168, v100
	v_mul_f32_e32 v101, v169, v101
	global_store_dwordx4 v[114:115], v[96:99], off
	v_mul_f32_e32 v104, v85, v85
	v_mul_f32_e32 v106, v87, v87
	v_cvt_pk_bf16_f32 v96, v100, v101
	v_cvt_pk_bf16_f32 v97, v102, v103
	v_cvt_pk_bf16_f32 v98, v120, v121
	v_cvt_pk_bf16_f32 v99, v118, v119
	global_store_dwordx4 v[114:115], v[96:99], off offset:64
	global_load_dword v107, v[116:117], off
	v_mul_f32_e32 v100, v90, v90
	v_mul_f32_e32 v101, v91, v91
	v_mul_f32_e32 v96, v94, v94
	v_mul_f32_e32 v97, v95, v95
	v_mul_f32_e32 v98, v92, v92
	v_mul_f32_e32 v99, v93, v93
	v_mul_f32_e32 v102, v88, v88
	v_mul_f32_e32 v103, v89, v89
	v_pk_mov_b32 v[108:109], v[98:99], v[96:97] op_sel:[1,0]
	v_mov_b32_e32 v99, v97
	v_pk_mov_b32 v[96:97], v[102:103], v[100:101] op_sel:[1,0]
	v_mov_b32_e32 v103, v101
	v_add_f32_e32 v98, v108, v98
	v_add_f32_e32 v99, v109, v99
	v_add_f32_e32 v96, v96, v102
	v_add_f32_e32 v97, v97, v103
	v_mul_f32_e32 v110, v80, v80
	v_mul_f32_e32 v111, v81, v81
	v_mul_f32_e32 v114, v82, v82
	v_mul_f32_e32 v115, v83, v83
	v_pk_fma_f32 v[100:101], v[84:85], v[84:85], v[104:105] op_sel_hi:[1,1,0]
	v_pk_add_f32 v[98:99], v[98:99], v[98:99] op_sel:[0,1] op_sel_hi:[1,0]
	v_pk_add_f32 v[96:97], v[96:97], v[96:97] op_sel:[0,1] op_sel_hi:[1,0]
	v_mov_b32_e32 v101, v114
	v_mov_b32_e32 v99, v110
	v_mov_b32_e32 v97, v111
	v_add_f32_e32 v96, v98, v96
	v_add_f32_e32 v97, v99, v97
	s_waitcnt vmcnt(0)
	v_pk_fma_f32 v[104:105], v[86:87], v[86:87], v[106:107] op_sel_hi:[1,1,0]
	s_nop 0
	v_mov_b32_e32 v105, v115
	v_add_f32_e32 v100, v100, v104
	v_add_f32_e32 v101, v101, v105
	s_nop 0
	v_add_f32_e32 v96, v96, v100
	v_add_f32_e32 v97, v97, v101
	s_nop 0
	v_add_f32_e32 v97, v96, v97
	ds_bpermute_b32 v98, v179, v97
	v_or_b32_e32 v96, 48, v154
	s_waitcnt lgkmcnt(0)
	v_add_f32_e32 v102, v97, v98
	ds_bpermute_b32 v103, v180, v102
	v_lshlrev_b64 v[98:99], 12, v[112:113]
	v_lshl_add_u64 v[98:99], s[14:15], 0, v[98:99]
	v_lshl_add_u64 v[98:99], v[98:99], 0, s[48:49]
	v_lshl_add_u64 v[98:99], v[98:99], 0, s[66:67]
	s_waitcnt lgkmcnt(0)
; __device__ __forceinline__ unsigned cvt_pk_bf16(float lo, float hi) { unsigned r; asm volatile("v_cvt_pk_bf16_f32 %0, %1, %2" : "=v"(r) : "v"(lo), "v"(hi)); return r; }
; DI float shx(float v, int mask, int lane) { return __int_as_float(__builtin_amdgcn_ds_bpermute((lane ^ mask) << 2, __float_as_int(v))); }
;     DI void operator()(const f32x4 (&acc)[2][2][4][2], const Unit& u, int wr, int wc, int fr, int fq) const {
;     ...
;                 for (int m = 0; m < 4; ++m) { const int row = row0 + ai * 128 + m * 16; const float s = rs[row]; float ss = 0.f;
; #pragma unroll
;                     for (int bj = 0; bj < 2; ++bj)
; #pragma unroll
;                         for (int n = 0; n < 2; ++n) { const f32x4 v = acc[ai][bj][m][n]; ss += (v[0] * v[0] + v[1] * v[1]) + (v[2] * v[2] + v[3] * v[3]); }
;                     ss += shx(ss, 16, ln); ss += shx(ss, 32, ln);
;                     const float r = s * rsqrtf(ss * s * s * (1.f / 64.f) + EPS);
;                     bf16_t* rowp = O + (size_t)row * 2048 + pn * 256 + 64 * wc + 8 * fq;
; #pragma unroll
;                     for (int bj = 0; bj < 2; ++bj) { const f32x4 v0 = acc[ai][bj][m][0] * r * g[bj][0], v1 = acc[ai][bj][m][1] * r * g[bj][1]; u32x4 w;
;                         w.x = cvt_pk_bf16(v0[0], v0[1]); w.y = cvt_pk_bf16(v0[2], v0[3]); w.z = cvt_pk_bf16(v1[0], v1[1]); w.w = cvt_pk_bf16(v1[2], v1[3]);
;                         *(u32x4*)(rowp + 32 * bj) = w; } }
	v_add_f32_e32 v102, v102, v103
	v_mul_f32_e32 v102, v107, v102
	v_mul_f32_e32 v102, v107, v102
	v_fmamk_f32 v102, v102, 0x3c800000, v185
	v_mul_f32_e32 v103, 0x4b800000, v102
	v_cmp_gt_f32_e32 vcc, s93, v102
	v_ashrrev_i32_e32 v97, 31, v96
	v_lshl_add_u64 v[98:99], v[98:99], 0, v[136:137]
	v_cndmask_b32_e32 v102, v102, v103, vcc
	v_rsq_f32_e32 v102, v102
	v_lshl_add_u64 v[100:101], v[96:97], 2, s[18:19]
	v_mul_f32_e32 v103, 0x45800000, v102
	v_cndmask_b32_e32 v102, v102, v103, vcc
	v_mul_f32_e32 v102, v107, v102
	v_mul_f32_e32 v92, v92, v102
	v_mul_f32_e32 v93, v93, v102
	v_mul_f32_e32 v94, v94, v102
	v_mul_f32_e32 v95, v95, v102
	v_mul_f32_e32 v88, v88, v102
	v_mul_f32_e32 v89, v89, v102
	v_mul_f32_e32 v90, v90, v102
	v_mul_f32_e32 v91, v91, v102
	v_mul_f32_e32 v80, v80, v102
	v_mul_f32_e32 v81, v81, v102
	v_mul_f32_e32 v82, v82, v102
	v_mul_f32_e32 v83, v83, v102
	v_mul_f32_e32 v84, v84, v102
	v_mul_f32_e32 v85, v85, v102
	v_mul_f32_e32 v86, v86, v102
	v_mul_f32_e32 v87, v87, v102
	v_mul_f32_e32 v94, v158, v94
	v_mul_f32_e32 v95, v159, v95
	v_mul_f32_e32 v92, v160, v92
	v_mul_f32_e32 v93, v161, v93
	v_mul_f32_e32 v90, v162, v90
	v_mul_f32_e32 v91, v163, v91
	v_mul_f32_e32 v88, v164, v88
	v_mul_f32_e32 v89, v165, v89
	v_mul_f32_e32 v102, v170, v82
	v_mul_f32_e32 v103, v171, v83
	v_mul_f32_e32 v104, v172, v80
	v_mul_f32_e32 v105, v173, v81
	v_cvt_pk_bf16_f32 v80, v92, v93
	v_cvt_pk_bf16_f32 v81, v94, v95
	v_cvt_pk_bf16_f32 v82, v88, v89
	v_cvt_pk_bf16_f32 v83, v90, v91
	v_mul_f32_e32 v86, v166, v86
	v_mul_f32_e32 v87, v167, v87
	v_mul_f32_e32 v84, v168, v84
	v_mul_f32_e32 v85, v169, v85
	global_store_dwordx4 v[98:99], v[80:83], off
	v_mul_f32_e32 v88, v69, v69
	v_mul_f32_e32 v90, v71, v71
	v_cvt_pk_bf16_f32 v80, v84, v85
	v_cvt_pk_bf16_f32 v81, v86, v87
	v_cvt_pk_bf16_f32 v82, v104, v105
	v_cvt_pk_bf16_f32 v83, v102, v103
	global_store_dwordx4 v[98:99], v[80:83], off offset:64
	global_load_dword v91, v[100:101], off
	v_mul_f32_e32 v84, v74, v74
	v_mul_f32_e32 v85, v75, v75
	v_mul_f32_e32 v80, v78, v78
	v_mul_f32_e32 v81, v79, v79
	v_mul_f32_e32 v82, v76, v76
	v_mul_f32_e32 v83, v77, v77
	v_mul_f32_e32 v86, v72, v72
	v_mul_f32_e32 v87, v73, v73
	v_pk_mov_b32 v[92:93], v[82:83], v[80:81] op_sel:[1,0]
	v_mov_b32_e32 v83, v81
	v_pk_mov_b32 v[80:81], v[86:87], v[84:85] op_sel:[1,0]
	v_mov_b32_e32 v87, v85
	v_add_f32_e32 v82, v92, v82
	v_add_f32_e32 v83, v93, v83
	v_add_f32_e32 v80, v80, v86
	v_add_f32_e32 v81, v81, v87
	v_mul_f32_e32 v94, v64, v64
	v_mul_f32_e32 v95, v65, v65
	v_mul_f32_e32 v98, v66, v66
	v_mul_f32_e32 v99, v67, v67
	v_pk_fma_f32 v[84:85], v[68:69], v[68:69], v[88:89] op_sel_hi:[1,1,0]
	v_pk_add_f32 v[82:83], v[82:83], v[82:83] op_sel:[0,1] op_sel_hi:[1,0]
	v_pk_add_f32 v[80:81], v[80:81], v[80:81] op_sel:[0,1] op_sel_hi:[1,0]
	v_mov_b32_e32 v85, v98
	v_mov_b32_e32 v83, v94
	v_mov_b32_e32 v81, v95
	v_add_f32_e32 v80, v82, v80
	v_add_f32_e32 v81, v83, v81
	s_waitcnt vmcnt(0)
	v_pk_fma_f32 v[88:89], v[70:71], v[70:71], v[90:91] op_sel_hi:[1,1,0]
	s_nop 0
	v_mov_b32_e32 v89, v99
	v_add_f32_e32 v84, v84, v88
	v_add_f32_e32 v85, v85, v89
	s_nop 0
	v_add_f32_e32 v80, v80, v84
	v_add_f32_e32 v81, v81, v85
	s_nop 0
	v_add_f32_e32 v80, v80, v81
	ds_bpermute_b32 v81, v179, v80
	s_waitcnt lgkmcnt(0)
	v_add_f32_e32 v82, v80, v81
	ds_bpermute_b32 v83, v180, v82
	v_lshlrev_b64 v[80:81], 12, v[96:97]
	v_lshl_add_u64 v[80:81], s[14:15], 0, v[80:81]
	v_lshl_add_u64 v[80:81], v[80:81], 0, s[48:49]
	v_lshl_add_u64 v[80:81], v[80:81], 0, s[66:67]
	s_waitcnt lgkmcnt(0)
	v_add_f32_e32 v82, v82, v83
	v_mul_f32_e32 v82, v91, v82
	v_mul_f32_e32 v82, v91, v82
	v_fmamk_f32 v82, v82, 0x3c800000, v185
	v_mul_f32_e32 v83, 0x4b800000, v82
	v_cmp_gt_f32_e32 vcc, s93, v82
	v_lshl_add_u64 v[80:81], v[80:81], 0, v[136:137]
	s_nop 0
	v_cndmask_b32_e32 v82, v82, v83, vcc
	v_rsq_f32_e32 v82, v82
	s_nop 0
	v_mul_f32_e32 v83, 0x45800000, v82
	v_cndmask_b32_e32 v82, v82, v83, vcc
	v_mul_f32_e32 v82, v91, v82
	v_mul_f32_e32 v76, v76, v82
	v_mul_f32_e32 v77, v77, v82
	v_mul_f32_e32 v78, v78, v82
	v_mul_f32_e32 v79, v79, v82
	v_mul_f32_e32 v72, v72, v82
	v_mul_f32_e32 v73, v73, v82
	v_mul_f32_e32 v74, v74, v82
	v_mul_f32_e32 v75, v75, v82
	v_mul_f32_e32 v64, v64, v82
	v_mul_f32_e32 v65, v65, v82
	v_mul_f32_e32 v66, v66, v82
	v_mul_f32_e32 v67, v67, v82
	v_mul_f32_e32 v68, v68, v82
	v_mul_f32_e32 v69, v69, v82
	v_mul_f32_e32 v70, v70, v82
	v_mul_f32_e32 v71, v71, v82
	v_mul_f32_e32 v78, v158, v78
	v_mul_f32_e32 v79, v159, v79
	v_mul_f32_e32 v76, v160, v76
	v_mul_f32_e32 v77, v161, v77
	v_mul_f32_e32 v74, v162, v74
	v_mul_f32_e32 v75, v163, v75
	v_mul_f32_e32 v72, v164, v72
	v_mul_f32_e32 v73, v165, v73
	v_mul_f32_e32 v82, v170, v66
	v_mul_f32_e32 v83, v171, v67
	v_mul_f32_e32 v84, v172, v64
	v_mul_f32_e32 v85, v173, v65
	v_cvt_pk_bf16_f32 v64, v76, v77
	v_cvt_pk_bf16_f32 v65, v78, v79
	v_cvt_pk_bf16_f32 v66, v72, v73
	v_cvt_pk_bf16_f32 v67, v74, v75
	v_mul_f32_e32 v70, v166, v70
	v_mul_f32_e32 v71, v167, v71
	v_mul_f32_e32 v68, v168, v68
	v_mul_f32_e32 v69, v169, v69
	global_store_dwordx4 v[80:81], v[64:67], off
	v_mul_f32_e32 v72, v53, v53
	v_mul_f32_e32 v74, v55, v55
	v_cvt_pk_bf16_f32 v64, v68, v69
	v_cvt_pk_bf16_f32 v65, v70, v71
	v_cvt_pk_bf16_f32 v66, v84, v85
	v_cvt_pk_bf16_f32 v67, v82, v83
	global_store_dwordx4 v[80:81], v[64:67], off offset:64
	global_load_dword v75, v[156:157], off offset:512
	v_mul_f32_e32 v68, v58, v58
	v_mul_f32_e32 v69, v59, v59
	v_mul_f32_e32 v64, v62, v62
	v_mul_f32_e32 v65, v63, v63
	v_mul_f32_e32 v66, v60, v60
	v_mul_f32_e32 v67, v61, v61
	v_mul_f32_e32 v70, v56, v56
	v_mul_f32_e32 v71, v57, v57
	v_pk_mov_b32 v[76:77], v[66:67], v[64:65] op_sel:[1,0]
	v_mov_b32_e32 v67, v65
	v_pk_mov_b32 v[64:65], v[70:71], v[68:69] op_sel:[1,0]
	v_mov_b32_e32 v71, v69
	v_add_f32_e32 v66, v76, v66
	v_add_f32_e32 v67, v77, v67
	v_add_f32_e32 v64, v64, v70
	v_add_f32_e32 v65, v65, v71
	v_mul_f32_e32 v78, v48, v48
	v_mul_f32_e32 v79, v49, v49
	v_mul_f32_e32 v80, v50, v50
	v_mul_f32_e32 v81, v51, v51
	v_pk_fma_f32 v[68:69], v[52:53], v[52:53], v[72:73] op_sel_hi:[1,1,0]
	v_pk_add_f32 v[66:67], v[66:67], v[66:67] op_sel:[0,1] op_sel_hi:[1,0]
	v_pk_add_f32 v[64:65], v[64:65], v[64:65] op_sel:[0,1] op_sel_hi:[1,0]
	v_mov_b32_e32 v69, v80
	v_mov_b32_e32 v67, v78
	v_mov_b32_e32 v65, v79
	v_add_f32_e32 v64, v66, v64
	v_add_f32_e32 v65, v67, v65
	s_waitcnt vmcnt(0)
; __device__ __forceinline__ unsigned cvt_pk_bf16(float lo, float hi) { unsigned r; asm volatile("v_cvt_pk_bf16_f32 %0, %1, %2" : "=v"(r) : "v"(lo), "v"(hi)); return r; }
; DI float shx(float v, int mask, int lane) { return __int_as_float(__builtin_amdgcn_ds_bpermute((lane ^ mask) << 2, __float_as_int(v))); }
;     DI void operator()(const f32x4 (&acc)[2][2][4][2], const Unit& u, int wr, int wc, int fr, int fq) const {
;     ...
;                 for (int m = 0; m < 4; ++m) { const int row = row0 + ai * 128 + m * 16; const float s = rs[row]; float ss = 0.f;
; #pragma unroll
;                     for (int bj = 0; bj < 2; ++bj)
; #pragma unroll
;                         for (int n = 0; n < 2; ++n) { const f32x4 v = acc[ai][bj][m][n]; ss += (v[0] * v[0] + v[1] * v[1]) + (v[2] * v[2] + v[3] * v[3]); }
;                     ss += shx(ss, 16, ln); ss += shx(ss, 32, ln);
;                     const float r = s * rsqrtf(ss * s * s * (1.f / 64.f) + EPS);
;                     bf16_t* rowp = O + (size_t)row * 2048 + pn * 256 + 64 * wc + 8 * fq;
; #pragma unroll
;                     for (int bj = 0; bj < 2; ++bj) { const f32x4 v0 = acc[ai][bj][m][0] * r * g[bj][0], v1 = acc[ai][bj][m][1] * r * g[bj][1]; u32x4 w;
;                         w.x = cvt_pk_bf16(v0[0], v0[1]); w.y = cvt_pk_bf16(v0[2], v0[3]); w.z = cvt_pk_bf16(v1[0], v1[1]); w.w = cvt_pk_bf16(v1[2], v1[3]);
;                         *(u32x4*)(rowp + 32 * bj) = w; } }
	v_pk_fma_f32 v[72:73], v[54:55], v[54:55], v[74:75] op_sel_hi:[1,1,0]
	s_nop 0
	v_mov_b32_e32 v73, v81
	v_add_f32_e32 v68, v68, v72
	v_add_f32_e32 v69, v69, v73
	s_nop 0
	v_add_f32_e32 v64, v64, v68
	v_add_f32_e32 v65, v65, v69
	s_nop 0
	v_add_f32_e32 v64, v64, v65
	ds_bpermute_b32 v65, v179, v64
	s_waitcnt lgkmcnt(0)
	v_add_f32_e32 v66, v64, v65
	ds_bpermute_b32 v67, v180, v66
	v_lshl_add_u64 v[64:65], v[174:175], 0, s[2:3]
	s_mov_b64 s[2:3], 0x90000
	s_waitcnt lgkmcnt(0)
	v_add_f32_e32 v66, v66, v67
	v_mul_f32_e32 v66, v75, v66
	v_mul_f32_e32 v66, v75, v66
	v_fmamk_f32 v66, v66, 0x3c800000, v185
	v_mul_f32_e32 v67, 0x4b800000, v66
	v_cmp_gt_f32_e32 vcc, s93, v66
	s_nop 1
	v_cndmask_b32_e32 v66, v66, v67, vcc
	v_rsq_f32_e32 v68, v66
	v_add_co_u32_e64 v66, s[6:7], s6, v174
	v_mul_f32_e32 v69, 0x45800000, v68
	v_cndmask_b32_e32 v68, v68, v69, vcc
	v_mul_f32_e32 v68, v75, v68
	v_mul_f32_e32 v60, v60, v68
	v_mul_f32_e32 v61, v61, v68
	v_mul_f32_e32 v62, v62, v68
	v_mul_f32_e32 v63, v63, v68
	v_mul_f32_e32 v56, v56, v68
	v_mul_f32_e32 v57, v57, v68
	v_mul_f32_e32 v58, v58, v68
	v_mul_f32_e32 v59, v59, v68
	v_mul_f32_e32 v48, v48, v68
	v_mul_f32_e32 v49, v49, v68
	v_mul_f32_e32 v50, v50, v68
	v_mul_f32_e32 v51, v51, v68
	v_addc_co_u32_e64 v67, s[6:7], 0, v175, s[6:7]
	v_mul_f32_e32 v52, v52, v68
	v_mul_f32_e32 v53, v53, v68
	v_mul_f32_e32 v54, v54, v68
	v_mul_f32_e32 v55, v55, v68
	v_mul_f32_e32 v62, v158, v62
	v_mul_f32_e32 v63, v159, v63
	v_mul_f32_e32 v60, v160, v60
	v_mul_f32_e32 v61, v161, v61
	v_mul_f32_e32 v58, v162, v58
	v_mul_f32_e32 v59, v163, v59
	v_mul_f32_e32 v56, v164, v56
	v_mul_f32_e32 v57, v165, v57
	v_mul_f32_e32 v68, v170, v50
	v_mul_f32_e32 v69, v171, v51
	v_mul_f32_e32 v70, v172, v48
	v_mul_f32_e32 v71, v173, v49
	v_cvt_pk_bf16_f32 v48, v60, v61
	v_cvt_pk_bf16_f32 v49, v62, v63
	v_cvt_pk_bf16_f32 v50, v56, v57
	v_cvt_pk_bf16_f32 v51, v58, v59
	v_mul_f32_e32 v54, v166, v54
	v_mul_f32_e32 v55, v167, v55
	v_mul_f32_e32 v52, v168, v52
	v_mul_f32_e32 v53, v169, v53
	global_store_dwordx4 v[66:67], v[48:51], off
	v_mul_f32_e32 v56, v37, v37
	v_mul_f32_e32 v58, v39, v39
	v_cvt_pk_bf16_f32 v48, v52, v53
	v_cvt_pk_bf16_f32 v49, v54, v55
	v_cvt_pk_bf16_f32 v50, v70, v71
	v_cvt_pk_bf16_f32 v51, v68, v69
	global_store_dwordx4 v[64:65], v[48:51], off offset:64
	global_load_dword v59, v[156:157], off offset:576
	v_mul_f32_e32 v52, v42, v42
	v_mul_f32_e32 v53, v43, v43
	v_mul_f32_e32 v48, v46, v46
	v_mul_f32_e32 v49, v47, v47
	v_mul_f32_e32 v50, v44, v44
	v_mul_f32_e32 v51, v45, v45
	v_mul_f32_e32 v54, v40, v40
	v_mul_f32_e32 v55, v41, v41
	v_pk_mov_b32 v[60:61], v[50:51], v[48:49] op_sel:[1,0]
	v_mov_b32_e32 v51, v49
	v_pk_mov_b32 v[48:49], v[54:55], v[52:53] op_sel:[1,0]
	v_mov_b32_e32 v55, v53
	v_add_f32_e32 v50, v60, v50
	v_add_f32_e32 v51, v61, v51
	v_add_f32_e32 v48, v48, v54
	v_add_f32_e32 v49, v49, v55
	v_mul_f32_e32 v62, v32, v32
	v_mul_f32_e32 v63, v33, v33
	v_mul_f32_e32 v64, v34, v34
	v_mul_f32_e32 v65, v35, v35
	v_pk_fma_f32 v[52:53], v[36:37], v[36:37], v[56:57] op_sel_hi:[1,1,0]
	v_pk_add_f32 v[50:51], v[50:51], v[50:51] op_sel:[0,1] op_sel_hi:[1,0]
	v_pk_add_f32 v[48:49], v[48:49], v[48:49] op_sel:[0,1] op_sel_hi:[1,0]
	v_mov_b32_e32 v53, v64
	v_mov_b32_e32 v51, v62
	v_mov_b32_e32 v49, v63
	v_add_f32_e32 v48, v50, v48
	v_add_f32_e32 v49, v51, v49
	s_mov_b32 s6, 0x90000
	s_waitcnt vmcnt(0)
	v_pk_fma_f32 v[56:57], v[38:39], v[38:39], v[58:59] op_sel_hi:[1,1,0]
	s_nop 0
	v_mov_b32_e32 v57, v65
	v_add_f32_e32 v52, v52, v56
	v_add_f32_e32 v53, v53, v57
	s_nop 0
	v_add_f32_e32 v48, v48, v52
	v_add_f32_e32 v49, v49, v53
	s_nop 0
	v_add_f32_e32 v48, v48, v49
	ds_bpermute_b32 v49, v179, v48
	s_waitcnt lgkmcnt(0)
	v_add_f32_e32 v50, v48, v49
	ds_bpermute_b32 v51, v180, v50
	v_lshl_add_u64 v[48:49], v[174:175], 0, s[2:3]
	s_mov_b64 s[2:3], 0xa0000
	s_waitcnt lgkmcnt(0)
	v_add_f32_e32 v50, v50, v51
	v_mul_f32_e32 v50, v59, v50
	v_mul_f32_e32 v50, v59, v50
	v_fmamk_f32 v50, v50, 0x3c800000, v185
	v_mul_f32_e32 v51, 0x4b800000, v50
	v_cmp_gt_f32_e32 vcc, s93, v50
	s_nop 1
	v_cndmask_b32_e32 v50, v50, v51, vcc
	v_rsq_f32_e32 v52, v50
	v_add_co_u32_e64 v50, s[6:7], s6, v174
	v_mul_f32_e32 v53, 0x45800000, v52
	v_cndmask_b32_e32 v52, v52, v53, vcc
	v_mul_f32_e32 v52, v59, v52
	v_mul_f32_e32 v44, v44, v52
	v_mul_f32_e32 v45, v45, v52
	v_mul_f32_e32 v46, v46, v52
	v_mul_f32_e32 v47, v47, v52
	v_mul_f32_e32 v40, v40, v52
	v_mul_f32_e32 v41, v41, v52
	v_mul_f32_e32 v42, v42, v52
	v_mul_f32_e32 v43, v43, v52
	v_mul_f32_e32 v32, v32, v52
	v_mul_f32_e32 v33, v33, v52
	v_mul_f32_e32 v34, v34, v52
	v_mul_f32_e32 v35, v35, v52
	v_addc_co_u32_e64 v51, s[6:7], 0, v175, s[6:7]
	v_mul_f32_e32 v36, v36, v52
	v_mul_f32_e32 v37, v37, v52
	v_mul_f32_e32 v38, v38, v52
	v_mul_f32_e32 v39, v39, v52
	v_mul_f32_e32 v46, v158, v46
	v_mul_f32_e32 v47, v159, v47
	v_mul_f32_e32 v44, v160, v44
	v_mul_f32_e32 v45, v161, v45
	v_mul_f32_e32 v42, v162, v42
	v_mul_f32_e32 v43, v163, v43
	v_mul_f32_e32 v40, v164, v40
	v_mul_f32_e32 v41, v165, v41
	v_mul_f32_e32 v52, v170, v34
	v_mul_f32_e32 v53, v171, v35
	v_mul_f32_e32 v54, v172, v32
	v_mul_f32_e32 v55, v173, v33
	v_cvt_pk_bf16_f32 v32, v44, v45
	v_cvt_pk_bf16_f32 v33, v46, v47
	v_cvt_pk_bf16_f32 v34, v40, v41
	v_cvt_pk_bf16_f32 v35, v42, v43
	v_mul_f32_e32 v38, v166, v38
	v_mul_f32_e32 v39, v167, v39
	v_mul_f32_e32 v36, v168, v36
	v_mul_f32_e32 v37, v169, v37
	global_store_dwordx4 v[50:51], v[32:35], off
	v_mul_f32_e32 v40, v21, v21
	v_mul_f32_e32 v42, v23, v23
	v_cvt_pk_bf16_f32 v32, v36, v37
	v_cvt_pk_bf16_f32 v33, v38, v39
	v_cvt_pk_bf16_f32 v34, v54, v55
	v_cvt_pk_bf16_f32 v35, v52, v53
	global_store_dwordx4 v[48:49], v[32:35], off offset:64
	global_load_dword v43, v[156:157], off offset:640
	v_mul_f32_e32 v36, v26, v26
	v_mul_f32_e32 v37, v27, v27
	v_mul_f32_e32 v32, v30, v30
	v_mul_f32_e32 v33, v31, v31
	v_mul_f32_e32 v34, v28, v28
	v_mul_f32_e32 v35, v29, v29
	v_mul_f32_e32 v38, v24, v24
	v_mul_f32_e32 v39, v25, v25
	v_pk_mov_b32 v[44:45], v[34:35], v[32:33] op_sel:[1,0]
	v_mov_b32_e32 v35, v33
	v_pk_mov_b32 v[32:33], v[38:39], v[36:37] op_sel:[1,0]
	v_mov_b32_e32 v39, v37
	v_add_f32_e32 v34, v44, v34
	v_add_f32_e32 v35, v45, v35
	v_add_f32_e32 v32, v32, v38
	v_add_f32_e32 v33, v33, v39
	v_mul_f32_e32 v46, v16, v16
	v_mul_f32_e32 v47, v17, v17
	v_mul_f32_e32 v48, v18, v18
	v_mul_f32_e32 v49, v19, v19
	v_pk_fma_f32 v[36:37], v[20:21], v[20:21], v[40:41] op_sel_hi:[1,1,0]
	v_pk_add_f32 v[34:35], v[34:35], v[34:35] op_sel:[0,1] op_sel_hi:[1,0]
	v_pk_add_f32 v[32:33], v[32:33], v[32:33] op_sel:[0,1] op_sel_hi:[1,0]
	v_mov_b32_e32 v37, v48
	v_mov_b32_e32 v35, v46
	v_mov_b32_e32 v33, v47
	v_add_f32_e32 v32, v34, v32
	v_add_f32_e32 v33, v35, v33
	s_mov_b32 s6, 0xa0000
	s_waitcnt vmcnt(0)
; __device__ __forceinline__ unsigned cvt_pk_bf16(float lo, float hi) { unsigned r; asm volatile("v_cvt_pk_bf16_f32 %0, %1, %2" : "=v"(r) : "v"(lo), "v"(hi)); return r; }
; DI float shx(float v, int mask, int lane) { return __int_as_float(__builtin_amdgcn_ds_bpermute((lane ^ mask) << 2, __float_as_int(v))); }
;     DI void operator()(const f32x4 (&acc)[2][2][4][2], const Unit& u, int wr, int wc, int fr, int fq) const {
;     ...
;                 for (int m = 0; m < 4; ++m) { const int row = row0 + ai * 128 + m * 16; const float s = rs[row]; float ss = 0.f;
; #pragma unroll
;                     for (int bj = 0; bj < 2; ++bj)
; #pragma unroll
;                         for (int n = 0; n < 2; ++n) { const f32x4 v = acc[ai][bj][m][n]; ss += (v[0] * v[0] + v[1] * v[1]) + (v[2] * v[2] + v[3] * v[3]); }
;                     ss += shx(ss, 16, ln); ss += shx(ss, 32, ln);
;                     const float r = s * rsqrtf(ss * s * s * (1.f / 64.f) + EPS);
;                     bf16_t* rowp = O + (size_t)row * 2048 + pn * 256 + 64 * wc + 8 * fq;
; #pragma unroll
;                     for (int bj = 0; bj < 2; ++bj) { const f32x4 v0 = acc[ai][bj][m][0] * r * g[bj][0], v1 = acc[ai][bj][m][1] * r * g[bj][1]; u32x4 w;
;                         w.x = cvt_pk_bf16(v0[0], v0[1]); w.y = cvt_pk_bf16(v0[2], v0[3]); w.z = cvt_pk_bf16(v1[0], v1[1]); w.w = cvt_pk_bf16(v1[2], v1[3]);
;                         *(u32x4*)(rowp + 32 * bj) = w; } }
;             return;
	v_pk_fma_f32 v[40:41], v[22:23], v[22:23], v[42:43] op_sel_hi:[1,1,0]
	s_nop 0
	v_mov_b32_e32 v41, v49
	v_add_f32_e32 v36, v36, v40
	v_add_f32_e32 v37, v37, v41
	s_nop 0
	v_add_f32_e32 v32, v32, v36
	v_add_f32_e32 v33, v33, v37
	s_nop 0
	v_add_f32_e32 v32, v32, v33
	ds_bpermute_b32 v33, v179, v32
	s_waitcnt lgkmcnt(0)
	v_add_f32_e32 v34, v32, v33
	ds_bpermute_b32 v35, v180, v34
	v_lshl_add_u64 v[32:33], v[174:175], 0, s[2:3]
	s_mov_b64 s[2:3], 0xb0000
	s_waitcnt lgkmcnt(0)
	v_add_f32_e32 v34, v34, v35
	v_mul_f32_e32 v34, v43, v34
	v_mul_f32_e32 v34, v43, v34
	v_fmamk_f32 v34, v34, 0x3c800000, v185
	v_mul_f32_e32 v35, 0x4b800000, v34
	v_cmp_gt_f32_e32 vcc, s93, v34
	s_nop 1
	v_cndmask_b32_e32 v34, v34, v35, vcc
	v_rsq_f32_e32 v36, v34
	v_add_co_u32_e64 v34, s[6:7], s6, v174
	v_mul_f32_e32 v37, 0x45800000, v36
	v_cndmask_b32_e32 v36, v36, v37, vcc
	v_mul_f32_e32 v36, v43, v36
	v_mul_f32_e32 v28, v28, v36
	v_mul_f32_e32 v29, v29, v36
	v_mul_f32_e32 v30, v30, v36
	v_mul_f32_e32 v31, v31, v36
	v_mul_f32_e32 v24, v24, v36
	v_mul_f32_e32 v25, v25, v36
	v_mul_f32_e32 v26, v26, v36
	v_mul_f32_e32 v27, v27, v36
	v_mul_f32_e32 v16, v16, v36
	v_mul_f32_e32 v17, v17, v36
	v_mul_f32_e32 v18, v18, v36
	v_mul_f32_e32 v19, v19, v36
	v_addc_co_u32_e64 v35, s[6:7], 0, v175, s[6:7]
	v_mul_f32_e32 v20, v20, v36
	v_mul_f32_e32 v21, v21, v36
	v_mul_f32_e32 v22, v22, v36
	v_mul_f32_e32 v23, v23, v36
	v_mul_f32_e32 v30, v158, v30
	v_mul_f32_e32 v31, v159, v31
	v_mul_f32_e32 v28, v160, v28
	v_mul_f32_e32 v29, v161, v29
	v_mul_f32_e32 v26, v162, v26
	v_mul_f32_e32 v27, v163, v27
	v_mul_f32_e32 v24, v164, v24
	v_mul_f32_e32 v25, v165, v25
	v_mul_f32_e32 v36, v170, v18
	v_mul_f32_e32 v37, v171, v19
	v_mul_f32_e32 v38, v172, v16
	v_mul_f32_e32 v39, v173, v17
	v_cvt_pk_bf16_f32 v16, v28, v29
	v_cvt_pk_bf16_f32 v17, v30, v31
	v_cvt_pk_bf16_f32 v18, v24, v25
	v_cvt_pk_bf16_f32 v19, v26, v27
	v_mul_f32_e32 v22, v166, v22
	v_mul_f32_e32 v23, v167, v23
	v_mul_f32_e32 v20, v168, v20
	v_mul_f32_e32 v21, v169, v21
	global_store_dwordx4 v[34:35], v[16:19], off
	v_mul_f32_e32 v24, v5, v5
	v_mul_f32_e32 v26, v7, v7
	v_cvt_pk_bf16_f32 v16, v20, v21
	v_cvt_pk_bf16_f32 v17, v22, v23
	v_cvt_pk_bf16_f32 v18, v38, v39
	v_cvt_pk_bf16_f32 v19, v36, v37
	global_store_dwordx4 v[32:33], v[16:19], off offset:64
	global_load_dword v27, v[156:157], off offset:704
	v_mul_f32_e32 v20, v10, v10
	v_mul_f32_e32 v21, v11, v11
	v_mul_f32_e32 v16, v14, v14
	v_mul_f32_e32 v17, v15, v15
	v_mul_f32_e32 v18, v12, v12
	v_mul_f32_e32 v19, v13, v13
	v_mul_f32_e32 v22, v8, v8
	v_mul_f32_e32 v23, v9, v9
	v_pk_mov_b32 v[28:29], v[18:19], v[16:17] op_sel:[1,0]
	v_mov_b32_e32 v19, v17
	v_pk_mov_b32 v[16:17], v[22:23], v[20:21] op_sel:[1,0]
	v_mov_b32_e32 v23, v21
	v_add_f32_e32 v18, v28, v18
	v_add_f32_e32 v19, v29, v19
	v_add_f32_e32 v16, v16, v22
	v_add_f32_e32 v17, v17, v23
	v_mul_f32_e32 v30, v0, v0
	v_mul_f32_e32 v31, v1, v1
	v_mul_f32_e32 v32, v2, v2
	v_mul_f32_e32 v33, v3, v3
	v_pk_fma_f32 v[20:21], v[4:5], v[4:5], v[24:25] op_sel_hi:[1,1,0]
	v_pk_add_f32 v[18:19], v[18:19], v[18:19] op_sel:[0,1] op_sel_hi:[1,0]
	v_pk_add_f32 v[16:17], v[16:17], v[16:17] op_sel:[0,1] op_sel_hi:[1,0]
	v_mov_b32_e32 v21, v32
	v_mov_b32_e32 v19, v30
	v_mov_b32_e32 v17, v31
	v_add_f32_e32 v16, v18, v16
	v_add_f32_e32 v17, v19, v17
	s_waitcnt vmcnt(0)
	v_pk_fma_f32 v[24:25], v[6:7], v[6:7], v[26:27] op_sel_hi:[1,1,0]
	s_nop 0
	v_mov_b32_e32 v25, v33
	v_add_f32_e32 v20, v20, v24
	v_add_f32_e32 v21, v21, v25
	s_nop 0
	v_add_f32_e32 v16, v16, v20
	v_add_f32_e32 v17, v17, v21
	s_nop 0
	v_add_f32_e32 v16, v16, v17
	ds_bpermute_b32 v17, v179, v16
	s_waitcnt lgkmcnt(0)
	v_add_f32_e32 v18, v16, v17
	ds_bpermute_b32 v19, v180, v18
	v_lshl_add_u64 v[16:17], v[174:175], 0, s[2:3]
	s_waitcnt lgkmcnt(0)
	v_add_f32_e32 v18, v18, v19
	v_mul_f32_e32 v18, v27, v18
	v_mul_f32_e32 v18, v27, v18
	v_fmamk_f32 v18, v18, 0x3c800000, v185
	v_mul_f32_e32 v19, 0x4b800000, v18
	v_cmp_gt_f32_e32 vcc, s93, v18
	s_nop 1
	v_cndmask_b32_e32 v18, v18, v19, vcc
	v_rsq_f32_e32 v20, v18
	v_add_co_u32_e64 v18, s[6:7], s94, v174
	v_mul_f32_e32 v21, 0x45800000, v20
	v_cndmask_b32_e32 v20, v20, v21, vcc
	v_mul_f32_e32 v20, v27, v20
	v_mul_f32_e32 v12, v12, v20
	v_mul_f32_e32 v13, v13, v20
	v_mul_f32_e32 v14, v14, v20
	v_mul_f32_e32 v15, v15, v20
	v_mul_f32_e32 v8, v8, v20
	v_mul_f32_e32 v9, v9, v20
	v_mul_f32_e32 v10, v10, v20
	v_mul_f32_e32 v11, v11, v20
	v_mul_f32_e32 v0, v0, v20
	v_mul_f32_e32 v1, v1, v20
	v_mul_f32_e32 v2, v2, v20
	v_mul_f32_e32 v3, v3, v20
	v_addc_co_u32_e64 v19, s[6:7], 0, v175, s[6:7]
	v_mul_f32_e32 v4, v4, v20
	v_mul_f32_e32 v5, v5, v20
	v_mul_f32_e32 v6, v6, v20
	v_mul_f32_e32 v7, v7, v20
	v_mul_f32_e32 v14, v158, v14
	v_mul_f32_e32 v15, v159, v15
	v_mul_f32_e32 v12, v160, v12
	v_mul_f32_e32 v13, v161, v13
	v_mul_f32_e32 v10, v162, v10
	v_mul_f32_e32 v11, v163, v11
	v_mul_f32_e32 v8, v164, v8
	v_mul_f32_e32 v9, v165, v9
	v_mul_f32_e32 v20, v170, v2
	v_mul_f32_e32 v21, v171, v3
	v_mul_f32_e32 v22, v172, v0
	v_mul_f32_e32 v23, v173, v1
	v_cvt_pk_bf16_f32 v0, v12, v13
	v_cvt_pk_bf16_f32 v1, v14, v15
	v_cvt_pk_bf16_f32 v2, v8, v9
	v_cvt_pk_bf16_f32 v3, v10, v11
	v_mul_f32_e32 v6, v166, v6
	v_mul_f32_e32 v7, v167, v7
	v_mul_f32_e32 v4, v168, v4
	v_mul_f32_e32 v5, v169, v5
	global_store_dwordx4 v[18:19], v[0:3], off
	s_nop 1
	v_cvt_pk_bf16_f32 v0, v4, v5
	v_cvt_pk_bf16_f32 v1, v6, v7
	v_cvt_pk_bf16_f32 v2, v22, v23
	v_cvt_pk_bf16_f32 v3, v20, v21
	global_store_dwordx4 v[16:17], v[0:3], off offset:64
	s_andn2_b64 vcc, exec, s[4:5]
	s_mov_b64 s[4:5], -1
	s_cbranch_vccnz .LBB0_1637

; __device__ __forceinline__ unsigned cvt_pk_bf16(float lo, float hi) { unsigned r; asm volatile("v_cvt_pk_bf16_f32 %0, %1, %2" : "=v"(r) : "v"(lo), "v"(hi)); return r; }
;     DI void operator()(const f32x4 (&acc)[2][2][4][2], const Unit& u, int wr, int wc, int fr, int fq) const {
;     ...
;             for (int m = 0; m < 4; ++m) { const int row = row0 + ai * 128 + m * 16; const f32x4 q4 = *(const f32x4*)(ssq4 + (size_t)row * 4);
;                 const float s = rsqrtf(((q4[0] + q4[1]) + (q4[2] + q4[3])) * (1.f / 256.f) + EPS); bf16_t* rowp = Q + (size_t)row * 768;
; #pragma unroll
;                 for (int bj = 0; bj < 2; ++bj) { const int c0 = u.pn * 256 + bj * 128 + wc * 32, h = c0 / 192, d0 = c0 - h * 192;
;                     if (d0 < 128) { const f32x4 v0 = acc[ai][bj][m][0] * s, v1 = acc[ai][bj][m][1] * s; u32x4 w;
;                         w.x = cvt_pk_bf16(v0[0], v0[1]); w.y = cvt_pk_bf16(v0[2], v0[3]); w.z = cvt_pk_bf16(v1[0], v1[1]); w.w = cvt_pk_bf16(v1[2], v1[3]);
;                         *(u32x4*)(rowp + c0 + 8 * fq) = w; }
;                     else { const int i0 = 16 * (wc & 1) + 4 * fq, pos = row & (SEQ - 1);
;                         const f32x4 c = *(const f32x4*)(cs + pos * 32 + i0), sv = *(const f32x4*)(sn + pos * 32 + i0);
;                         const f32x4 x1 = acc[ai][bj][m][0] * s, x2 = acc[ai][bj][m][1] * s; const f32x4 o1 = x1 * c - x2 * sv, o2 = x2 * c + x1 * sv; u32x2 a, b;
;                         a.x = cvt_pk_bf16(o1[0], o1[1]); a.y = cvt_pk_bf16(o1[2], o1[3]); b.x = cvt_pk_bf16(o2[0], o2[1]); b.y = cvt_pk_bf16(o2[2], o2[3]);
;                         *(u32x2*)(rowp + h * 192 + 128 + i0) = a; *(u32x2*)(rowp + h * 192 + 160 + i0) = b; } } }
.LBB0_1790:
	v_lshl_add_u32 v154, s65, 8, v139
	v_ashrrev_i32_e32 v155, 31, v154
	v_lshl_add_u64 v[152:153], v[154:155], 4, s[20:21]
	global_load_dwordx4 v[168:171], v[152:153], off
	s_lshl_b32 s0, s64, 8
	v_mov_b64_e32 v[156:157], s[18:19]
	s_or_b32 s62, s0, s79
	v_mad_i64_i32 v[158:159], s[0:1], v154, s91, v[156:157]
	v_lshlrev_b32_e32 v136, 5, v154
	v_and_b32_e32 v136, 0x1f9e0, v136
	v_lshlrev_b32_e32 v160, 2, v136
	s_mul_hi_i32 s0, s62, 0x2aaaaaab
	s_lshr_b32 s1, s0, 31
	s_lshr_b32 s0, s0, 5
	s_add_i32 s0, s0, s1
	s_mulk_i32 s0, 0xc0
	s_sub_i32 s95, s62, s0
	s_cmpk_gt_i32 s95, 0x7f
	s_cselect_b64 s[12:13], -1, 0
	s_and_b64 s[6:7], exec, s[12:13]
	s_mov_b64 s[8:9], -1
	v_lshlrev_b32_e32 v152, 1, v140
	s_waitcnt vmcnt(0)
	v_mov_b32_e32 v156, v169
	v_mov_b32_e32 v157, v170
	v_mov_b32_e32 v169, v171
	v_add_f32_e32 v156, v156, v168
	v_add_f32_e32 v157, v157, v169
	s_nop 0
	v_add_f32_e32 v136, v156, v157
	v_fmamk_f32 v136, v136, 0x3b800000, v167
	v_mul_f32_e32 v153, 0x4b800000, v136
	v_cmp_gt_f32_e32 vcc, s90, v136
	s_nop 1
	v_cndmask_b32_e32 v136, v136, v153, vcc
	v_rsq_f32_e32 v136, v136
	s_nop 0
	v_mul_f32_e32 v153, 0x45800000, v136
	v_cndmask_b32_e32 v156, v136, v153, vcc
	v_mov_b32_e32 v157, v156
	v_mul_f32_e32 v162, v124, v156
	v_mul_f32_e32 v163, v125, v157
	v_mul_f32_e32 v124, v120, v156
	v_mul_f32_e32 v125, v121, v157
	s_mov_b64 vcc, s[6:7]
	s_cbranch_vccz .LBB0_1792
	v_mov_b32_e32 v161, v137
	v_lshl_add_u64 v[120:121], v[144:145], 0, v[160:161]
	global_load_dwordx4 v[168:171], v[120:121], off
	v_lshl_add_u64 v[120:121], v[142:143], 0, v[160:161]
	global_load_dwordx4 v[172:175], v[120:121], off
	s_sub_i32 s0, s62, s95
	v_mov_b32_e32 v120, v156
	v_mov_b32_e32 v121, v156
	v_mul_f32_e32 v176, v126, v120
	v_mul_f32_e32 v177, v127, v121
	v_mul_f32_e32 v120, v122, v120
	v_mul_f32_e32 v121, v123, v121
	s_ashr_i32 s1, s0, 31
	v_mov_b32_e32 v153, v137
	v_lshl_add_u64 v[178:179], s[0:1], 1, v[158:159]
	v_lshl_add_u64 v[178:179], v[178:179], 0, v[152:153]
	s_mov_b64 s[8:9], 0
	s_waitcnt vmcnt(0)
	v_mul_f32_e32 v180, v120, v170
	v_mul_f32_e32 v181, v121, v171
	v_mul_f32_e32 v182, v124, v168
	v_mul_f32_e32 v183, v125, v169
	v_mul_f32_e32 v170, v176, v170
	v_mul_f32_e32 v171, v177, v171
	v_mul_f32_e32 v168, v162, v168
	v_mul_f32_e32 v169, v163, v169
	v_pk_fma_f32 v[176:177], v[176:177], v[174:175], v[180:181] neg_lo:[0,0,1] neg_hi:[0,0,1]
	v_pk_fma_f32 v[180:181], v[162:163], v[172:173], v[182:183] neg_lo:[0,0,1] neg_hi:[0,0,1]
	v_fma_f32 v120, v120, v174, v170
	v_fma_f32 v121, v121, v175, v171
	v_fma_f32 v168, v124, v172, v168
	v_fma_f32 v169, v125, v173, v169
	v_cvt_pk_bf16_f32 v170, v180, v181
	v_cvt_pk_bf16_f32 v171, v176, v177
	s_nop 0
	v_cvt_pk_bf16_f32 v168, v168, v169
	v_cvt_pk_bf16_f32 v169, v120, v121
	global_store_dwordx2 v[178:179], v[170:171], off offset:256
	global_store_dwordx2 v[178:179], v[168:169], off offset:320
.LBB0_1792:
	v_lshlrev_b32_e32 v136, 1, v138
	s_andn2_b64 vcc, exec, s[8:9]
	v_lshl_add_u64 v[120:121], v[158:159], 0, v[136:137]
	s_cbranch_vccnz .LBB0_1794
	v_mov_b32_e32 v168, v156
	v_mov_b32_e32 v169, v156
	v_mul_f32_e32 v126, v126, v168
	v_mul_f32_e32 v127, v127, v169
	s_ashr_i32 s63, s62, 31
	v_mul_f32_e32 v168, v122, v168
	v_mul_f32_e32 v169, v123, v169
	v_cvt_pk_bf16_f32 v122, v162, v163
	v_cvt_pk_bf16_f32 v123, v126, v127
	v_lshl_add_u64 v[126:127], s[62:63], 1, v[120:121]
	v_cvt_pk_bf16_f32 v124, v124, v125
	v_cvt_pk_bf16_f32 v125, v168, v169
	global_store_dwordx4 v[126:127], v[122:125], off
.LBB0_1794:
	s_or_b32 s0, s62, 0x80
	s_mul_hi_i32 s1, s0, 0x2aaaaaab
	s_lshr_b32 s2, s1, 31
	s_lshr_b32 s1, s1, 5
	s_add_i32 s1, s1, s2
	s_mulk_i32 s1, 0xc0
	s_sub_i32 s94, s0, s1
	s_cmpk_gt_i32 s94, 0x7f
	s_mov_b64 s[6:7], -1
	s_cselect_b64 s[64:65], -1, 0
	s_cmpk_lt_i32 s94, 0x80
	v_mul_f32_e32 v116, v116, v156
	v_mul_f32_e32 v117, v117, v157
	v_mul_f32_e32 v112, v112, v156
	v_mul_f32_e32 v113, v113, v157
	s_cbranch_scc1 .LBB0_1796
	v_mov_b32_e32 v161, v137
	v_lshl_add_u64 v[122:123], v[144:145], 0, v[160:161]
	global_load_dwordx4 v[122:125], v[122:123], off
	v_lshl_add_u64 v[126:127], v[142:143], 0, v[160:161]
	global_load_dwordx4 v[160:163], v[126:127], off
	s_ashr_i32 s1, s94, 31
	s_ashr_i32 s2, s62, 31
	v_mov_b32_e32 v157, v156
	s_sub_u32 s0, s62, s94
	v_mul_f32_e32 v168, v114, v156
	v_mul_f32_e32 v169, v115, v157
	s_subb_u32 s1, s2, s1
	v_mov_b32_e32 v153, v137
	v_mul_f32_e32 v126, v118, v156
	v_mul_f32_e32 v127, v119, v157
	v_lshl_add_u64 v[158:159], s[0:1], 1, v[158:159]
	v_lshl_add_u64 v[158:159], v[158:159], 0, v[152:153]
	s_mov_b64 s[6:7], 0
	s_waitcnt vmcnt(0)
	v_mul_f32_e32 v170, v168, v124
	v_mul_f32_e32 v171, v169, v125
	v_mul_f32_e32 v172, v112, v122
	v_mul_f32_e32 v173, v113, v123
	v_mul_f32_e32 v122, v116, v122
	v_mul_f32_e32 v123, v117, v123
	v_mul_f32_e32 v124, v126, v124
	v_mul_f32_e32 v125, v127, v125
	v_pk_fma_f32 v[126:127], v[126:127], v[162:163], v[170:171] neg_lo:[0,0,1] neg_hi:[0,0,1]
	v_pk_fma_f32 v[170:171], v[116:117], v[160:161], v[172:173] neg_lo:[0,0,1] neg_hi:[0,0,1]
	v_fma_f32 v122, v112, v160, v122
	v_fma_f32 v123, v113, v161, v123
	v_cvt_pk_bf16_f32 v160, v170, v171
	v_cvt_pk_bf16_f32 v161, v126, v127
	v_fma_f32 v124, v168, v162, v124
	v_fma_f32 v125, v169, v163, v125
	v_cvt_pk_bf16_f32 v122, v122, v123
	s_nop 0
	v_cvt_pk_bf16_f32 v123, v124, v125
	global_store_dwordx2 v[158:159], v[160:161], off offset:512
	global_store_dwordx2 v[158:159], v[122:123], off offset:576
; __device__ __forceinline__ unsigned cvt_pk_bf16(float lo, float hi) { unsigned r; asm volatile("v_cvt_pk_bf16_f32 %0, %1, %2" : "=v"(r) : "v"(lo), "v"(hi)); return r; }
;     DI void operator()(const f32x4 (&acc)[2][2][4][2], const Unit& u, int wr, int wc, int fr, int fq) const {
;     ...
;             for (int m = 0; m < 4; ++m) { const int row = row0 + ai * 128 + m * 16; const f32x4 q4 = *(const f32x4*)(ssq4 + (size_t)row * 4);
;                 const float s = rsqrtf(((q4[0] + q4[1]) + (q4[2] + q4[3])) * (1.f / 256.f) + EPS); bf16_t* rowp = Q + (size_t)row * 768;
; #pragma unroll
;                 for (int bj = 0; bj < 2; ++bj) { const int c0 = u.pn * 256 + bj * 128 + wc * 32, h = c0 / 192, d0 = c0 - h * 192;
;                     if (d0 < 128) { const f32x4 v0 = acc[ai][bj][m][0] * s, v1 = acc[ai][bj][m][1] * s; u32x4 w;
;                         w.x = cvt_pk_bf16(v0[0], v0[1]); w.y = cvt_pk_bf16(v0[2], v0[3]); w.z = cvt_pk_bf16(v1[0], v1[1]); w.w = cvt_pk_bf16(v1[2], v1[3]);
;                         *(u32x4*)(rowp + c0 + 8 * fq) = w; }
;                     else { const int i0 = 16 * (wc & 1) + 4 * fq, pos = row & (SEQ - 1);
;                         const f32x4 c = *(const f32x4*)(cs + pos * 32 + i0), sv = *(const f32x4*)(sn + pos * 32 + i0);
;                         const f32x4 x1 = acc[ai][bj][m][0] * s, x2 = acc[ai][bj][m][1] * s; const f32x4 o1 = x1 * c - x2 * sv, o2 = x2 * c + x1 * sv; u32x2 a, b;
;                         a.x = cvt_pk_bf16(o1[0], o1[1]); a.y = cvt_pk_bf16(o1[2], o1[3]); b.x = cvt_pk_bf16(o2[0], o2[1]); b.y = cvt_pk_bf16(o2[2], o2[3]);
;                         *(u32x2*)(rowp + h * 192 + 128 + i0) = a; *(u32x2*)(rowp + h * 192 + 160 + i0) = b; } } }
.LBB0_1796:
	s_andn2_b64 vcc, exec, s[6:7]
	s_cbranch_vccnz .LBB0_1798
	v_mov_b32_e32 v157, v156
	s_ashr_i32 s63, s62, 31
	v_mul_f32_e32 v118, v118, v156
	v_mul_f32_e32 v119, v119, v157
	v_mul_f32_e32 v122, v114, v156
	v_mul_f32_e32 v123, v115, v157
	v_cvt_pk_bf16_f32 v114, v116, v117
	v_cvt_pk_bf16_f32 v115, v118, v119
	v_cvt_pk_bf16_f32 v116, v112, v113
	v_lshl_add_u64 v[112:113], s[62:63], 1, v[120:121]
	v_cvt_pk_bf16_f32 v117, v122, v123
	global_store_dwordx4 v[112:113], v[114:117], off offset:256
.LBB0_1798:
	v_or_b32_e32 v112, 16, v154
	v_ashrrev_i32_e32 v113, 31, v112
	v_lshl_add_u64 v[114:115], v[112:113], 4, s[20:21]
	global_load_dwordx4 v[116:119], v[114:115], off
	v_mov_b64_e32 v[114:115], s[18:19]
	v_cndmask_b32_e64 v113, 0, 1, s[12:13]
	v_mad_i64_i32 v[114:115], s[0:1], v112, s91, v[114:115]
	v_lshlrev_b32_e32 v120, 5, v112
	v_cmp_ne_u32_e64 s[8:9], 1, v113
	s_mov_b64 s[66:67], -1
	s_andn2_b64 vcc, exec, s[12:13]
	s_waitcnt vmcnt(0)
	v_mov_b32_e32 v112, v117
	v_mov_b32_e32 v113, v118
	v_mov_b32_e32 v117, v119
	v_add_f32_e32 v112, v112, v116
	v_add_f32_e32 v113, v113, v117
	s_nop 0
	v_add_f32_e32 v112, v112, v113
	v_fmamk_f32 v112, v112, 0x3b800000, v167
	v_mul_f32_e32 v113, 0x4b800000, v112
	v_cmp_gt_f32_e64 s[6:7], s90, v112
	s_nop 1
	v_cndmask_b32_e64 v112, v112, v113, s[6:7]
	v_rsq_f32_e32 v112, v112
	v_and_b32_e32 v113, 0x1fbe0, v120
	v_lshlrev_b32_e32 v116, 2, v113
	v_mul_f32_e32 v113, 0x45800000, v112
	v_cndmask_b32_e64 v112, v112, v113, s[6:7]
	v_mov_b32_e32 v113, v112
	v_mul_f32_e32 v118, v108, v112
	v_mul_f32_e32 v119, v109, v113
	v_mul_f32_e32 v108, v104, v112
	v_mul_f32_e32 v109, v105, v113
	s_cbranch_vccnz .LBB0_1800
	v_mov_b32_e32 v117, v137
	v_lshl_add_u64 v[104:105], v[144:145], 0, v[116:117]
	global_load_dwordx4 v[120:123], v[104:105], off
	v_lshl_add_u64 v[104:105], v[142:143], 0, v[116:117]
	global_load_dwordx4 v[124:127], v[104:105], off
	s_sub_i32 s0, s62, s95
	v_mov_b32_e32 v104, v112
	v_mov_b32_e32 v105, v112
	v_mul_f32_e32 v156, v110, v104
	v_mul_f32_e32 v157, v111, v105
	v_mul_f32_e32 v104, v106, v104
	v_mul_f32_e32 v105, v107, v105
	s_ashr_i32 s1, s0, 31
	v_mov_b32_e32 v153, v137
	v_lshl_add_u64 v[158:159], s[0:1], 1, v[114:115]
	v_lshl_add_u64 v[158:159], v[158:159], 0, v[152:153]
	s_mov_b64 s[66:67], 0
	s_waitcnt vmcnt(0)
	v_mul_f32_e32 v160, v104, v122
	v_mul_f32_e32 v161, v105, v123
	v_mul_f32_e32 v162, v108, v120
	v_mul_f32_e32 v163, v109, v121
	v_mul_f32_e32 v122, v156, v122
	v_mul_f32_e32 v123, v157, v123
	v_mul_f32_e32 v120, v118, v120
	v_mul_f32_e32 v121, v119, v121
	v_pk_fma_f32 v[156:157], v[156:157], v[126:127], v[160:161] neg_lo:[0,0,1] neg_hi:[0,0,1]
	v_pk_fma_f32 v[160:161], v[118:119], v[124:125], v[162:163] neg_lo:[0,0,1] neg_hi:[0,0,1]
	v_fma_f32 v104, v104, v126, v122
	v_fma_f32 v105, v105, v127, v123
	v_fma_f32 v120, v108, v124, v120
	v_fma_f32 v121, v109, v125, v121
	v_cvt_pk_bf16_f32 v122, v160, v161
	v_cvt_pk_bf16_f32 v123, v156, v157
	s_nop 0
	v_cvt_pk_bf16_f32 v120, v120, v121
	v_cvt_pk_bf16_f32 v121, v104, v105
	global_store_dwordx2 v[158:159], v[122:123], off offset:256
	global_store_dwordx2 v[158:159], v[120:121], off offset:320
.LBB0_1800:
	s_andn2_b64 vcc, exec, s[66:67]
	v_lshl_add_u64 v[104:105], v[114:115], 0, v[136:137]
	s_cbranch_vccnz .LBB0_1802
	v_mov_b32_e32 v120, v112
	v_mov_b32_e32 v121, v112
	v_mul_f32_e32 v110, v110, v120
	v_mul_f32_e32 v111, v111, v121
	s_ashr_i32 s63, s62, 31
	v_mul_f32_e32 v120, v106, v120
	v_mul_f32_e32 v121, v107, v121
	v_cvt_pk_bf16_f32 v106, v118, v119
	v_cvt_pk_bf16_f32 v107, v110, v111
	v_lshl_add_u64 v[110:111], s[62:63], 1, v[104:105]
	v_cvt_pk_bf16_f32 v108, v108, v109
	v_cvt_pk_bf16_f32 v109, v120, v121
	global_store_dwordx4 v[110:111], v[106:109], off
.LBB0_1802:
	s_nop 1
	v_cndmask_b32_e64 v106, 0, 1, s[64:65]
	s_mov_b64 s[12:13], -1
	v_cmp_ne_u32_e64 s[6:7], 1, v106
	s_andn2_b64 vcc, exec, s[64:65]
	v_mul_f32_e32 v100, v100, v112
	v_mul_f32_e32 v101, v101, v113
	v_mul_f32_e32 v96, v96, v112
	v_mul_f32_e32 v97, v97, v113
	s_cbranch_vccnz .LBB0_1804
	v_mov_b32_e32 v117, v137
	v_lshl_add_u64 v[106:107], v[144:145], 0, v[116:117]
	global_load_dwordx4 v[106:109], v[106:107], off
	v_lshl_add_u64 v[110:111], v[142:143], 0, v[116:117]
	global_load_dwordx4 v[116:119], v[110:111], off
	s_ashr_i32 s1, s94, 31
	s_ashr_i32 s2, s62, 31
	v_mov_b32_e32 v113, v112
	s_sub_u32 s0, s62, s94
	v_mul_f32_e32 v120, v98, v112
	v_mul_f32_e32 v121, v99, v113
	s_subb_u32 s1, s2, s1
	v_mov_b32_e32 v153, v137
	v_mul_f32_e32 v110, v102, v112
	v_mul_f32_e32 v111, v103, v113
	v_lshl_add_u64 v[114:115], s[0:1], 1, v[114:115]
	v_lshl_add_u64 v[114:115], v[114:115], 0, v[152:153]
	s_mov_b64 s[12:13], 0
	s_waitcnt vmcnt(0)
	v_mul_f32_e32 v122, v120, v108
	v_mul_f32_e32 v123, v121, v109
	v_mul_f32_e32 v124, v96, v106
	v_mul_f32_e32 v125, v97, v107
	v_mul_f32_e32 v106, v100, v106
	v_mul_f32_e32 v107, v101, v107
	v_mul_f32_e32 v108, v110, v108
	v_mul_f32_e32 v109, v111, v109
	v_pk_fma_f32 v[110:111], v[110:111], v[118:119], v[122:123] neg_lo:[0,0,1] neg_hi:[0,0,1]
	v_pk_fma_f32 v[122:123], v[100:101], v[116:117], v[124:125] neg_lo:[0,0,1] neg_hi:[0,0,1]
	v_fma_f32 v106, v96, v116, v106
	v_fma_f32 v107, v97, v117, v107
	v_cvt_pk_bf16_f32 v116, v122, v123
	v_cvt_pk_bf16_f32 v117, v110, v111
	v_fma_f32 v108, v120, v118, v108
	v_fma_f32 v109, v121, v119, v109
	v_cvt_pk_bf16_f32 v106, v106, v107
	s_nop 0
	v_cvt_pk_bf16_f32 v107, v108, v109
	global_store_dwordx2 v[114:115], v[116:117], off offset:512
	global_store_dwordx2 v[114:115], v[106:107], off offset:576
; __device__ __forceinline__ unsigned cvt_pk_bf16(float lo, float hi) { unsigned r; asm volatile("v_cvt_pk_bf16_f32 %0, %1, %2" : "=v"(r) : "v"(lo), "v"(hi)); return r; }
;     DI void operator()(const f32x4 (&acc)[2][2][4][2], const Unit& u, int wr, int wc, int fr, int fq) const {
;     ...
;             for (int m = 0; m < 4; ++m) { const int row = row0 + ai * 128 + m * 16; const f32x4 q4 = *(const f32x4*)(ssq4 + (size_t)row * 4);
;                 const float s = rsqrtf(((q4[0] + q4[1]) + (q4[2] + q4[3])) * (1.f / 256.f) + EPS); bf16_t* rowp = Q + (size_t)row * 768;
; #pragma unroll
;                 for (int bj = 0; bj < 2; ++bj) { const int c0 = u.pn * 256 + bj * 128 + wc * 32, h = c0 / 192, d0 = c0 - h * 192;
;                     if (d0 < 128) { const f32x4 v0 = acc[ai][bj][m][0] * s, v1 = acc[ai][bj][m][1] * s; u32x4 w;
;                         w.x = cvt_pk_bf16(v0[0], v0[1]); w.y = cvt_pk_bf16(v0[2], v0[3]); w.z = cvt_pk_bf16(v1[0], v1[1]); w.w = cvt_pk_bf16(v1[2], v1[3]);
;                         *(u32x4*)(rowp + c0 + 8 * fq) = w; }
;                     else { const int i0 = 16 * (wc & 1) + 4 * fq, pos = row & (SEQ - 1);
;                         const f32x4 c = *(const f32x4*)(cs + pos * 32 + i0), sv = *(const f32x4*)(sn + pos * 32 + i0);
;                         const f32x4 x1 = acc[ai][bj][m][0] * s, x2 = acc[ai][bj][m][1] * s; const f32x4 o1 = x1 * c - x2 * sv, o2 = x2 * c + x1 * sv; u32x2 a, b;
;                         a.x = cvt_pk_bf16(o1[0], o1[1]); a.y = cvt_pk_bf16(o1[2], o1[3]); b.x = cvt_pk_bf16(o2[0], o2[1]); b.y = cvt_pk_bf16(o2[2], o2[3]);
;                         *(u32x2*)(rowp + h * 192 + 128 + i0) = a; *(u32x2*)(rowp + h * 192 + 160 + i0) = b; } } }
.LBB0_1804:
	s_andn2_b64 vcc, exec, s[12:13]
	s_cbranch_vccnz .LBB0_1806
	v_mov_b32_e32 v113, v112
	s_ashr_i32 s63, s62, 31
	v_mul_f32_e32 v102, v102, v112
	v_mul_f32_e32 v103, v103, v113
	v_mul_f32_e32 v106, v98, v112
	v_mul_f32_e32 v107, v99, v113
	v_cvt_pk_bf16_f32 v98, v100, v101
	v_cvt_pk_bf16_f32 v99, v102, v103
	v_cvt_pk_bf16_f32 v100, v96, v97
	v_lshl_add_u64 v[96:97], s[62:63], 1, v[104:105]
	v_cvt_pk_bf16_f32 v101, v106, v107
	global_store_dwordx4 v[96:97], v[98:101], off offset:256
.LBB0_1806:
	v_or_b32_e32 v96, 32, v154
	v_ashrrev_i32_e32 v97, 31, v96
	v_lshl_add_u64 v[98:99], v[96:97], 4, s[20:21]
	global_load_dwordx4 v[100:103], v[98:99], off
	v_mov_b64_e32 v[98:99], s[18:19]
	v_mad_i64_i32 v[98:99], s[0:1], v96, s91, v[98:99]
	v_lshlrev_b32_e32 v96, 5, v96
	v_and_b32_e32 v96, 0x1fde0, v96
	s_mov_b64 s[64:65], -1
	s_and_b64 vcc, exec, s[8:9]
	s_waitcnt vmcnt(0)
	v_mov_b32_e32 v104, v101
	v_mov_b32_e32 v105, v102
	v_mov_b32_e32 v101, v103
	v_add_f32_e32 v100, v104, v100
	v_add_f32_e32 v101, v105, v101
	s_nop 0
	v_add_f32_e32 v97, v100, v101
	v_fmamk_f32 v97, v97, 0x3b800000, v167
	v_mul_f32_e32 v100, 0x4b800000, v97
	v_cmp_gt_f32_e64 s[12:13], s90, v97
	s_nop 1
	v_cndmask_b32_e64 v97, v97, v100, s[12:13]
	v_rsq_f32_e32 v97, v97
	v_lshlrev_b32_e32 v100, 2, v96
	v_mul_f32_e32 v96, 0x45800000, v97
	v_cndmask_b32_e64 v96, v97, v96, s[12:13]
	v_mov_b32_e32 v97, v96
	v_mul_f32_e32 v102, v92, v96
	v_mul_f32_e32 v103, v93, v97
	v_mul_f32_e32 v92, v88, v96
	v_mul_f32_e32 v93, v89, v97
	s_cbranch_vccnz .LBB0_1808
	v_mov_b32_e32 v101, v137
	v_lshl_add_u64 v[88:89], v[144:145], 0, v[100:101]
	global_load_dwordx4 v[104:107], v[88:89], off
	v_lshl_add_u64 v[88:89], v[142:143], 0, v[100:101]
	global_load_dwordx4 v[108:111], v[88:89], off
	s_sub_i32 s0, s62, s95
	v_mov_b32_e32 v88, v96
	v_mov_b32_e32 v89, v96
	v_mul_f32_e32 v112, v94, v88
	v_mul_f32_e32 v113, v95, v89
	v_mul_f32_e32 v88, v90, v88
	v_mul_f32_e32 v89, v91, v89
	s_ashr_i32 s1, s0, 31
	v_mov_b32_e32 v153, v137
	v_lshl_add_u64 v[114:115], s[0:1], 1, v[98:99]
	v_lshl_add_u64 v[114:115], v[114:115], 0, v[152:153]
	s_mov_b64 s[64:65], 0
	s_waitcnt vmcnt(0)
	v_mul_f32_e32 v116, v88, v106
	v_mul_f32_e32 v117, v89, v107
	v_mul_f32_e32 v118, v92, v104
	v_mul_f32_e32 v119, v93, v105
	v_mul_f32_e32 v106, v112, v106
	v_mul_f32_e32 v107, v113, v107
	v_mul_f32_e32 v104, v102, v104
	v_mul_f32_e32 v105, v103, v105
	v_pk_fma_f32 v[112:113], v[112:113], v[110:111], v[116:117] neg_lo:[0,0,1] neg_hi:[0,0,1]
	v_pk_fma_f32 v[116:117], v[102:103], v[108:109], v[118:119] neg_lo:[0,0,1] neg_hi:[0,0,1]
	v_fma_f32 v88, v88, v110, v106
	v_fma_f32 v89, v89, v111, v107
	v_fma_f32 v104, v92, v108, v104
	v_fma_f32 v105, v93, v109, v105
	v_cvt_pk_bf16_f32 v106, v116, v117
	v_cvt_pk_bf16_f32 v107, v112, v113
	s_nop 0
	v_cvt_pk_bf16_f32 v104, v104, v105
	v_cvt_pk_bf16_f32 v105, v88, v89
	global_store_dwordx2 v[114:115], v[106:107], off offset:256
	global_store_dwordx2 v[114:115], v[104:105], off offset:320
.LBB0_1808:
	s_andn2_b64 vcc, exec, s[64:65]
	v_lshl_add_u64 v[88:89], v[98:99], 0, v[136:137]
	s_cbranch_vccnz .LBB0_1810
	v_mov_b32_e32 v104, v96
	v_mov_b32_e32 v105, v96
	v_mul_f32_e32 v94, v94, v104
	v_mul_f32_e32 v95, v95, v105
	s_ashr_i32 s63, s62, 31
	v_mul_f32_e32 v104, v90, v104
	v_mul_f32_e32 v105, v91, v105
	v_cvt_pk_bf16_f32 v90, v102, v103
	v_cvt_pk_bf16_f32 v91, v94, v95
	v_lshl_add_u64 v[94:95], s[62:63], 1, v[88:89]
	v_cvt_pk_bf16_f32 v92, v92, v93
	v_cvt_pk_bf16_f32 v93, v104, v105
	global_store_dwordx4 v[94:95], v[90:93], off
.LBB0_1810:
	s_mov_b64 s[12:13], -1
	s_and_b64 vcc, exec, s[6:7]
	v_mul_f32_e32 v84, v84, v96
	v_mul_f32_e32 v85, v85, v97
	v_mul_f32_e32 v80, v80, v96
	v_mul_f32_e32 v81, v81, v97
	s_cbranch_vccnz .LBB0_1812
	v_mov_b32_e32 v101, v137
	v_lshl_add_u64 v[90:91], v[144:145], 0, v[100:101]
	global_load_dwordx4 v[90:93], v[90:91], off
	v_lshl_add_u64 v[94:95], v[142:143], 0, v[100:101]
	global_load_dwordx4 v[100:103], v[94:95], off
	s_ashr_i32 s1, s94, 31
	s_ashr_i32 s2, s62, 31
	v_mov_b32_e32 v97, v96
	s_sub_u32 s0, s62, s94
	v_mul_f32_e32 v104, v82, v96
	v_mul_f32_e32 v105, v83, v97
	s_subb_u32 s1, s2, s1
	v_mov_b32_e32 v153, v137
	v_mul_f32_e32 v94, v86, v96
	v_mul_f32_e32 v95, v87, v97
	v_lshl_add_u64 v[98:99], s[0:1], 1, v[98:99]
	v_lshl_add_u64 v[98:99], v[98:99], 0, v[152:153]
	s_mov_b64 s[12:13], 0
	s_waitcnt vmcnt(0)
	v_mul_f32_e32 v106, v104, v92
	v_mul_f32_e32 v107, v105, v93
	v_mul_f32_e32 v108, v80, v90
	v_mul_f32_e32 v109, v81, v91
	v_mul_f32_e32 v90, v84, v90
	v_mul_f32_e32 v91, v85, v91
	v_mul_f32_e32 v92, v94, v92
	v_mul_f32_e32 v93, v95, v93
	v_pk_fma_f32 v[94:95], v[94:95], v[102:103], v[106:107] neg_lo:[0,0,1] neg_hi:[0,0,1]
	v_pk_fma_f32 v[106:107], v[84:85], v[100:101], v[108:109] neg_lo:[0,0,1] neg_hi:[0,0,1]
	v_fma_f32 v90, v80, v100, v90
	v_fma_f32 v91, v81, v101, v91
	v_cvt_pk_bf16_f32 v100, v106, v107
	v_cvt_pk_bf16_f32 v101, v94, v95
	v_fma_f32 v92, v104, v102, v92
	v_fma_f32 v93, v105, v103, v93
	v_cvt_pk_bf16_f32 v90, v90, v91
	s_nop 0
	v_cvt_pk_bf16_f32 v91, v92, v93
	global_store_dwordx2 v[98:99], v[100:101], off offset:512
	global_store_dwordx2 v[98:99], v[90:91], off offset:576
.LBB0_1812:
	s_andn2_b64 vcc, exec, s[12:13]
	s_cbranch_vccnz .LBB0_1814
	v_mov_b32_e32 v97, v96
	s_ashr_i32 s63, s62, 31
	v_mul_f32_e32 v86, v86, v96
	v_mul_f32_e32 v87, v87, v97
	v_mul_f32_e32 v90, v82, v96
	v_mul_f32_e32 v91, v83, v97
	v_cvt_pk_bf16_f32 v82, v84, v85
	v_cvt_pk_bf16_f32 v83, v86, v87
	v_cvt_pk_bf16_f32 v84, v80, v81
	v_lshl_add_u64 v[80:81], s[62:63], 1, v[88:89]
	v_cvt_pk_bf16_f32 v85, v90, v91
	global_store_dwordx4 v[80:81], v[82:85], off offset:256
; __device__ __forceinline__ unsigned cvt_pk_bf16(float lo, float hi) { unsigned r; asm volatile("v_cvt_pk_bf16_f32 %0, %1, %2" : "=v"(r) : "v"(lo), "v"(hi)); return r; }
;     DI void operator()(const f32x4 (&acc)[2][2][4][2], const Unit& u, int wr, int wc, int fr, int fq) const {
;     ...
;             for (int m = 0; m < 4; ++m) { const int row = row0 + ai * 128 + m * 16; const f32x4 q4 = *(const f32x4*)(ssq4 + (size_t)row * 4);
;                 const float s = rsqrtf(((q4[0] + q4[1]) + (q4[2] + q4[3])) * (1.f / 256.f) + EPS); bf16_t* rowp = Q + (size_t)row * 768;
; #pragma unroll
;                 for (int bj = 0; bj < 2; ++bj) { const int c0 = u.pn * 256 + bj * 128 + wc * 32, h = c0 / 192, d0 = c0 - h * 192;
;                     if (d0 < 128) { const f32x4 v0 = acc[ai][bj][m][0] * s, v1 = acc[ai][bj][m][1] * s; u32x4 w;
;                         w.x = cvt_pk_bf16(v0[0], v0[1]); w.y = cvt_pk_bf16(v0[2], v0[3]); w.z = cvt_pk_bf16(v1[0], v1[1]); w.w = cvt_pk_bf16(v1[2], v1[3]);
;                         *(u32x4*)(rowp + c0 + 8 * fq) = w; }
;                     else { const int i0 = 16 * (wc & 1) + 4 * fq, pos = row & (SEQ - 1);
;                         const f32x4 c = *(const f32x4*)(cs + pos * 32 + i0), sv = *(const f32x4*)(sn + pos * 32 + i0);
;                         const f32x4 x1 = acc[ai][bj][m][0] * s, x2 = acc[ai][bj][m][1] * s; const f32x4 o1 = x1 * c - x2 * sv, o2 = x2 * c + x1 * sv; u32x2 a, b;
;                         a.x = cvt_pk_bf16(o1[0], o1[1]); a.y = cvt_pk_bf16(o1[2], o1[3]); b.x = cvt_pk_bf16(o2[0], o2[1]); b.y = cvt_pk_bf16(o2[2], o2[3]);
;                         *(u32x2*)(rowp + h * 192 + 128 + i0) = a; *(u32x2*)(rowp + h * 192 + 160 + i0) = b; } } }
.LBB0_1814:
	v_or_b32_e32 v80, 48, v154
	v_ashrrev_i32_e32 v81, 31, v80
	v_lshl_add_u64 v[82:83], v[80:81], 4, s[20:21]
	global_load_dwordx4 v[84:87], v[82:83], off
	v_mov_b64_e32 v[82:83], s[18:19]
	v_mad_i64_i32 v[82:83], s[0:1], v80, s91, v[82:83]
	v_lshlrev_b32_e32 v80, 5, v80
	v_and_b32_e32 v80, 0x1ffe0, v80
	s_mov_b64 s[64:65], -1
	s_and_b64 vcc, exec, s[8:9]
	s_waitcnt vmcnt(0)
	v_mov_b32_e32 v88, v85
	v_mov_b32_e32 v89, v86
	v_mov_b32_e32 v85, v87
	v_add_f32_e32 v84, v88, v84
	v_add_f32_e32 v85, v89, v85
	s_nop 0
	v_add_f32_e32 v81, v84, v85
	v_fmamk_f32 v81, v81, 0x3b800000, v167
	v_mul_f32_e32 v84, 0x4b800000, v81
	v_cmp_gt_f32_e64 s[12:13], s90, v81
	s_nop 1
	v_cndmask_b32_e64 v81, v81, v84, s[12:13]
	v_rsq_f32_e32 v81, v81
	v_lshlrev_b32_e32 v84, 2, v80
	v_mul_f32_e32 v80, 0x45800000, v81
	v_cndmask_b32_e64 v80, v81, v80, s[12:13]
	v_mov_b32_e32 v81, v80
	v_mul_f32_e32 v86, v76, v80
	v_mul_f32_e32 v87, v77, v81
	v_mul_f32_e32 v76, v72, v80
	v_mul_f32_e32 v77, v73, v81
	s_cbranch_vccnz .LBB0_1816
	v_mov_b32_e32 v85, v137
	v_lshl_add_u64 v[72:73], v[144:145], 0, v[84:85]
	global_load_dwordx4 v[88:91], v[72:73], off
	v_lshl_add_u64 v[72:73], v[142:143], 0, v[84:85]
	global_load_dwordx4 v[92:95], v[72:73], off
	s_sub_i32 s0, s62, s95
	v_mov_b32_e32 v72, v80
	v_mov_b32_e32 v73, v80
	v_mul_f32_e32 v96, v78, v72
	v_mul_f32_e32 v97, v79, v73
	v_mul_f32_e32 v72, v74, v72
	v_mul_f32_e32 v73, v75, v73
	s_ashr_i32 s1, s0, 31
	v_mov_b32_e32 v153, v137
	v_lshl_add_u64 v[98:99], s[0:1], 1, v[82:83]
	v_lshl_add_u64 v[98:99], v[98:99], 0, v[152:153]
	s_mov_b64 s[64:65], 0
	s_waitcnt vmcnt(0)
	v_mul_f32_e32 v100, v72, v90
	v_mul_f32_e32 v101, v73, v91
	v_mul_f32_e32 v102, v76, v88
	v_mul_f32_e32 v103, v77, v89
	v_mul_f32_e32 v90, v96, v90
	v_mul_f32_e32 v91, v97, v91
	v_mul_f32_e32 v88, v86, v88
	v_mul_f32_e32 v89, v87, v89
	v_pk_fma_f32 v[96:97], v[96:97], v[94:95], v[100:101] neg_lo:[0,0,1] neg_hi:[0,0,1]
	v_pk_fma_f32 v[100:101], v[86:87], v[92:93], v[102:103] neg_lo:[0,0,1] neg_hi:[0,0,1]
	v_fma_f32 v72, v72, v94, v90
	v_fma_f32 v73, v73, v95, v91
	v_fma_f32 v88, v76, v92, v88
	v_fma_f32 v89, v77, v93, v89
	v_cvt_pk_bf16_f32 v90, v100, v101
	v_cvt_pk_bf16_f32 v91, v96, v97
	s_nop 0
	v_cvt_pk_bf16_f32 v88, v88, v89
	v_cvt_pk_bf16_f32 v89, v72, v73
	global_store_dwordx2 v[98:99], v[90:91], off offset:256
	global_store_dwordx2 v[98:99], v[88:89], off offset:320
.LBB0_1816:
	s_andn2_b64 vcc, exec, s[64:65]
	v_lshl_add_u64 v[72:73], v[82:83], 0, v[136:137]
	s_cbranch_vccnz .LBB0_1818
	v_mov_b32_e32 v88, v80
	v_mov_b32_e32 v89, v80
	v_mul_f32_e32 v78, v78, v88
	v_mul_f32_e32 v79, v79, v89
	s_ashr_i32 s63, s62, 31
	v_mul_f32_e32 v88, v74, v88
	v_mul_f32_e32 v89, v75, v89
	v_cvt_pk_bf16_f32 v74, v86, v87
	v_cvt_pk_bf16_f32 v75, v78, v79
	v_lshl_add_u64 v[78:79], s[62:63], 1, v[72:73]
	v_cvt_pk_bf16_f32 v76, v76, v77
	v_cvt_pk_bf16_f32 v77, v88, v89
	global_store_dwordx4 v[78:79], v[74:77], off
.LBB0_1818:
	s_mov_b64 s[12:13], -1
	s_and_b64 vcc, exec, s[6:7]
	v_mul_f32_e32 v68, v68, v80
	v_mul_f32_e32 v69, v69, v81
	v_mul_f32_e32 v64, v64, v80
	v_mul_f32_e32 v65, v65, v81
	s_cbranch_vccnz .LBB0_1820
	v_mov_b32_e32 v85, v137
	v_lshl_add_u64 v[74:75], v[144:145], 0, v[84:85]
	global_load_dwordx4 v[74:77], v[74:75], off
	v_lshl_add_u64 v[78:79], v[142:143], 0, v[84:85]
	global_load_dwordx4 v[84:87], v[78:79], off
	s_ashr_i32 s1, s94, 31
	s_ashr_i32 s2, s62, 31
	v_mov_b32_e32 v81, v80
	s_sub_u32 s0, s62, s94
	v_mul_f32_e32 v88, v66, v80
	v_mul_f32_e32 v89, v67, v81
	s_subb_u32 s1, s2, s1
	v_mov_b32_e32 v153, v137
	v_mul_f32_e32 v78, v70, v80
	v_mul_f32_e32 v79, v71, v81
	v_lshl_add_u64 v[82:83], s[0:1], 1, v[82:83]
	v_lshl_add_u64 v[82:83], v[82:83], 0, v[152:153]
	s_mov_b64 s[12:13], 0
	s_waitcnt vmcnt(0)
	v_mul_f32_e32 v90, v88, v76
	v_mul_f32_e32 v91, v89, v77
	v_mul_f32_e32 v92, v64, v74
	v_mul_f32_e32 v93, v65, v75
	v_mul_f32_e32 v74, v68, v74
	v_mul_f32_e32 v75, v69, v75
	v_mul_f32_e32 v76, v78, v76
	v_mul_f32_e32 v77, v79, v77
	v_pk_fma_f32 v[78:79], v[78:79], v[86:87], v[90:91] neg_lo:[0,0,1] neg_hi:[0,0,1]
	v_pk_fma_f32 v[90:91], v[68:69], v[84:85], v[92:93] neg_lo:[0,0,1] neg_hi:[0,0,1]
	v_fma_f32 v74, v64, v84, v74
	v_fma_f32 v75, v65, v85, v75
	v_cvt_pk_bf16_f32 v84, v90, v91
	v_cvt_pk_bf16_f32 v85, v78, v79
	v_fma_f32 v76, v88, v86, v76
	v_fma_f32 v77, v89, v87, v77
	v_cvt_pk_bf16_f32 v74, v74, v75
	s_nop 0
	v_cvt_pk_bf16_f32 v75, v76, v77
	global_store_dwordx2 v[82:83], v[84:85], off offset:512
	global_store_dwordx2 v[82:83], v[74:75], off offset:576
.LBB0_1820:
	s_andn2_b64 vcc, exec, s[12:13]
	s_cbranch_vccnz .LBB0_1822
	v_mov_b32_e32 v81, v80
	s_ashr_i32 s63, s62, 31
	v_mul_f32_e32 v70, v70, v80
	v_mul_f32_e32 v71, v71, v81
	v_mul_f32_e32 v74, v66, v80
	v_mul_f32_e32 v75, v67, v81
	v_cvt_pk_bf16_f32 v66, v68, v69
	v_cvt_pk_bf16_f32 v67, v70, v71
	v_cvt_pk_bf16_f32 v68, v64, v65
	v_lshl_add_u64 v[64:65], s[62:63], 1, v[72:73]
	v_cvt_pk_bf16_f32 v69, v74, v75
	global_store_dwordx4 v[64:65], v[66:69], off offset:256
; __device__ __forceinline__ unsigned cvt_pk_bf16(float lo, float hi) { unsigned r; asm volatile("v_cvt_pk_bf16_f32 %0, %1, %2" : "=v"(r) : "v"(lo), "v"(hi)); return r; }
;     DI void operator()(const f32x4 (&acc)[2][2][4][2], const Unit& u, int wr, int wc, int fr, int fq) const {
;     ...
;             for (int m = 0; m < 4; ++m) { const int row = row0 + ai * 128 + m * 16; const f32x4 q4 = *(const f32x4*)(ssq4 + (size_t)row * 4);
;                 const float s = rsqrtf(((q4[0] + q4[1]) + (q4[2] + q4[3])) * (1.f / 256.f) + EPS); bf16_t* rowp = Q + (size_t)row * 768;
; #pragma unroll
;                 for (int bj = 0; bj < 2; ++bj) { const int c0 = u.pn * 256 + bj * 128 + wc * 32, h = c0 / 192, d0 = c0 - h * 192;
;                     if (d0 < 128) { const f32x4 v0 = acc[ai][bj][m][0] * s, v1 = acc[ai][bj][m][1] * s; u32x4 w;
;                         w.x = cvt_pk_bf16(v0[0], v0[1]); w.y = cvt_pk_bf16(v0[2], v0[3]); w.z = cvt_pk_bf16(v1[0], v1[1]); w.w = cvt_pk_bf16(v1[2], v1[3]);
;                         *(u32x4*)(rowp + c0 + 8 * fq) = w; }
;                     else { const int i0 = 16 * (wc & 1) + 4 * fq, pos = row & (SEQ - 1);
;                         const f32x4 c = *(const f32x4*)(cs + pos * 32 + i0), sv = *(const f32x4*)(sn + pos * 32 + i0);
;                         const f32x4 x1 = acc[ai][bj][m][0] * s, x2 = acc[ai][bj][m][1] * s; const f32x4 o1 = x1 * c - x2 * sv, o2 = x2 * c + x1 * sv; u32x2 a, b;
;                         a.x = cvt_pk_bf16(o1[0], o1[1]); a.y = cvt_pk_bf16(o1[2], o1[3]); b.x = cvt_pk_bf16(o2[0], o2[1]); b.y = cvt_pk_bf16(o2[2], o2[3]);
;                         *(u32x2*)(rowp + h * 192 + 128 + i0) = a; *(u32x2*)(rowp + h * 192 + 160 + i0) = b; } } }
.LBB0_1822:
	v_add_u32_e32 v64, 0x80, v154
	v_ashrrev_i32_e32 v65, 31, v64
	v_lshl_add_u64 v[66:67], v[64:65], 4, s[20:21]
	global_load_dwordx4 v[68:71], v[66:67], off
	v_mov_b64_e32 v[66:67], s[18:19]
	v_mad_i64_i32 v[66:67], s[0:1], v64, s91, v[66:67]
	v_lshlrev_b32_e32 v64, 5, v64
	v_and_b32_e32 v64, 0x1f9e0, v64
	s_mov_b64 s[64:65], -1
	s_and_b64 vcc, exec, s[8:9]
	s_waitcnt vmcnt(0)
	v_mov_b32_e32 v72, v69
	v_mov_b32_e32 v73, v70
	v_mov_b32_e32 v69, v71
	v_add_f32_e32 v68, v72, v68
	v_add_f32_e32 v69, v73, v69
	s_nop 0
	v_add_f32_e32 v65, v68, v69
	v_fmamk_f32 v65, v65, 0x3b800000, v167
	v_mul_f32_e32 v68, 0x4b800000, v65
	v_cmp_gt_f32_e64 s[12:13], s90, v65
	s_nop 1
	v_cndmask_b32_e64 v65, v65, v68, s[12:13]
	v_rsq_f32_e32 v65, v65
	v_lshlrev_b32_e32 v68, 2, v64
	v_mul_f32_e32 v64, 0x45800000, v65
	v_cndmask_b32_e64 v64, v65, v64, s[12:13]
	v_mov_b32_e32 v65, v64
	v_mul_f32_e32 v70, v60, v64
	v_mul_f32_e32 v71, v61, v65
	v_mul_f32_e32 v60, v56, v64
	v_mul_f32_e32 v61, v57, v65
	s_cbranch_vccnz .LBB0_1824
	v_mov_b32_e32 v69, v137
	v_lshl_add_u64 v[56:57], v[144:145], 0, v[68:69]
	global_load_dwordx4 v[72:75], v[56:57], off
	v_lshl_add_u64 v[56:57], v[142:143], 0, v[68:69]
	global_load_dwordx4 v[76:79], v[56:57], off
	s_sub_i32 s0, s62, s95
	v_mov_b32_e32 v56, v64
	v_mov_b32_e32 v57, v64
	v_mul_f32_e32 v80, v62, v56
	v_mul_f32_e32 v81, v63, v57
	v_mul_f32_e32 v56, v58, v56
	v_mul_f32_e32 v57, v59, v57
	s_ashr_i32 s1, s0, 31
	v_mov_b32_e32 v153, v137
	v_lshl_add_u64 v[82:83], s[0:1], 1, v[66:67]
	v_lshl_add_u64 v[82:83], v[82:83], 0, v[152:153]
	s_mov_b64 s[64:65], 0
	s_waitcnt vmcnt(0)
	v_mul_f32_e32 v84, v56, v74
	v_mul_f32_e32 v85, v57, v75
	v_mul_f32_e32 v86, v60, v72
	v_mul_f32_e32 v87, v61, v73
	v_mul_f32_e32 v74, v80, v74
	v_mul_f32_e32 v75, v81, v75
	v_mul_f32_e32 v72, v70, v72
	v_mul_f32_e32 v73, v71, v73
	v_pk_fma_f32 v[80:81], v[80:81], v[78:79], v[84:85] neg_lo:[0,0,1] neg_hi:[0,0,1]
	v_pk_fma_f32 v[84:85], v[70:71], v[76:77], v[86:87] neg_lo:[0,0,1] neg_hi:[0,0,1]
	v_fma_f32 v56, v56, v78, v74
	v_fma_f32 v57, v57, v79, v75
	v_fma_f32 v72, v60, v76, v72
	v_fma_f32 v73, v61, v77, v73
	v_cvt_pk_bf16_f32 v74, v84, v85
	v_cvt_pk_bf16_f32 v75, v80, v81
	s_nop 0
	v_cvt_pk_bf16_f32 v72, v72, v73
	v_cvt_pk_bf16_f32 v73, v56, v57
	global_store_dwordx2 v[82:83], v[74:75], off offset:256
	global_store_dwordx2 v[82:83], v[72:73], off offset:320
.LBB0_1824:
	s_andn2_b64 vcc, exec, s[64:65]
	v_lshl_add_u64 v[56:57], v[66:67], 0, v[136:137]
	s_cbranch_vccnz .LBB0_1826
	v_mov_b32_e32 v72, v64
	v_mov_b32_e32 v73, v64
	v_mul_f32_e32 v62, v62, v72
	v_mul_f32_e32 v63, v63, v73
	s_ashr_i32 s63, s62, 31
	v_mul_f32_e32 v72, v58, v72
	v_mul_f32_e32 v73, v59, v73
	v_cvt_pk_bf16_f32 v58, v70, v71
	v_cvt_pk_bf16_f32 v59, v62, v63
	v_lshl_add_u64 v[62:63], s[62:63], 1, v[56:57]
	v_cvt_pk_bf16_f32 v60, v60, v61
	v_cvt_pk_bf16_f32 v61, v72, v73
	global_store_dwordx4 v[62:63], v[58:61], off
.LBB0_1826:
	s_mov_b64 s[12:13], -1
	s_and_b64 vcc, exec, s[6:7]
	v_mul_f32_e32 v52, v52, v64
	v_mul_f32_e32 v53, v53, v65
	v_mul_f32_e32 v48, v48, v64
	v_mul_f32_e32 v49, v49, v65
	s_cbranch_vccnz .LBB0_1828
	v_mov_b32_e32 v69, v137
	v_lshl_add_u64 v[58:59], v[144:145], 0, v[68:69]
	global_load_dwordx4 v[58:61], v[58:59], off
	v_lshl_add_u64 v[62:63], v[142:143], 0, v[68:69]
	global_load_dwordx4 v[68:71], v[62:63], off
	s_ashr_i32 s1, s94, 31
	s_ashr_i32 s2, s62, 31
	v_mov_b32_e32 v65, v64
	s_sub_u32 s0, s62, s94
	v_mul_f32_e32 v72, v50, v64
	v_mul_f32_e32 v73, v51, v65
	s_subb_u32 s1, s2, s1
	v_mov_b32_e32 v153, v137
	v_mul_f32_e32 v62, v54, v64
	v_mul_f32_e32 v63, v55, v65
	v_lshl_add_u64 v[66:67], s[0:1], 1, v[66:67]
	v_lshl_add_u64 v[66:67], v[66:67], 0, v[152:153]
	s_mov_b64 s[12:13], 0
	s_waitcnt vmcnt(0)
	v_mul_f32_e32 v74, v72, v60
	v_mul_f32_e32 v75, v73, v61
	v_mul_f32_e32 v76, v48, v58
	v_mul_f32_e32 v77, v49, v59
	v_mul_f32_e32 v58, v52, v58
	v_mul_f32_e32 v59, v53, v59
	v_mul_f32_e32 v60, v62, v60
	v_mul_f32_e32 v61, v63, v61
	v_pk_fma_f32 v[62:63], v[62:63], v[70:71], v[74:75] neg_lo:[0,0,1] neg_hi:[0,0,1]
	v_pk_fma_f32 v[74:75], v[52:53], v[68:69], v[76:77] neg_lo:[0,0,1] neg_hi:[0,0,1]
	v_fma_f32 v58, v48, v68, v58
	v_fma_f32 v59, v49, v69, v59
	v_cvt_pk_bf16_f32 v68, v74, v75
	v_cvt_pk_bf16_f32 v69, v62, v63
	v_fma_f32 v60, v72, v70, v60
	v_fma_f32 v61, v73, v71, v61
	v_cvt_pk_bf16_f32 v58, v58, v59
	s_nop 0
	v_cvt_pk_bf16_f32 v59, v60, v61
	global_store_dwordx2 v[66:67], v[68:69], off offset:512
	global_store_dwordx2 v[66:67], v[58:59], off offset:576
.LBB0_1828:
	s_andn2_b64 vcc, exec, s[12:13]
	s_cbranch_vccnz .LBB0_1830
	v_mov_b32_e32 v65, v64
	s_ashr_i32 s63, s62, 31
	v_mul_f32_e32 v54, v54, v64
	v_mul_f32_e32 v55, v55, v65
	v_mul_f32_e32 v58, v50, v64
	v_mul_f32_e32 v59, v51, v65
	v_cvt_pk_bf16_f32 v50, v52, v53
	v_cvt_pk_bf16_f32 v51, v54, v55
	v_cvt_pk_bf16_f32 v52, v48, v49
	v_lshl_add_u64 v[48:49], s[62:63], 1, v[56:57]
	v_cvt_pk_bf16_f32 v53, v58, v59
	global_store_dwordx4 v[48:49], v[50:53], off offset:256
; __device__ __forceinline__ unsigned cvt_pk_bf16(float lo, float hi) { unsigned r; asm volatile("v_cvt_pk_bf16_f32 %0, %1, %2" : "=v"(r) : "v"(lo), "v"(hi)); return r; }
;     DI void operator()(const f32x4 (&acc)[2][2][4][2], const Unit& u, int wr, int wc, int fr, int fq) const {
;     ...
;             for (int m = 0; m < 4; ++m) { const int row = row0 + ai * 128 + m * 16; const f32x4 q4 = *(const f32x4*)(ssq4 + (size_t)row * 4);
;                 const float s = rsqrtf(((q4[0] + q4[1]) + (q4[2] + q4[3])) * (1.f / 256.f) + EPS); bf16_t* rowp = Q + (size_t)row * 768;
; #pragma unroll
;                 for (int bj = 0; bj < 2; ++bj) { const int c0 = u.pn * 256 + bj * 128 + wc * 32, h = c0 / 192, d0 = c0 - h * 192;
;                     if (d0 < 128) { const f32x4 v0 = acc[ai][bj][m][0] * s, v1 = acc[ai][bj][m][1] * s; u32x4 w;
;                         w.x = cvt_pk_bf16(v0[0], v0[1]); w.y = cvt_pk_bf16(v0[2], v0[3]); w.z = cvt_pk_bf16(v1[0], v1[1]); w.w = cvt_pk_bf16(v1[2], v1[3]);
;                         *(u32x4*)(rowp + c0 + 8 * fq) = w; }
;                     else { const int i0 = 16 * (wc & 1) + 4 * fq, pos = row & (SEQ - 1);
;                         const f32x4 c = *(const f32x4*)(cs + pos * 32 + i0), sv = *(const f32x4*)(sn + pos * 32 + i0);
;                         const f32x4 x1 = acc[ai][bj][m][0] * s, x2 = acc[ai][bj][m][1] * s; const f32x4 o1 = x1 * c - x2 * sv, o2 = x2 * c + x1 * sv; u32x2 a, b;
;                         a.x = cvt_pk_bf16(o1[0], o1[1]); a.y = cvt_pk_bf16(o1[2], o1[3]); b.x = cvt_pk_bf16(o2[0], o2[1]); b.y = cvt_pk_bf16(o2[2], o2[3]);
;                         *(u32x2*)(rowp + h * 192 + 128 + i0) = a; *(u32x2*)(rowp + h * 192 + 160 + i0) = b; } } }
.LBB0_1830:
	v_add_u32_e32 v48, 0x90, v154
	v_ashrrev_i32_e32 v49, 31, v48
	v_lshl_add_u64 v[50:51], v[48:49], 4, s[20:21]
	global_load_dwordx4 v[52:55], v[50:51], off
	v_mov_b64_e32 v[50:51], s[18:19]
	v_mad_i64_i32 v[50:51], s[0:1], v48, s91, v[50:51]
	v_lshlrev_b32_e32 v48, 5, v48
	v_and_b32_e32 v48, 0x1fbe0, v48
	s_mov_b64 s[64:65], -1
	s_and_b64 vcc, exec, s[8:9]
	s_waitcnt vmcnt(0)
	v_mov_b32_e32 v56, v53
	v_mov_b32_e32 v57, v54
	v_mov_b32_e32 v53, v55
	v_add_f32_e32 v52, v56, v52
	v_add_f32_e32 v53, v57, v53
	s_nop 0
	v_add_f32_e32 v49, v52, v53
	v_fmamk_f32 v49, v49, 0x3b800000, v167
	v_mul_f32_e32 v52, 0x4b800000, v49
	v_cmp_gt_f32_e64 s[12:13], s90, v49
	s_nop 1
	v_cndmask_b32_e64 v49, v49, v52, s[12:13]
	v_rsq_f32_e32 v49, v49
	v_lshlrev_b32_e32 v52, 2, v48
	v_mul_f32_e32 v48, 0x45800000, v49
	v_cndmask_b32_e64 v48, v49, v48, s[12:13]
	v_mov_b32_e32 v49, v48
	v_mul_f32_e32 v54, v44, v48
	v_mul_f32_e32 v55, v45, v49
	v_mul_f32_e32 v44, v40, v48
	v_mul_f32_e32 v45, v41, v49
	s_cbranch_vccnz .LBB0_1832
	v_mov_b32_e32 v53, v137
	v_lshl_add_u64 v[40:41], v[144:145], 0, v[52:53]
	global_load_dwordx4 v[56:59], v[40:41], off
	v_lshl_add_u64 v[40:41], v[142:143], 0, v[52:53]
	global_load_dwordx4 v[60:63], v[40:41], off
	s_sub_i32 s0, s62, s95
	v_mov_b32_e32 v40, v48
	v_mov_b32_e32 v41, v48
	v_mul_f32_e32 v64, v46, v40
	v_mul_f32_e32 v65, v47, v41
	v_mul_f32_e32 v40, v42, v40
	v_mul_f32_e32 v41, v43, v41
	s_ashr_i32 s1, s0, 31
	v_mov_b32_e32 v153, v137
	v_lshl_add_u64 v[66:67], s[0:1], 1, v[50:51]
	v_lshl_add_u64 v[66:67], v[66:67], 0, v[152:153]
	s_mov_b64 s[64:65], 0
	s_waitcnt vmcnt(0)
	v_mul_f32_e32 v68, v40, v58
	v_mul_f32_e32 v69, v41, v59
	v_mul_f32_e32 v70, v44, v56
	v_mul_f32_e32 v71, v45, v57
	v_mul_f32_e32 v58, v64, v58
	v_mul_f32_e32 v59, v65, v59
	v_mul_f32_e32 v56, v54, v56
	v_mul_f32_e32 v57, v55, v57
	v_pk_fma_f32 v[64:65], v[64:65], v[62:63], v[68:69] neg_lo:[0,0,1] neg_hi:[0,0,1]
	v_pk_fma_f32 v[68:69], v[54:55], v[60:61], v[70:71] neg_lo:[0,0,1] neg_hi:[0,0,1]
	v_fma_f32 v40, v40, v62, v58
	v_fma_f32 v41, v41, v63, v59
	v_fma_f32 v56, v44, v60, v56
	v_fma_f32 v57, v45, v61, v57
	v_cvt_pk_bf16_f32 v58, v68, v69
	v_cvt_pk_bf16_f32 v59, v64, v65
	s_nop 0
	v_cvt_pk_bf16_f32 v56, v56, v57
	v_cvt_pk_bf16_f32 v57, v40, v41
	global_store_dwordx2 v[66:67], v[58:59], off offset:256
	global_store_dwordx2 v[66:67], v[56:57], off offset:320
.LBB0_1832:
	s_andn2_b64 vcc, exec, s[64:65]
	v_lshl_add_u64 v[40:41], v[50:51], 0, v[136:137]
	s_cbranch_vccnz .LBB0_1834
	v_mov_b32_e32 v56, v48
	v_mov_b32_e32 v57, v48
	v_mul_f32_e32 v46, v46, v56
	v_mul_f32_e32 v47, v47, v57
	s_ashr_i32 s63, s62, 31
	v_mul_f32_e32 v56, v42, v56
	v_mul_f32_e32 v57, v43, v57
	v_cvt_pk_bf16_f32 v42, v54, v55
	v_cvt_pk_bf16_f32 v43, v46, v47
	v_lshl_add_u64 v[46:47], s[62:63], 1, v[40:41]
	v_cvt_pk_bf16_f32 v44, v44, v45
	v_cvt_pk_bf16_f32 v45, v56, v57
	global_store_dwordx4 v[46:47], v[42:45], off
.LBB0_1834:
	s_mov_b64 s[12:13], -1
	s_and_b64 vcc, exec, s[6:7]
	v_mul_f32_e32 v36, v36, v48
	v_mul_f32_e32 v37, v37, v49
	v_mul_f32_e32 v32, v32, v48
	v_mul_f32_e32 v33, v33, v49
	s_cbranch_vccnz .LBB0_1836
	v_mov_b32_e32 v53, v137
	v_lshl_add_u64 v[42:43], v[144:145], 0, v[52:53]
	global_load_dwordx4 v[42:45], v[42:43], off
	v_lshl_add_u64 v[46:47], v[142:143], 0, v[52:53]
	global_load_dwordx4 v[52:55], v[46:47], off
	s_ashr_i32 s1, s94, 31
	s_ashr_i32 s2, s62, 31
	v_mov_b32_e32 v49, v48
	s_sub_u32 s0, s62, s94
	v_mul_f32_e32 v56, v34, v48
	v_mul_f32_e32 v57, v35, v49
	s_subb_u32 s1, s2, s1
	v_mov_b32_e32 v153, v137
	v_mul_f32_e32 v46, v38, v48
	v_mul_f32_e32 v47, v39, v49
	v_lshl_add_u64 v[50:51], s[0:1], 1, v[50:51]
	v_lshl_add_u64 v[50:51], v[50:51], 0, v[152:153]
	s_mov_b64 s[12:13], 0
	s_waitcnt vmcnt(0)
	v_mul_f32_e32 v58, v56, v44
	v_mul_f32_e32 v59, v57, v45
	v_mul_f32_e32 v60, v32, v42
	v_mul_f32_e32 v61, v33, v43
	v_mul_f32_e32 v42, v36, v42
	v_mul_f32_e32 v43, v37, v43
	v_mul_f32_e32 v44, v46, v44
	v_mul_f32_e32 v45, v47, v45
	v_pk_fma_f32 v[46:47], v[46:47], v[54:55], v[58:59] neg_lo:[0,0,1] neg_hi:[0,0,1]
	v_pk_fma_f32 v[58:59], v[36:37], v[52:53], v[60:61] neg_lo:[0,0,1] neg_hi:[0,0,1]
	v_fma_f32 v42, v32, v52, v42
	v_fma_f32 v43, v33, v53, v43
	v_cvt_pk_bf16_f32 v52, v58, v59
	v_cvt_pk_bf16_f32 v53, v46, v47
	v_fma_f32 v44, v56, v54, v44
	v_fma_f32 v45, v57, v55, v45
	v_cvt_pk_bf16_f32 v42, v42, v43
	s_nop 0
	v_cvt_pk_bf16_f32 v43, v44, v45
	global_store_dwordx2 v[50:51], v[52:53], off offset:512
	global_store_dwordx2 v[50:51], v[42:43], off offset:576
.LBB0_1836:
	s_andn2_b64 vcc, exec, s[12:13]
	s_cbranch_vccnz .LBB0_1838
	v_mov_b32_e32 v49, v48
	s_ashr_i32 s63, s62, 31
	v_mul_f32_e32 v38, v38, v48
	v_mul_f32_e32 v39, v39, v49
	v_mul_f32_e32 v42, v34, v48
	v_mul_f32_e32 v43, v35, v49
	v_cvt_pk_bf16_f32 v34, v36, v37
	v_cvt_pk_bf16_f32 v35, v38, v39
	v_cvt_pk_bf16_f32 v36, v32, v33
	v_lshl_add_u64 v[32:33], s[62:63], 1, v[40:41]
	v_cvt_pk_bf16_f32 v37, v42, v43
	global_store_dwordx4 v[32:33], v[34:37], off offset:256
; __device__ __forceinline__ unsigned cvt_pk_bf16(float lo, float hi) { unsigned r; asm volatile("v_cvt_pk_bf16_f32 %0, %1, %2" : "=v"(r) : "v"(lo), "v"(hi)); return r; }
;     DI void operator()(const f32x4 (&acc)[2][2][4][2], const Unit& u, int wr, int wc, int fr, int fq) const {
;     ...
;             for (int m = 0; m < 4; ++m) { const int row = row0 + ai * 128 + m * 16; const f32x4 q4 = *(const f32x4*)(ssq4 + (size_t)row * 4);
;                 const float s = rsqrtf(((q4[0] + q4[1]) + (q4[2] + q4[3])) * (1.f / 256.f) + EPS); bf16_t* rowp = Q + (size_t)row * 768;
; #pragma unroll
;                 for (int bj = 0; bj < 2; ++bj) { const int c0 = u.pn * 256 + bj * 128 + wc * 32, h = c0 / 192, d0 = c0 - h * 192;
;                     if (d0 < 128) { const f32x4 v0 = acc[ai][bj][m][0] * s, v1 = acc[ai][bj][m][1] * s; u32x4 w;
;                         w.x = cvt_pk_bf16(v0[0], v0[1]); w.y = cvt_pk_bf16(v0[2], v0[3]); w.z = cvt_pk_bf16(v1[0], v1[1]); w.w = cvt_pk_bf16(v1[2], v1[3]);
;                         *(u32x4*)(rowp + c0 + 8 * fq) = w; }
;                     else { const int i0 = 16 * (wc & 1) + 4 * fq, pos = row & (SEQ - 1);
;                         const f32x4 c = *(const f32x4*)(cs + pos * 32 + i0), sv = *(const f32x4*)(sn + pos * 32 + i0);
;                         const f32x4 x1 = acc[ai][bj][m][0] * s, x2 = acc[ai][bj][m][1] * s; const f32x4 o1 = x1 * c - x2 * sv, o2 = x2 * c + x1 * sv; u32x2 a, b;
;                         a.x = cvt_pk_bf16(o1[0], o1[1]); a.y = cvt_pk_bf16(o1[2], o1[3]); b.x = cvt_pk_bf16(o2[0], o2[1]); b.y = cvt_pk_bf16(o2[2], o2[3]);
;                         *(u32x2*)(rowp + h * 192 + 128 + i0) = a; *(u32x2*)(rowp + h * 192 + 160 + i0) = b; } } }
.LBB0_1838:
	v_add_u32_e32 v32, 0xa0, v154
	v_ashrrev_i32_e32 v33, 31, v32
	v_lshl_add_u64 v[34:35], v[32:33], 4, s[20:21]
	global_load_dwordx4 v[36:39], v[34:35], off
	v_mov_b64_e32 v[34:35], s[18:19]
	v_mad_i64_i32 v[34:35], s[0:1], v32, s91, v[34:35]
	v_lshlrev_b32_e32 v32, 5, v32
	v_and_b32_e32 v32, 0x1fde0, v32
	s_mov_b64 s[64:65], -1
	s_and_b64 vcc, exec, s[8:9]
	s_waitcnt vmcnt(0)
	v_mov_b32_e32 v40, v37
	v_mov_b32_e32 v41, v38
	v_mov_b32_e32 v37, v39
	v_add_f32_e32 v36, v40, v36
	v_add_f32_e32 v37, v41, v37
	s_nop 0
	v_add_f32_e32 v33, v36, v37
	v_fmamk_f32 v33, v33, 0x3b800000, v167
	v_mul_f32_e32 v36, 0x4b800000, v33
	v_cmp_gt_f32_e64 s[12:13], s90, v33
	s_nop 1
	v_cndmask_b32_e64 v33, v33, v36, s[12:13]
	v_rsq_f32_e32 v33, v33
	v_lshlrev_b32_e32 v36, 2, v32
	v_mul_f32_e32 v32, 0x45800000, v33
	v_cndmask_b32_e64 v32, v33, v32, s[12:13]
	v_mov_b32_e32 v33, v32
	v_mul_f32_e32 v38, v28, v32
	v_mul_f32_e32 v39, v29, v33
	v_mul_f32_e32 v28, v24, v32
	v_mul_f32_e32 v29, v25, v33
	s_cbranch_vccnz .LBB0_1840
	v_mov_b32_e32 v37, v137
	v_lshl_add_u64 v[24:25], v[144:145], 0, v[36:37]
	global_load_dwordx4 v[40:43], v[24:25], off
	v_lshl_add_u64 v[24:25], v[142:143], 0, v[36:37]
	global_load_dwordx4 v[44:47], v[24:25], off
	s_sub_i32 s0, s62, s95
	v_mov_b32_e32 v24, v32
	v_mov_b32_e32 v25, v32
	v_mul_f32_e32 v48, v30, v24
	v_mul_f32_e32 v49, v31, v25
	v_mul_f32_e32 v24, v26, v24
	v_mul_f32_e32 v25, v27, v25
	s_ashr_i32 s1, s0, 31
	v_mov_b32_e32 v153, v137
	v_lshl_add_u64 v[50:51], s[0:1], 1, v[34:35]
	v_lshl_add_u64 v[50:51], v[50:51], 0, v[152:153]
	s_mov_b64 s[64:65], 0
	s_waitcnt vmcnt(0)
	v_mul_f32_e32 v52, v24, v42
	v_mul_f32_e32 v53, v25, v43
	v_mul_f32_e32 v54, v28, v40
	v_mul_f32_e32 v55, v29, v41
	v_mul_f32_e32 v42, v48, v42
	v_mul_f32_e32 v43, v49, v43
	v_mul_f32_e32 v40, v38, v40
	v_mul_f32_e32 v41, v39, v41
	v_pk_fma_f32 v[48:49], v[48:49], v[46:47], v[52:53] neg_lo:[0,0,1] neg_hi:[0,0,1]
	v_pk_fma_f32 v[52:53], v[38:39], v[44:45], v[54:55] neg_lo:[0,0,1] neg_hi:[0,0,1]
	v_fma_f32 v24, v24, v46, v42
	v_fma_f32 v25, v25, v47, v43
	v_fma_f32 v40, v28, v44, v40
	v_fma_f32 v41, v29, v45, v41
	v_cvt_pk_bf16_f32 v42, v52, v53
	v_cvt_pk_bf16_f32 v43, v48, v49
	s_nop 0
	v_cvt_pk_bf16_f32 v40, v40, v41
	v_cvt_pk_bf16_f32 v41, v24, v25
	global_store_dwordx2 v[50:51], v[42:43], off offset:256
	global_store_dwordx2 v[50:51], v[40:41], off offset:320
.LBB0_1840:
	s_andn2_b64 vcc, exec, s[64:65]
	v_lshl_add_u64 v[24:25], v[34:35], 0, v[136:137]
	s_cbranch_vccnz .LBB0_1842
	v_mov_b32_e32 v40, v32
	v_mov_b32_e32 v41, v32
	v_mul_f32_e32 v30, v30, v40
	v_mul_f32_e32 v31, v31, v41
	s_ashr_i32 s63, s62, 31
	v_mul_f32_e32 v40, v26, v40
	v_mul_f32_e32 v41, v27, v41
	v_cvt_pk_bf16_f32 v26, v38, v39
	v_cvt_pk_bf16_f32 v27, v30, v31
	v_lshl_add_u64 v[30:31], s[62:63], 1, v[24:25]
	v_cvt_pk_bf16_f32 v28, v28, v29
	v_cvt_pk_bf16_f32 v29, v40, v41
	global_store_dwordx4 v[30:31], v[26:29], off
.LBB0_1842:
	s_mov_b64 s[12:13], -1
	s_and_b64 vcc, exec, s[6:7]
	v_mul_f32_e32 v20, v20, v32
	v_mul_f32_e32 v21, v21, v33
	v_mul_f32_e32 v16, v16, v32
	v_mul_f32_e32 v17, v17, v33
	s_cbranch_vccnz .LBB0_1844
	v_mov_b32_e32 v37, v137
	v_lshl_add_u64 v[26:27], v[144:145], 0, v[36:37]
	global_load_dwordx4 v[26:29], v[26:27], off
	v_lshl_add_u64 v[30:31], v[142:143], 0, v[36:37]
	global_load_dwordx4 v[36:39], v[30:31], off
	s_ashr_i32 s1, s94, 31
	s_ashr_i32 s2, s62, 31
	v_mov_b32_e32 v33, v32
	s_sub_u32 s0, s62, s94
	v_mul_f32_e32 v40, v18, v32
	v_mul_f32_e32 v41, v19, v33
	s_subb_u32 s1, s2, s1
	v_mov_b32_e32 v153, v137
	v_mul_f32_e32 v30, v22, v32
	v_mul_f32_e32 v31, v23, v33
	v_lshl_add_u64 v[34:35], s[0:1], 1, v[34:35]
	v_lshl_add_u64 v[34:35], v[34:35], 0, v[152:153]
	s_mov_b64 s[12:13], 0
	s_waitcnt vmcnt(0)
	v_mul_f32_e32 v42, v40, v28
	v_mul_f32_e32 v43, v41, v29
	v_mul_f32_e32 v44, v16, v26
	v_mul_f32_e32 v45, v17, v27
	v_mul_f32_e32 v26, v20, v26
	v_mul_f32_e32 v27, v21, v27
	v_mul_f32_e32 v28, v30, v28
	v_mul_f32_e32 v29, v31, v29
	v_pk_fma_f32 v[30:31], v[30:31], v[38:39], v[42:43] neg_lo:[0,0,1] neg_hi:[0,0,1]
	v_pk_fma_f32 v[42:43], v[20:21], v[36:37], v[44:45] neg_lo:[0,0,1] neg_hi:[0,0,1]
	v_fma_f32 v26, v16, v36, v26
	v_fma_f32 v27, v17, v37, v27
	v_cvt_pk_bf16_f32 v36, v42, v43
	v_cvt_pk_bf16_f32 v37, v30, v31
	v_fma_f32 v28, v40, v38, v28
	v_fma_f32 v29, v41, v39, v29
	v_cvt_pk_bf16_f32 v26, v26, v27
	s_nop 0
	v_cvt_pk_bf16_f32 v27, v28, v29
	global_store_dwordx2 v[34:35], v[36:37], off offset:512
	global_store_dwordx2 v[34:35], v[26:27], off offset:576
; __device__ __forceinline__ unsigned cvt_pk_bf16(float lo, float hi) { unsigned r; asm volatile("v_cvt_pk_bf16_f32 %0, %1, %2" : "=v"(r) : "v"(lo), "v"(hi)); return r; }
;     DI void operator()(const f32x4 (&acc)[2][2][4][2], const Unit& u, int wr, int wc, int fr, int fq) const {
;     ...
;             for (int m = 0; m < 4; ++m) { const int row = row0 + ai * 128 + m * 16; const f32x4 q4 = *(const f32x4*)(ssq4 + (size_t)row * 4);
;                 const float s = rsqrtf(((q4[0] + q4[1]) + (q4[2] + q4[3])) * (1.f / 256.f) + EPS); bf16_t* rowp = Q + (size_t)row * 768;
; #pragma unroll
;                 for (int bj = 0; bj < 2; ++bj) { const int c0 = u.pn * 256 + bj * 128 + wc * 32, h = c0 / 192, d0 = c0 - h * 192;
;                     if (d0 < 128) { const f32x4 v0 = acc[ai][bj][m][0] * s, v1 = acc[ai][bj][m][1] * s; u32x4 w;
;                         w.x = cvt_pk_bf16(v0[0], v0[1]); w.y = cvt_pk_bf16(v0[2], v0[3]); w.z = cvt_pk_bf16(v1[0], v1[1]); w.w = cvt_pk_bf16(v1[2], v1[3]);
;                         *(u32x4*)(rowp + c0 + 8 * fq) = w; }
;                     else { const int i0 = 16 * (wc & 1) + 4 * fq, pos = row & (SEQ - 1);
;                         const f32x4 c = *(const f32x4*)(cs + pos * 32 + i0), sv = *(const f32x4*)(sn + pos * 32 + i0);
;                         const f32x4 x1 = acc[ai][bj][m][0] * s, x2 = acc[ai][bj][m][1] * s; const f32x4 o1 = x1 * c - x2 * sv, o2 = x2 * c + x1 * sv; u32x2 a, b;
;                         a.x = cvt_pk_bf16(o1[0], o1[1]); a.y = cvt_pk_bf16(o1[2], o1[3]); b.x = cvt_pk_bf16(o2[0], o2[1]); b.y = cvt_pk_bf16(o2[2], o2[3]);
;                         *(u32x2*)(rowp + h * 192 + 128 + i0) = a; *(u32x2*)(rowp + h * 192 + 160 + i0) = b; } } }
.LBB0_1844:
	s_andn2_b64 vcc, exec, s[12:13]
	s_cbranch_vccnz .LBB0_1846
	v_mov_b32_e32 v33, v32
	s_ashr_i32 s63, s62, 31
	v_mul_f32_e32 v22, v22, v32
	v_mul_f32_e32 v23, v23, v33
	v_mul_f32_e32 v26, v18, v32
	v_mul_f32_e32 v27, v19, v33
	v_cvt_pk_bf16_f32 v18, v20, v21
	v_cvt_pk_bf16_f32 v19, v22, v23
	v_cvt_pk_bf16_f32 v20, v16, v17
	v_lshl_add_u64 v[16:17], s[62:63], 1, v[24:25]
	v_cvt_pk_bf16_f32 v21, v26, v27
	global_store_dwordx4 v[16:17], v[18:21], off offset:256
.LBB0_1846:
	v_add_u32_e32 v16, 0xb0, v154
	v_ashrrev_i32_e32 v17, 31, v16
	v_lshl_add_u64 v[18:19], v[16:17], 4, s[20:21]
	global_load_dwordx4 v[20:23], v[18:19], off
	s_and_b64 vcc, exec, s[8:9]
	v_mov_b64_e32 v[18:19], s[18:19]
	v_mad_i64_i32 v[18:19], s[0:1], v16, s91, v[18:19]
	v_lshlrev_b32_e32 v16, 5, v16
	v_and_b32_e32 v16, 0x1ffe0, v16
	s_mov_b64 s[12:13], -1
	s_waitcnt vmcnt(0)
	v_mov_b32_e32 v24, v21
	v_mov_b32_e32 v25, v22
	v_mov_b32_e32 v21, v23
	v_add_f32_e32 v20, v24, v20
	v_add_f32_e32 v21, v25, v21
	s_nop 0
	v_add_f32_e32 v17, v20, v21
	v_fmamk_f32 v17, v17, 0x3b800000, v167
	v_mul_f32_e32 v20, 0x4b800000, v17
	v_cmp_gt_f32_e64 s[8:9], s90, v17
	s_nop 1
	v_cndmask_b32_e64 v17, v17, v20, s[8:9]
	v_rsq_f32_e32 v17, v17
	v_lshlrev_b32_e32 v20, 2, v16
	v_mul_f32_e32 v16, 0x45800000, v17
	v_cndmask_b32_e64 v16, v17, v16, s[8:9]
	v_mov_b32_e32 v17, v16
	v_mul_f32_e32 v22, v12, v16
	v_mul_f32_e32 v23, v13, v17
	v_mul_f32_e32 v12, v8, v16
	v_mul_f32_e32 v13, v9, v17
	s_cbranch_vccnz .LBB0_1848
	v_mov_b32_e32 v21, v137
	v_lshl_add_u64 v[8:9], v[144:145], 0, v[20:21]
	global_load_dwordx4 v[24:27], v[8:9], off
	v_lshl_add_u64 v[8:9], v[142:143], 0, v[20:21]
	global_load_dwordx4 v[28:31], v[8:9], off
	s_sub_i32 s0, s62, s95
	v_mov_b32_e32 v8, v16
	v_mov_b32_e32 v9, v16
	v_mul_f32_e32 v32, v14, v8
	v_mul_f32_e32 v33, v15, v9
	v_mul_f32_e32 v8, v10, v8
	v_mul_f32_e32 v9, v11, v9
	s_ashr_i32 s1, s0, 31
	v_mov_b32_e32 v153, v137
	v_lshl_add_u64 v[34:35], s[0:1], 1, v[18:19]
	v_lshl_add_u64 v[34:35], v[34:35], 0, v[152:153]
	s_mov_b64 s[12:13], 0
	s_waitcnt vmcnt(0)
	v_mul_f32_e32 v36, v8, v26
	v_mul_f32_e32 v37, v9, v27
	v_mul_f32_e32 v38, v12, v24
	v_mul_f32_e32 v39, v13, v25
	v_mul_f32_e32 v26, v32, v26
	v_mul_f32_e32 v27, v33, v27
	v_mul_f32_e32 v24, v22, v24
	v_mul_f32_e32 v25, v23, v25
	v_pk_fma_f32 v[32:33], v[32:33], v[30:31], v[36:37] neg_lo:[0,0,1] neg_hi:[0,0,1]
	v_pk_fma_f32 v[36:37], v[22:23], v[28:29], v[38:39] neg_lo:[0,0,1] neg_hi:[0,0,1]
	v_fma_f32 v8, v8, v30, v26
	v_fma_f32 v9, v9, v31, v27
	v_fma_f32 v24, v12, v28, v24
	v_fma_f32 v25, v13, v29, v25
	v_cvt_pk_bf16_f32 v26, v36, v37
	v_cvt_pk_bf16_f32 v27, v32, v33
	s_nop 0
	v_cvt_pk_bf16_f32 v24, v24, v25
	v_cvt_pk_bf16_f32 v25, v8, v9
	global_store_dwordx2 v[34:35], v[26:27], off offset:256
	global_store_dwordx2 v[34:35], v[24:25], off offset:320
.LBB0_1848:
	s_andn2_b64 vcc, exec, s[12:13]
	v_lshl_add_u64 v[8:9], v[18:19], 0, v[136:137]
	s_cbranch_vccnz .LBB0_1850
	v_mov_b32_e32 v24, v16
	v_mov_b32_e32 v25, v16
	v_mul_f32_e32 v14, v14, v24
	v_mul_f32_e32 v15, v15, v25
	s_ashr_i32 s63, s62, 31
	v_mul_f32_e32 v24, v10, v24
	v_mul_f32_e32 v25, v11, v25
	v_cvt_pk_bf16_f32 v10, v22, v23
	v_cvt_pk_bf16_f32 v11, v14, v15
	v_lshl_add_u64 v[14:15], s[62:63], 1, v[8:9]
	v_cvt_pk_bf16_f32 v12, v12, v13
	v_cvt_pk_bf16_f32 v13, v24, v25
	global_store_dwordx4 v[14:15], v[10:13], off
.LBB0_1850:
	s_mov_b64 s[8:9], -1
	s_and_b64 vcc, exec, s[6:7]
	v_mul_f32_e32 v4, v4, v16
	v_mul_f32_e32 v5, v5, v17
	v_mul_f32_e32 v0, v0, v16
	v_mul_f32_e32 v1, v1, v17
	s_cbranch_vccz .LBB0_1853
	s_andn2_b64 vcc, exec, s[8:9]
	s_cbranch_vccz .LBB0_1854

; __device__ __forceinline__ unsigned cvt_pk_bf16(float lo, float hi) { unsigned r; asm volatile("v_cvt_pk_bf16_f32 %0, %1, %2" : "=v"(r) : "v"(lo), "v"(hi)); return r; }
;     DI void operator()(const f32x4 (&acc)[2][2][4][2], const Unit& u, int wr, int wc, int fr, int fq) const {
;     ...
;                     if (d0 < 128) { const f32x4 v0 = acc[ai][bj][m][0] * s, v1 = acc[ai][bj][m][1] * s; u32x4 w;
;                         w.x = cvt_pk_bf16(v0[0], v0[1]); w.y = cvt_pk_bf16(v0[2], v0[3]); w.z = cvt_pk_bf16(v1[0], v1[1]); w.w = cvt_pk_bf16(v1[2], v1[3]);
;                         *(u32x4*)(rowp + c0 + 8 * fq) = w; }
;                     else { const int i0 = 16 * (wc & 1) + 4 * fq, pos = row & (SEQ - 1);
;                         const f32x4 c = *(const f32x4*)(cs + pos * 32 + i0), sv = *(const f32x4*)(sn + pos * 32 + i0);
;                         const f32x4 x1 = acc[ai][bj][m][0] * s, x2 = acc[ai][bj][m][1] * s; const f32x4 o1 = x1 * c - x2 * sv, o2 = x2 * c + x1 * sv; u32x2 a, b;
;                         a.x = cvt_pk_bf16(o1[0], o1[1]); a.y = cvt_pk_bf16(o1[2], o1[3]); b.x = cvt_pk_bf16(o2[0], o2[1]); b.y = cvt_pk_bf16(o2[2], o2[3]);
;                         *(u32x2*)(rowp + h * 192 + 128 + i0) = a; *(u32x2*)(rowp + h * 192 + 160 + i0) = b; } } }
.LBB0_1853:
	v_mov_b32_e32 v21, v137
	v_lshl_add_u64 v[10:11], v[144:145], 0, v[20:21]
	global_load_dwordx4 v[10:13], v[10:11], off
	v_lshl_add_u64 v[14:15], v[142:143], 0, v[20:21]
	global_load_dwordx4 v[20:23], v[14:15], off
	s_ashr_i32 s1, s94, 31
	s_ashr_i32 s2, s62, 31
	v_mov_b32_e32 v17, v16
	s_sub_u32 s0, s62, s94
	v_mul_f32_e32 v24, v2, v16
	v_mul_f32_e32 v25, v3, v17
	s_subb_u32 s1, s2, s1
	v_mov_b32_e32 v153, v137
	v_mul_f32_e32 v14, v6, v16
	v_mul_f32_e32 v15, v7, v17
	v_lshl_add_u64 v[18:19], s[0:1], 1, v[18:19]
	v_lshl_add_u64 v[18:19], v[18:19], 0, v[152:153]
	s_waitcnt vmcnt(0)
	v_mul_f32_e32 v26, v24, v12
	v_mul_f32_e32 v27, v25, v13
	v_mul_f32_e32 v28, v0, v10
	v_mul_f32_e32 v29, v1, v11
	v_mul_f32_e32 v10, v4, v10
	v_mul_f32_e32 v11, v5, v11
	v_mul_f32_e32 v12, v14, v12
	v_mul_f32_e32 v13, v15, v13
	v_pk_fma_f32 v[14:15], v[14:15], v[22:23], v[26:27] neg_lo:[0,0,1] neg_hi:[0,0,1]
	v_pk_fma_f32 v[26:27], v[4:5], v[20:21], v[28:29] neg_lo:[0,0,1] neg_hi:[0,0,1]
	v_fma_f32 v10, v0, v20, v10
	v_fma_f32 v11, v1, v21, v11
	v_cvt_pk_bf16_f32 v20, v26, v27
	v_cvt_pk_bf16_f32 v21, v14, v15
	v_fma_f32 v12, v24, v22, v12
	v_fma_f32 v13, v25, v23, v13
	v_cvt_pk_bf16_f32 v10, v10, v11
	s_nop 0
	v_cvt_pk_bf16_f32 v11, v12, v13
	global_store_dwordx2 v[18:19], v[20:21], off offset:512
	global_store_dwordx2 v[18:19], v[10:11], off offset:576
	s_cbranch_execnz .LBB0_1852
.LBB0_1854:
	v_mov_b32_e32 v17, v16
	s_ashr_i32 s63, s62, 31
	v_mul_f32_e32 v6, v6, v16
	v_mul_f32_e32 v7, v7, v17
	v_mul_f32_e32 v10, v2, v16
	v_mul_f32_e32 v11, v3, v17
	v_cvt_pk_bf16_f32 v2, v4, v5
	v_cvt_pk_bf16_f32 v3, v6, v7
	v_cvt_pk_bf16_f32 v4, v0, v1
	v_lshl_add_u64 v[0:1], s[62:63], 1, v[8:9]
	v_cvt_pk_bf16_f32 v5, v10, v11
	global_store_dwordx4 v[0:1], v[2:5], off offset:256
	s_and_b64 vcc, exec, s[4:5]
	s_mov_b64 s[4:5], -1
	s_cbranch_vccnz .LBB0_1778

; __device__ __forceinline__ unsigned cvt_pk_bf16(float lo, float hi) { unsigned r; asm volatile("v_cvt_pk_bf16_f32 %0, %1, %2" : "=v"(r) : "v"(lo), "v"(hi)); return r; }
; DI float shx(float v, int mask, int lane) { return __int_as_float(__builtin_amdgcn_ds_bpermute((lane ^ mask) << 2, __float_as_int(v))); }
;     DI void operator()(const f32x4 (&acc)[2][2][4][2], const Unit& u, int wr, int wc, int fr, int fq) const {
;     ...
;         float rs[2][4];
; #pragma unroll
;         for (int ai = 0; ai < 2; ++ai)
; #pragma unroll
;             for (int m = 0; m < 4; ++m) { const f32x4 q4 = *(const f32x4*)(sskv4 + (size_t)(row0 + ai * 128 + m * 16) * 4); rs[ai][m] = rsqrtf(((q4[0] + q4[1]) + (q4[2] + q4[3])) * (1.f / 128.f) + EPS); }
; #pragma unroll
;         for (int ai = 0; ai < 2; ++ai)
; #pragma unroll
;             for (int m = 0; m < 4; ++m) { const int row = row0 + ai * 128 + m * 16; const float s = rs[ai][m];
;                 const f32x4 w0 = acc[ai][1][m][0] * s, w1 = acc[ai][1][m][1] * s; u32x4 w;
;                 w.x = cvt_pk_bf16(w0[0], w0[1]); w.y = cvt_pk_bf16(w0[2], w0[3]); w.z = cvt_pk_bf16(w1[0], w1[1]); w.w = cvt_pk_bf16(w1[2], w1[3]);
;                 *(u32x4*)(V + (size_t)row * 512 + h * 128 + cw) = w;
;                 const f32x4 v0 = acc[ai][0][m][0] * s, v1 = acc[ai][0][m][1] * s;
;                 float ss = ((v0[0] * v0[0] + v0[1] * v0[1]) + (v0[2] * v0[2] + v0[3] * v0[3])) + ((v1[0] * v1[0] + v1[1] * v1[1]) + (v1[2] * v1[2] + v1[3] * v1[3]));
;                 ss += shx(ss, 16, ln); ss += shx(ss, 32, ln);
;                 if (fq == 0) part[(ai * 128 + wr * 64 + m * 16 + fr) * 4 + wc] = ss; }
.LBB0_1877:
	v_lshl_add_u32 v192, s93, 8, v175
	v_ashrrev_i32_e32 v193, 31, v192
	v_or_b32_e32 v190, 16, v192
	v_lshl_add_u64 v[128:129], v[192:193], 4, s[22:23]
	v_ashrrev_i32_e32 v191, 31, v190
	global_load_dwordx4 v[206:209], v[128:129], off
	v_lshl_add_u64 v[128:129], v[190:191], 4, s[22:23]
	global_load_dwordx4 v[210:213], v[128:129], off
	v_or_b32_e32 v188, 32, v192
	v_or_b32_e32 v186, 48, v192
	v_add_u32_e32 v184, 0x80, v192
	v_add_u32_e32 v182, 0x90, v192
	v_add_u32_e32 v180, 0xa0, v192
	v_add_u32_e32 v178, 0xb0, v192
	v_ashrrev_i32_e32 v189, 31, v188
	v_ashrrev_i32_e32 v187, 31, v186
	v_ashrrev_i32_e32 v185, 31, v184
	v_ashrrev_i32_e32 v183, 31, v182
	v_ashrrev_i32_e32 v181, 31, v180
	v_ashrrev_i32_e32 v179, 31, v178
	v_lshl_add_u64 v[128:129], v[188:189], 4, s[22:23]
	v_lshl_add_u64 v[130:131], v[186:187], 4, s[22:23]
	v_lshl_add_u64 v[132:133], v[184:185], 4, s[22:23]
	v_lshl_add_u64 v[134:135], v[182:183], 4, s[22:23]
	v_lshl_add_u64 v[196:197], v[180:181], 4, s[22:23]
	v_lshl_add_u64 v[214:215], v[178:179], 4, s[22:23]
	global_load_dwordx4 v[148:151], v[128:129], off
	global_load_dwordx4 v[144:147], v[130:131], off
	global_load_dwordx4 v[140:143], v[132:133], off
	global_load_dwordx4 v[136:139], v[134:135], off
	s_nop 0
	global_load_dwordx4 v[132:135], v[196:197], off
	global_load_dwordx4 v[128:131], v[214:215], off
	s_lshl_b32 s62, s92, 7
	s_ashr_i32 s63, s62, 31
	s_waitcnt vmcnt(0)
	v_mov_b32_e32 v196, v207
	v_mov_b32_e32 v197, v208
	v_mov_b32_e32 v207, v209
	v_add_f32_e32 v196, v196, v206
	v_add_f32_e32 v197, v197, v207
	v_mov_b32_e32 v206, v211
	v_mov_b32_e32 v207, v212
	v_mov_b32_e32 v211, v213
	v_add_f32_e32 v206, v206, v210
	v_add_f32_e32 v207, v207, v211
	v_mov_b32_e32 v209, v196
	v_mov_b32_e32 v208, v206
	v_mov_b32_e32 v196, v207
	v_add_f32_e32 v196, v208, v196
	v_add_f32_e32 v197, v209, v197
	s_nop 0
	v_pk_fma_f32 v[196:197], v[196:197], s[36:37], v[174:175] op_sel_hi:[1,0,0]
	s_nop 0
	v_mul_f32_e32 v177, 0x4b800000, v197
	v_cmp_gt_f32_e64 s[8:9], s87, v197
	v_cmp_gt_f32_e32 vcc, s87, v196
	s_nop 0
	v_cndmask_b32_e64 v177, v197, v177, s[8:9]
	v_rsq_f32_e32 v177, v177
	s_nop 0
	v_mul_f32_e32 v194, 0x45800000, v177
	v_cndmask_b32_e64 v194, v177, v194, s[8:9]
	v_mul_f32_e32 v124, v124, v194
	v_mul_f32_e32 v125, v125, v194
	v_mul_f32_e32 v208, v58, v194
	v_mul_f32_e32 v209, v59, v194
	v_mul_f32_e32 v210, v56, v194
	v_mul_f32_e32 v211, v57, v194
	v_mul_f32_e32 v212, v62, v194
	v_mul_f32_e32 v213, v63, v194
	v_mul_f32_e32 v214, v60, v194
	v_mul_f32_e32 v215, v61, v194
	v_mul_f32_e32 v206, v122, v194
	v_mul_f32_e32 v207, v123, v194
	v_cvt_pk_bf16_f32 v122, v124, v125
	v_mul_f32_e32 v123, v211, v211
	v_mul_f32_e32 v124, v209, v209
	v_mul_f32_e32 v125, v215, v215
	v_mul_f32_e32 v177, v213, v213
	v_fmac_f32_e32 v123, v210, v210
	v_fmac_f32_e32 v124, v208, v208
	v_fmac_f32_e32 v125, v214, v214
	v_fmac_f32_e32 v177, v212, v212
	v_add_f32_e32 v123, v123, v124
	v_add_f32_e32 v124, v125, v177
	v_add_f32_e32 v177, v123, v124
	ds_bpermute_b32 v197, v198, v177
	v_mul_f32_e32 v120, v120, v194
	v_mul_f32_e32 v121, v121, v194
	v_mul_f32_e32 v126, v126, v194
	v_mul_f32_e32 v127, v127, v194
	s_nop 0
	v_cvt_pk_bf16_f32 v123, v126, v127
	v_cvt_pk_bf16_f32 v124, v120, v121
	s_waitcnt lgkmcnt(0)
	v_add_f32_e32 v120, v177, v197
	ds_bpermute_b32 v121, v199, v120
	v_lshlrev_b64 v[126:127], 10, v[192:193]
	v_lshl_add_u64 v[126:127], s[12:13], 0, v[126:127]
	v_lshl_add_u64 v[126:127], s[62:63], 1, v[126:127]
	v_lshl_add_u64 v[126:127], v[126:127], 0, v[160:161]
	v_cvt_pk_bf16_f32 v125, v206, v207
	global_store_dwordx4 v[126:127], v[122:125], off
	s_and_saveexec_b64 s[8:9], s[4:5]
	s_cbranch_execz .LBB0_1879
	s_waitcnt lgkmcnt(0)
	v_add_f32_e32 v120, v120, v121
	ds_write_b32 v201, v120
.LBB0_1879:
	s_or_b64 exec, exec, s[8:9]
	v_mul_f32_e32 v120, 0x4b800000, v196
	v_cndmask_b32_e32 v120, v196, v120, vcc
	v_rsq_f32_e32 v120, v120
	s_waitcnt lgkmcnt(0)
	v_mul_f32_e32 v121, 0x45800000, v120
	v_cndmask_b32_e32 v120, v120, v121, vcc
	v_mul_f32_e32 v116, v116, v120
	v_mul_f32_e32 v117, v117, v120
	v_mul_f32_e32 v122, v114, v120
	v_mul_f32_e32 v123, v115, v120
	v_cvt_pk_bf16_f32 v114, v116, v117
	v_mul_f32_e32 v116, v54, v120
	v_mul_f32_e32 v117, v55, v120
	v_mul_f32_e32 v124, v52, v120
	v_mul_f32_e32 v125, v53, v120
	v_mul_f32_e32 v117, v117, v117
	v_mul_f32_e32 v115, v125, v125
	v_mul_f32_e32 v126, v50, v120
	v_mul_f32_e32 v127, v51, v120
	v_mul_f32_e32 v196, v48, v120
	v_mul_f32_e32 v197, v49, v120
	v_fmac_f32_e32 v115, v124, v124
	v_fmac_f32_e32 v117, v116, v116
	v_add_f32_e32 v115, v115, v117
	v_mul_f32_e32 v116, v197, v197
	v_mul_f32_e32 v117, v127, v127
	v_fmac_f32_e32 v116, v196, v196
	v_fmac_f32_e32 v117, v126, v126
	v_add_f32_e32 v116, v116, v117
	v_mul_f32_e32 v118, v118, v120
	v_mul_f32_e32 v119, v119, v120
	v_mul_f32_e32 v112, v112, v120
	v_mul_f32_e32 v113, v113, v120
	v_add_f32_e32 v121, v115, v116
	ds_bpermute_b32 v124, v198, v121
	v_cvt_pk_bf16_f32 v115, v118, v119
	v_cvt_pk_bf16_f32 v116, v112, v113
	v_lshlrev_b64 v[118:119], 10, v[190:191]
	v_lshl_add_u64 v[118:119], s[12:13], 0, v[118:119]
	s_waitcnt lgkmcnt(0)
	v_add_f32_e32 v112, v121, v124
	ds_bpermute_b32 v113, v199, v112
	v_lshl_add_u64 v[118:119], s[62:63], 1, v[118:119]
	v_lshl_add_u64 v[118:119], v[118:119], 0, v[160:161]
	v_cvt_pk_bf16_f32 v117, v122, v123
	global_store_dwordx4 v[118:119], v[114:117], off
	s_and_saveexec_b64 s[8:9], s[4:5]
	s_cbranch_execz .LBB0_1881
	s_waitcnt lgkmcnt(0)
	v_add_f32_e32 v112, v112, v113
	ds_write_b32 v201, v112 offset:256
; __device__ __forceinline__ unsigned cvt_pk_bf16(float lo, float hi) { unsigned r; asm volatile("v_cvt_pk_bf16_f32 %0, %1, %2" : "=v"(r) : "v"(lo), "v"(hi)); return r; }
; DI float shx(float v, int mask, int lane) { return __int_as_float(__builtin_amdgcn_ds_bpermute((lane ^ mask) << 2, __float_as_int(v))); }
;     DI void operator()(const f32x4 (&acc)[2][2][4][2], const Unit& u, int wr, int wc, int fr, int fq) const {
;     ...
;         for (int ai = 0; ai < 2; ++ai)
; #pragma unroll
;             for (int m = 0; m < 4; ++m) { const int row = row0 + ai * 128 + m * 16; const float s = rs[ai][m];
;                 const f32x4 w0 = acc[ai][1][m][0] * s, w1 = acc[ai][1][m][1] * s; u32x4 w;
;                 w.x = cvt_pk_bf16(w0[0], w0[1]); w.y = cvt_pk_bf16(w0[2], w0[3]); w.z = cvt_pk_bf16(w1[0], w1[1]); w.w = cvt_pk_bf16(w1[2], w1[3]);
;                 *(u32x4*)(V + (size_t)row * 512 + h * 128 + cw) = w;
;                 const f32x4 v0 = acc[ai][0][m][0] * s, v1 = acc[ai][0][m][1] * s;
;                 float ss = ((v0[0] * v0[0] + v0[1] * v0[1]) + (v0[2] * v0[2] + v0[3] * v0[3])) + ((v1[0] * v1[0] + v1[1] * v1[1]) + (v1[2] * v1[2] + v1[3] * v1[3]));
;                 ss += shx(ss, 16, ln); ss += shx(ss, 32, ln);
;                 if (fq == 0) part[(ai * 128 + wr * 64 + m * 16 + fr) * 4 + wc] = ss; }
.LBB0_1881:
	s_or_b64 exec, exec, s[8:9]
	v_mov_b32_e32 v112, v149
	s_waitcnt lgkmcnt(0)
	v_mov_b32_e32 v113, v150
	v_mov_b32_e32 v149, v151
	v_mov_b32_e32 v114, v145
	v_mov_b32_e32 v115, v146
	v_mov_b32_e32 v145, v147
	v_add_f32_e32 v112, v112, v148
	v_add_f32_e32 v113, v113, v149
	v_add_f32_e32 v114, v114, v144
	v_add_f32_e32 v115, v115, v145
	v_mov_b32_e32 v117, v112
	v_mov_b32_e32 v116, v114
	v_mov_b32_e32 v112, v115
	v_add_f32_e32 v112, v116, v112
	v_add_f32_e32 v113, v117, v113
	s_nop 0
	v_pk_fma_f32 v[114:115], v[112:113], s[36:37], v[174:175] op_sel_hi:[1,0,0]
	s_nop 0
	v_mul_f32_e32 v112, 0x4b800000, v115
	v_cmp_gt_f32_e64 s[8:9], s87, v115
	v_cmp_gt_f32_e32 vcc, s87, v114
	s_nop 0
	v_cndmask_b32_e64 v112, v115, v112, s[8:9]
	v_rsq_f32_e32 v112, v112
	s_nop 0
	v_mul_f32_e32 v113, 0x45800000, v112
	v_cndmask_b32_e64 v112, v112, v113, s[8:9]
	v_mul_f32_e32 v108, v108, v112
	v_mul_f32_e32 v109, v109, v112
	v_mul_f32_e32 v116, v106, v112
	v_mul_f32_e32 v117, v107, v112
	v_cvt_pk_bf16_f32 v106, v108, v109
	v_mul_f32_e32 v108, v46, v112
	v_mul_f32_e32 v109, v47, v112
	v_mul_f32_e32 v118, v44, v112
	v_mul_f32_e32 v119, v45, v112
	v_mul_f32_e32 v109, v109, v109
	v_mul_f32_e32 v107, v119, v119
	v_mul_f32_e32 v122, v42, v112
	v_mul_f32_e32 v123, v43, v112
	v_mul_f32_e32 v124, v40, v112
	v_mul_f32_e32 v125, v41, v112
	v_fmac_f32_e32 v107, v118, v118
	v_fmac_f32_e32 v109, v108, v108
	v_add_f32_e32 v107, v107, v109
	v_mul_f32_e32 v108, v125, v125
	v_mul_f32_e32 v109, v123, v123
	v_fmac_f32_e32 v108, v124, v124
	v_fmac_f32_e32 v109, v122, v122
	v_add_f32_e32 v108, v108, v109
	v_mul_f32_e32 v110, v110, v112
	v_mul_f32_e32 v111, v111, v112
	v_mul_f32_e32 v104, v104, v112
	v_mul_f32_e32 v105, v105, v112
	v_add_f32_e32 v113, v107, v108
	ds_bpermute_b32 v115, v198, v113
	v_cvt_pk_bf16_f32 v107, v110, v111
	v_cvt_pk_bf16_f32 v108, v104, v105
	v_lshlrev_b64 v[110:111], 10, v[188:189]
	v_lshl_add_u64 v[110:111], s[12:13], 0, v[110:111]
	s_waitcnt lgkmcnt(0)
	v_add_f32_e32 v104, v113, v115
	ds_bpermute_b32 v105, v199, v104
	v_lshl_add_u64 v[110:111], s[62:63], 1, v[110:111]
	v_lshl_add_u64 v[110:111], v[110:111], 0, v[160:161]
	v_cvt_pk_bf16_f32 v109, v116, v117
	global_store_dwordx4 v[110:111], v[106:109], off
	s_and_saveexec_b64 s[8:9], s[4:5]
	s_cbranch_execz .LBB0_1883
	s_waitcnt lgkmcnt(0)
	v_add_f32_e32 v104, v104, v105
	ds_write_b32 v201, v104 offset:512
.LBB0_1883:
	s_or_b64 exec, exec, s[8:9]
	v_mul_f32_e32 v104, 0x4b800000, v114
	v_cndmask_b32_e32 v104, v114, v104, vcc
	v_rsq_f32_e32 v104, v104
	s_waitcnt lgkmcnt(0)
	v_mul_f32_e32 v105, 0x45800000, v104
	v_cndmask_b32_e32 v104, v104, v105, vcc
	v_mul_f32_e32 v100, v100, v104
	v_mul_f32_e32 v101, v101, v104
	v_mul_f32_e32 v106, v98, v104
	v_mul_f32_e32 v107, v99, v104
	v_cvt_pk_bf16_f32 v98, v100, v101
	v_mul_f32_e32 v100, v38, v104
	v_mul_f32_e32 v101, v39, v104
	v_mul_f32_e32 v108, v36, v104
	v_mul_f32_e32 v109, v37, v104
	v_mul_f32_e32 v101, v101, v101
	v_mul_f32_e32 v99, v109, v109
	v_mul_f32_e32 v110, v34, v104
	v_mul_f32_e32 v111, v35, v104
	v_mul_f32_e32 v114, v32, v104
	v_mul_f32_e32 v115, v33, v104
	v_fmac_f32_e32 v99, v108, v108
	v_fmac_f32_e32 v101, v100, v100
	v_add_f32_e32 v99, v99, v101
	v_mul_f32_e32 v100, v115, v115
	v_mul_f32_e32 v101, v111, v111
	v_fmac_f32_e32 v100, v114, v114
	v_fmac_f32_e32 v101, v110, v110
	v_add_f32_e32 v100, v100, v101
	v_mul_f32_e32 v102, v102, v104
	v_mul_f32_e32 v103, v103, v104
	v_mul_f32_e32 v96, v96, v104
	v_mul_f32_e32 v97, v97, v104
	v_add_f32_e32 v105, v99, v100
	ds_bpermute_b32 v108, v198, v105
	v_cvt_pk_bf16_f32 v99, v102, v103
	v_cvt_pk_bf16_f32 v100, v96, v97
	v_lshlrev_b64 v[102:103], 10, v[186:187]
	v_lshl_add_u64 v[102:103], s[12:13], 0, v[102:103]
	s_waitcnt lgkmcnt(0)
	v_add_f32_e32 v96, v105, v108
	ds_bpermute_b32 v97, v199, v96
	v_lshl_add_u64 v[102:103], s[62:63], 1, v[102:103]
	v_lshl_add_u64 v[102:103], v[102:103], 0, v[160:161]
	v_cvt_pk_bf16_f32 v101, v106, v107
	global_store_dwordx4 v[102:103], v[98:101], off
	s_and_saveexec_b64 s[8:9], s[4:5]
	s_cbranch_execz .LBB0_1885
	s_waitcnt lgkmcnt(0)
	v_add_f32_e32 v96, v96, v97
	ds_write_b32 v201, v96 offset:768
.LBB0_1885:
	s_or_b64 exec, exec, s[8:9]
	v_mov_b32_e32 v96, v141
	s_waitcnt lgkmcnt(0)
	v_mov_b32_e32 v97, v142
	v_mov_b32_e32 v141, v143
	v_mov_b32_e32 v98, v137
	v_mov_b32_e32 v99, v138
	v_mov_b32_e32 v137, v139
	v_add_f32_e32 v96, v96, v140
	v_add_f32_e32 v97, v97, v141
	v_add_f32_e32 v98, v98, v136
	v_add_f32_e32 v99, v99, v137
	v_mov_b32_e32 v101, v96
	v_mov_b32_e32 v100, v98
	v_mov_b32_e32 v96, v99
	v_add_f32_e32 v96, v100, v96
	v_add_f32_e32 v97, v101, v97
	s_nop 0
	v_pk_fma_f32 v[98:99], v[96:97], s[36:37], v[174:175] op_sel_hi:[1,0,0]
	s_nop 0
	v_mul_f32_e32 v96, 0x4b800000, v99
	v_cmp_gt_f32_e64 s[8:9], s87, v99
	v_cmp_gt_f32_e32 vcc, s87, v98
	s_nop 0
	v_cndmask_b32_e64 v96, v99, v96, s[8:9]
	v_rsq_f32_e32 v96, v96
	s_nop 0
	v_mul_f32_e32 v97, 0x45800000, v96
	v_cndmask_b32_e64 v96, v96, v97, s[8:9]
	v_mul_f32_e32 v92, v92, v96
	v_mul_f32_e32 v93, v93, v96
	v_mul_f32_e32 v100, v90, v96
	v_mul_f32_e32 v101, v91, v96
	v_cvt_pk_bf16_f32 v90, v92, v93
	v_mul_f32_e32 v92, v30, v96
	v_mul_f32_e32 v93, v31, v96
	v_mul_f32_e32 v102, v28, v96
	v_mul_f32_e32 v103, v29, v96
	v_mul_f32_e32 v93, v93, v93
	v_mul_f32_e32 v91, v103, v103
	v_mul_f32_e32 v106, v26, v96
	v_mul_f32_e32 v107, v27, v96
	v_mul_f32_e32 v108, v24, v96
	v_mul_f32_e32 v109, v25, v96
	v_fmac_f32_e32 v91, v102, v102
	v_fmac_f32_e32 v93, v92, v92
	v_add_f32_e32 v91, v91, v93
	v_mul_f32_e32 v92, v109, v109
	v_mul_f32_e32 v93, v107, v107
	v_fmac_f32_e32 v92, v108, v108
	v_fmac_f32_e32 v93, v106, v106
	v_add_f32_e32 v92, v92, v93
	v_mul_f32_e32 v94, v94, v96
	v_mul_f32_e32 v95, v95, v96
	v_mul_f32_e32 v88, v88, v96
	v_mul_f32_e32 v89, v89, v96
	v_add_f32_e32 v97, v91, v92
	ds_bpermute_b32 v99, v198, v97
	v_cvt_pk_bf16_f32 v91, v94, v95
	v_cvt_pk_bf16_f32 v92, v88, v89
	v_lshlrev_b64 v[94:95], 10, v[184:185]
	v_lshl_add_u64 v[94:95], s[12:13], 0, v[94:95]
	s_waitcnt lgkmcnt(0)
	v_add_f32_e32 v88, v97, v99
	ds_bpermute_b32 v89, v199, v88
	v_lshl_add_u64 v[94:95], s[62:63], 1, v[94:95]
	v_lshl_add_u64 v[94:95], v[94:95], 0, v[160:161]
	v_cvt_pk_bf16_f32 v93, v100, v101
	global_store_dwordx4 v[94:95], v[90:93], off
	s_and_saveexec_b64 s[8:9], s[4:5]
	s_cbranch_execz .LBB0_1887
	s_waitcnt lgkmcnt(0)
	v_add_f32_e32 v88, v88, v89
	ds_write_b32 v201, v88 offset:2048
; __device__ __forceinline__ unsigned cvt_pk_bf16(float lo, float hi) { unsigned r; asm volatile("v_cvt_pk_bf16_f32 %0, %1, %2" : "=v"(r) : "v"(lo), "v"(hi)); return r; }
; DI float shx(float v, int mask, int lane) { return __int_as_float(__builtin_amdgcn_ds_bpermute((lane ^ mask) << 2, __float_as_int(v))); }
;     DI void operator()(const f32x4 (&acc)[2][2][4][2], const Unit& u, int wr, int wc, int fr, int fq) const {
;     ...
;         for (int ai = 0; ai < 2; ++ai)
; #pragma unroll
;             for (int m = 0; m < 4; ++m) { const int row = row0 + ai * 128 + m * 16; const float s = rs[ai][m];
;                 const f32x4 w0 = acc[ai][1][m][0] * s, w1 = acc[ai][1][m][1] * s; u32x4 w;
;                 w.x = cvt_pk_bf16(w0[0], w0[1]); w.y = cvt_pk_bf16(w0[2], w0[3]); w.z = cvt_pk_bf16(w1[0], w1[1]); w.w = cvt_pk_bf16(w1[2], w1[3]);
;                 *(u32x4*)(V + (size_t)row * 512 + h * 128 + cw) = w;
;                 const f32x4 v0 = acc[ai][0][m][0] * s, v1 = acc[ai][0][m][1] * s;
;                 float ss = ((v0[0] * v0[0] + v0[1] * v0[1]) + (v0[2] * v0[2] + v0[3] * v0[3])) + ((v1[0] * v1[0] + v1[1] * v1[1]) + (v1[2] * v1[2] + v1[3] * v1[3]));
;                 ss += shx(ss, 16, ln); ss += shx(ss, 32, ln);
;                 if (fq == 0) part[(ai * 128 + wr * 64 + m * 16 + fr) * 4 + wc] = ss; }
.LBB0_1887:
	s_or_b64 exec, exec, s[8:9]
	v_mul_f32_e32 v88, 0x4b800000, v98
	v_cndmask_b32_e32 v88, v98, v88, vcc
	v_rsq_f32_e32 v88, v88
	s_waitcnt lgkmcnt(0)
	v_mul_f32_e32 v89, 0x45800000, v88
	v_cndmask_b32_e32 v88, v88, v89, vcc
	v_mul_f32_e32 v84, v84, v88
	v_mul_f32_e32 v85, v85, v88
	v_mul_f32_e32 v90, v82, v88
	v_mul_f32_e32 v91, v83, v88
	v_cvt_pk_bf16_f32 v82, v84, v85
	v_mul_f32_e32 v84, v22, v88
	v_mul_f32_e32 v85, v23, v88
	v_mul_f32_e32 v92, v20, v88
	v_mul_f32_e32 v93, v21, v88
	v_mul_f32_e32 v85, v85, v85
	v_mul_f32_e32 v83, v93, v93
	v_mul_f32_e32 v94, v18, v88
	v_mul_f32_e32 v95, v19, v88
	v_mul_f32_e32 v98, v16, v88
	v_mul_f32_e32 v99, v17, v88
	v_fmac_f32_e32 v83, v92, v92
	v_fmac_f32_e32 v85, v84, v84
	v_add_f32_e32 v83, v83, v85
	v_mul_f32_e32 v84, v99, v99
	v_mul_f32_e32 v85, v95, v95
	v_fmac_f32_e32 v84, v98, v98
	v_fmac_f32_e32 v85, v94, v94
	v_add_f32_e32 v84, v84, v85
	v_mul_f32_e32 v86, v86, v88
	v_mul_f32_e32 v87, v87, v88
	v_mul_f32_e32 v80, v80, v88
	v_mul_f32_e32 v81, v81, v88
	v_add_f32_e32 v89, v83, v84
	ds_bpermute_b32 v92, v198, v89
	v_cvt_pk_bf16_f32 v83, v86, v87
	v_cvt_pk_bf16_f32 v84, v80, v81
	v_lshlrev_b64 v[86:87], 10, v[182:183]
	v_lshl_add_u64 v[86:87], s[12:13], 0, v[86:87]
	s_waitcnt lgkmcnt(0)
	v_add_f32_e32 v80, v89, v92
	ds_bpermute_b32 v81, v199, v80
	v_lshl_add_u64 v[86:87], s[62:63], 1, v[86:87]
	v_lshl_add_u64 v[86:87], v[86:87], 0, v[160:161]
	v_cvt_pk_bf16_f32 v85, v90, v91
	global_store_dwordx4 v[86:87], v[82:85], off
	s_and_saveexec_b64 s[8:9], s[4:5]
	s_cbranch_execz .LBB0_1889
	s_waitcnt lgkmcnt(0)
	v_add_f32_e32 v80, v80, v81
	ds_write_b32 v201, v80 offset:2304
.LBB0_1889:
	s_or_b64 exec, exec, s[8:9]
	v_mov_b32_e32 v80, v133
	s_waitcnt lgkmcnt(0)
	v_mov_b32_e32 v81, v134
	v_mov_b32_e32 v133, v135
	v_mov_b32_e32 v82, v129
	v_mov_b32_e32 v83, v130
	v_mov_b32_e32 v129, v131
	v_add_f32_e32 v80, v80, v132
	v_add_f32_e32 v81, v81, v133
	v_add_f32_e32 v82, v82, v128
	v_add_f32_e32 v83, v83, v129
	v_mov_b32_e32 v85, v80
	v_mov_b32_e32 v84, v82
	v_mov_b32_e32 v80, v83
	v_add_f32_e32 v80, v84, v80
	v_add_f32_e32 v81, v85, v81
	s_nop 0
	v_pk_fma_f32 v[82:83], v[80:81], s[36:37], v[174:175] op_sel_hi:[1,0,0]
	s_nop 0
	v_mul_f32_e32 v80, 0x4b800000, v83
	v_cmp_gt_f32_e64 s[8:9], s87, v83
	v_cmp_gt_f32_e32 vcc, s87, v82
	s_nop 0
	v_cndmask_b32_e64 v80, v83, v80, s[8:9]
	v_rsq_f32_e32 v80, v80
	s_nop 0
	v_mul_f32_e32 v81, 0x45800000, v80
	v_cndmask_b32_e64 v80, v80, v81, s[8:9]
	v_mul_f32_e32 v76, v76, v80
	v_mul_f32_e32 v77, v77, v80
	v_mul_f32_e32 v84, v74, v80
	v_mul_f32_e32 v85, v75, v80
	v_cvt_pk_bf16_f32 v74, v76, v77
	v_mul_f32_e32 v76, v14, v80
	v_mul_f32_e32 v77, v15, v80
	v_mul_f32_e32 v86, v12, v80
	v_mul_f32_e32 v87, v13, v80
	v_mul_f32_e32 v77, v77, v77
	v_mul_f32_e32 v75, v87, v87
	v_mul_f32_e32 v90, v10, v80
	v_mul_f32_e32 v91, v11, v80
	v_mul_f32_e32 v92, v8, v80
	v_mul_f32_e32 v93, v9, v80
	v_fmac_f32_e32 v75, v86, v86
	v_fmac_f32_e32 v77, v76, v76
	v_add_f32_e32 v75, v75, v77
	v_mul_f32_e32 v76, v93, v93
	v_mul_f32_e32 v77, v91, v91
	v_fmac_f32_e32 v76, v92, v92
	v_fmac_f32_e32 v77, v90, v90
	v_add_f32_e32 v76, v76, v77
	v_mul_f32_e32 v78, v78, v80
	v_mul_f32_e32 v79, v79, v80
	v_mul_f32_e32 v72, v72, v80
	v_mul_f32_e32 v73, v73, v80
	v_add_f32_e32 v81, v75, v76
	ds_bpermute_b32 v83, v198, v81
	v_cvt_pk_bf16_f32 v75, v78, v79
	v_cvt_pk_bf16_f32 v76, v72, v73
	v_lshlrev_b64 v[78:79], 10, v[180:181]
	v_lshl_add_u64 v[78:79], s[12:13], 0, v[78:79]
	s_waitcnt lgkmcnt(0)
	v_add_f32_e32 v72, v81, v83
	ds_bpermute_b32 v73, v199, v72
	v_lshl_add_u64 v[78:79], s[62:63], 1, v[78:79]
	v_lshl_add_u64 v[78:79], v[78:79], 0, v[160:161]
	v_cvt_pk_bf16_f32 v77, v84, v85
	global_store_dwordx4 v[78:79], v[74:77], off
	s_and_saveexec_b64 s[8:9], s[4:5]
	s_cbranch_execz .LBB0_1891
	s_waitcnt lgkmcnt(0)
	v_add_f32_e32 v72, v72, v73
	ds_write_b32 v201, v72 offset:2560
.LBB0_1891:
	s_or_b64 exec, exec, s[8:9]
	v_mul_f32_e32 v72, 0x4b800000, v82
	v_cndmask_b32_e32 v72, v82, v72, vcc
	v_rsq_f32_e32 v72, v72
	s_waitcnt lgkmcnt(0)
	v_mul_f32_e32 v73, 0x45800000, v72
	v_cndmask_b32_e32 v76, v72, v73, vcc
	v_mul_f32_e32 v68, v68, v76
	v_mul_f32_e32 v69, v69, v76
	v_mul_f32_e32 v72, v66, v76
	v_mul_f32_e32 v73, v67, v76
	v_cvt_pk_bf16_f32 v66, v68, v69
	v_mul_f32_e32 v68, v6, v76
	v_mul_f32_e32 v69, v7, v76
	v_mul_f32_e32 v74, v4, v76
	v_mul_f32_e32 v75, v5, v76
	v_mul_f32_e32 v69, v69, v69
	v_mul_f32_e32 v67, v75, v75
	v_mul_f32_e32 v78, v2, v76
	v_mul_f32_e32 v79, v3, v76
	v_mul_f32_e32 v82, v0, v76
	v_mul_f32_e32 v83, v1, v76
	v_fmac_f32_e32 v67, v74, v74
	v_fmac_f32_e32 v69, v68, v68
	v_add_f32_e32 v67, v67, v69
	v_mul_f32_e32 v68, v83, v83
	v_mul_f32_e32 v69, v79, v79
	v_fmac_f32_e32 v68, v82, v82
	v_fmac_f32_e32 v69, v78, v78
	v_add_f32_e32 v68, v68, v69
	v_add_f32_e32 v74, v67, v68
	ds_bpermute_b32 v75, v198, v74
	v_mul_f32_e32 v64, v64, v76
	v_mul_f32_e32 v65, v65, v76
	v_mul_f32_e32 v70, v70, v76
	v_mul_f32_e32 v71, v71, v76
	s_nop 0
	v_cvt_pk_bf16_f32 v67, v70, v71
	v_cvt_pk_bf16_f32 v68, v64, v65
	s_waitcnt lgkmcnt(0)
	v_add_f32_e32 v64, v74, v75
	ds_bpermute_b32 v65, v199, v64
	v_lshlrev_b64 v[70:71], 10, v[178:179]
	v_lshl_add_u64 v[70:71], s[12:13], 0, v[70:71]
	v_lshl_add_u64 v[70:71], s[62:63], 1, v[70:71]
	v_lshl_add_u64 v[70:71], v[70:71], 0, v[160:161]
	v_cvt_pk_bf16_f32 v69, v72, v73
	global_store_dwordx4 v[70:71], v[66:69], off
	s_and_saveexec_b64 s[8:9], s[4:5]
	s_cbranch_execz .LBB0_1893
	s_waitcnt lgkmcnt(0)
	v_add_f32_e32 v64, v64, v65
	ds_write_b32 v201, v64 offset:2816
; #define LAS __attribute__((address_space(3)))
; __device__ __forceinline__ unsigned cvt_pk_bf16(float lo, float hi) { unsigned r; asm volatile("v_cvt_pk_bf16_f32 %0, %1, %2" : "=v"(r) : "v"(lo), "v"(hi)); return r; }
;     DI void operator()(const f32x4 (&acc)[2][2][4][2], const Unit& u, int wr, int wc, int fr, int fq) const {
;     ...
;         const f32x4 g0 = *(const f32x4*)(gk + cw), g1 = *(const f32x4*)(gk + cw + 4), gr = *(const f32x4*)(gk + 128 + wc * 16 + fq * 4);
;         asm volatile("s_waitcnt lgkmcnt(0)" ::: "memory"); __builtin_amdgcn_s_barrier(); asm volatile("" ::: "memory");
; #pragma unroll
;         for (int ai = 0; ai < 2; ++ai)
; #pragma unroll
;             for (int m = 0; m < 4; ++m) { const int row = row0 + ai * 128 + m * 16; const f32x4 pp = *(const LAS f32x4*)(part + (ai * 128 + wr * 64 + m * 16 + fr) * 4);
;                 const f32x2_ kr2 = *(const f32x2_*)(sskr2 + (size_t)row * 2);
;                 const float rstd = rsqrtf((((pp[0] + pp[1]) + (pp[2] + pp[3])) + (kr2[0] + kr2[1])) * (1.f / 192.f) + EPS), s = rs[ai][m] * rstd;
;                 const f32x4 v0 = acc[ai][0][m][0] * s * g0, v1 = acc[ai][0][m][1] * s * g1; u32x4 w;
;                 w.x = cvt_pk_bf16(v0[0], v0[1]); w.y = cvt_pk_bf16(v0[2], v0[3]); w.z = cvt_pk_bf16(v1[0], v1[1]); w.w = cvt_pk_bf16(v1[2], v1[3]);
;                 bf16_t* kp = KM + (size_t)row * 768 + h * 192;
;                 *(u32x4*)(kp + cw) = w;
;                 const f32x4 kr = *(const f32x4*)(KR + (size_t)row * 64 + wc * 16 + fq * 4) * rstd * gr; u32x2 r2; r2.x = cvt_pk_bf16(kr[0], kr[1]); r2.y = cvt_pk_bf16(kr[2], kr[3]);
;                 *(u32x2*)(kp + 128 + wc * 16 + fq * 4) = r2; }
.LBB0_1893:
	s_or_b64 exec, exec, s[8:9]
	global_load_dwordx4 v[68:71], v[164:165], off offset:16
	global_load_dwordx4 v[72:75], v[164:165], off
	s_waitcnt lgkmcnt(0)
	global_load_dwordx4 v[64:67], v[166:167], off offset:512
	s_waitcnt lgkmcnt(0)
	s_barrier
	v_lshl_add_u64 v[78:79], v[192:193], 3, s[24:25]
	global_load_dwordx2 v[86:87], v[78:79], off
	ds_read_b128 v[82:85], v200
	s_mul_i32 s0, s92, 0xc0
	v_mov_b64_e32 v[78:79], s[20:21]
	s_ashr_i32 s1, s0, 31
	v_mad_i64_i32 v[92:93], s[2:3], v192, s88, v[78:79]
	s_waitcnt lgkmcnt(0)
	v_add_f32_e32 v77, v84, v85
	v_mov_b32_e32 v84, v82
	s_lshl_b64 s[8:9], s[0:1], 1
	v_lshlrev_b64 v[90:91], 8, v[192:193]
	v_lshl_add_u64 v[90:91], v[162:163], 0, v[90:91]
	v_mov_b32_e32 v177, v161
	s_waitcnt vmcnt(0)
	v_mov_b32_e32 v85, v86
	v_mov_b32_e32 v86, v83
	v_add_f32_e32 v82, v84, v86
	v_add_f32_e32 v83, v85, v87
	s_nop 0
	v_add_f32_e32 v77, v82, v77
	v_add_f32_e32 v77, v77, v83
	v_fmamk_f32 v77, v77, 0x3baaaaab, v174
	v_mul_f32_e32 v81, 0x4b800000, v77
	v_cmp_gt_f32_e32 vcc, s87, v77
	v_lshl_add_u64 v[82:83], v[92:93], 0, s[8:9]
	v_lshl_add_u64 v[84:85], v[82:83], 0, v[160:161]
	v_cndmask_b32_e32 v77, v77, v81, vcc
	v_rsq_f32_e32 v77, v77
	s_nop 0
	v_mul_f32_e32 v81, 0x45800000, v77
	v_cndmask_b32_e32 v86, v77, v81, vcc
	v_mul_f32_e32 v92, v194, v86
	v_mul_f32_e32 v56, v56, v92
	v_mul_f32_e32 v57, v57, v92
	v_mul_f32_e32 v58, v58, v92
	v_mul_f32_e32 v59, v59, v92
	v_mul_f32_e32 v60, v60, v92
	v_mul_f32_e32 v61, v61, v92
	v_mul_f32_e32 v62, v62, v92
	v_mul_f32_e32 v63, v63, v92
	v_mul_f32_e32 v58, v74, v58
	v_mul_f32_e32 v59, v75, v59
	v_mul_f32_e32 v56, v72, v56
	v_mul_f32_e32 v57, v73, v57
	v_mul_f32_e32 v62, v70, v62
	v_mul_f32_e32 v63, v71, v63
	v_mul_f32_e32 v60, v68, v60
	v_mul_f32_e32 v61, v69, v61
	v_cvt_pk_bf16_f32 v56, v56, v57
	v_cvt_pk_bf16_f32 v57, v58, v59
	s_nop 0
	v_cvt_pk_bf16_f32 v58, v60, v61
	v_cvt_pk_bf16_f32 v59, v62, v63
	global_store_dwordx4 v[84:85], v[56:59], off
	global_load_dwordx4 v[56:59], v[90:91], off
	v_lshl_add_u64 v[62:63], v[82:83], 0, s[48:49]
	v_lshl_add_u64 v[62:63], v[62:63], 0, v[176:177]
	v_lshl_add_u64 v[60:61], v[190:191], 3, s[24:25]
	v_mad_i64_i32 v[82:83], s[0:1], v190, s88, v[78:79]
	s_waitcnt vmcnt(0)
	v_mul_f32_e32 v56, v56, v86
	v_mul_f32_e32 v57, v57, v86
	v_mul_f32_e32 v58, v58, v86
	v_mul_f32_e32 v59, v59, v86
	v_mul_f32_e32 v56, v64, v56
	v_mul_f32_e32 v57, v65, v57
	v_mul_f32_e32 v58, v66, v58
	v_mul_f32_e32 v59, v67, v59
	v_cvt_pk_bf16_f32 v56, v56, v57
	s_nop 0
	v_cvt_pk_bf16_f32 v57, v58, v59
	global_store_dwordx2 v[62:63], v[56:57], off offset:256
	global_load_dwordx2 v[60:61], v[60:61], off
	ds_read_b128 v[56:59], v200 offset:256
	v_lshlrev_b64 v[62:63], 8, v[190:191]
	s_waitcnt lgkmcnt(0)
	v_add_f32_e32 v77, v58, v59
	v_mov_b32_e32 v58, v56
	s_waitcnt vmcnt(0)
	v_mov_b32_e32 v59, v60
	v_mov_b32_e32 v60, v57
	v_add_f32_e32 v56, v58, v60
	v_add_f32_e32 v57, v59, v61
	v_lshl_add_u64 v[58:59], v[82:83], 0, s[8:9]
	v_add_f32_e32 v56, v56, v77
	v_add_f32_e32 v56, v56, v57
	v_fmamk_f32 v56, v56, 0x3baaaaab, v174
	v_mul_f32_e32 v57, 0x4b800000, v56
	v_cmp_gt_f32_e32 vcc, s87, v56
	v_lshl_add_u64 v[60:61], v[58:59], 0, v[160:161]
	s_nop 0
	v_cndmask_b32_e32 v56, v56, v57, vcc
	v_rsq_f32_e32 v77, v56
	v_lshl_add_u64 v[56:57], v[162:163], 0, v[62:63]
	v_mul_f32_e32 v62, 0x45800000, v77
	v_cndmask_b32_e32 v62, v77, v62, vcc
	v_mul_f32_e32 v82, v120, v62
	v_mul_f32_e32 v48, v48, v82
	v_mul_f32_e32 v49, v49, v82
	v_mul_f32_e32 v50, v50, v82
	v_mul_f32_e32 v51, v51, v82
	v_mul_f32_e32 v52, v52, v82
	v_mul_f32_e32 v53, v53, v82
	v_mul_f32_e32 v54, v54, v82
	v_mul_f32_e32 v55, v55, v82
	v_mul_f32_e32 v82, v70, v50
	v_mul_f32_e32 v83, v71, v51
	v_mul_f32_e32 v50, v68, v48
	v_mul_f32_e32 v51, v69, v49
	v_mul_f32_e32 v54, v74, v54
	v_mul_f32_e32 v55, v75, v55
	v_mul_f32_e32 v52, v72, v52
	v_mul_f32_e32 v53, v73, v53
	s_nop 0
	v_cvt_pk_bf16_f32 v48, v52, v53
	v_cvt_pk_bf16_f32 v49, v54, v55
	v_cvt_pk_bf16_f32 v50, v50, v51
	v_cvt_pk_bf16_f32 v51, v82, v83
	global_store_dwordx4 v[60:61], v[48:51], off
	global_load_dwordx4 v[48:51], v[56:57], off
	v_lshl_add_u64 v[54:55], v[58:59], 0, s[48:49]
	v_lshl_add_u64 v[54:55], v[54:55], 0, v[176:177]
	v_lshl_add_u64 v[52:53], v[188:189], 3, s[24:25]
	v_mad_i64_i32 v[56:57], s[0:1], v188, s88, v[78:79]
	s_waitcnt vmcnt(0)
	v_mul_f32_e32 v48, v48, v62
	v_mul_f32_e32 v49, v49, v62
	v_mul_f32_e32 v50, v50, v62
	v_mul_f32_e32 v51, v51, v62
	v_mul_f32_e32 v48, v64, v48
	v_mul_f32_e32 v49, v65, v49
	v_mul_f32_e32 v50, v66, v50
	v_mul_f32_e32 v51, v67, v51
	v_cvt_pk_bf16_f32 v48, v48, v49
	s_nop 0
	v_cvt_pk_bf16_f32 v49, v50, v51
	global_store_dwordx2 v[54:55], v[48:49], off offset:256
	global_load_dwordx2 v[52:53], v[52:53], off
	ds_read_b128 v[48:51], v200 offset:512
	v_lshlrev_b64 v[54:55], 8, v[188:189]
	s_waitcnt lgkmcnt(0)
	v_add_f32_e32 v58, v50, v51
	v_mov_b32_e32 v50, v48
	s_waitcnt vmcnt(0)
; #define LAS __attribute__((address_space(3)))
; __device__ __forceinline__ unsigned cvt_pk_bf16(float lo, float hi) { unsigned r; asm volatile("v_cvt_pk_bf16_f32 %0, %1, %2" : "=v"(r) : "v"(lo), "v"(hi)); return r; }
;     DI void operator()(const f32x4 (&acc)[2][2][4][2], const Unit& u, int wr, int wc, int fr, int fq) const {
;     ...
;         for (int ai = 0; ai < 2; ++ai)
; #pragma unroll
;             for (int m = 0; m < 4; ++m) { const int row = row0 + ai * 128 + m * 16; const f32x4 pp = *(const LAS f32x4*)(part + (ai * 128 + wr * 64 + m * 16 + fr) * 4);
;                 const f32x2_ kr2 = *(const f32x2_*)(sskr2 + (size_t)row * 2);
;                 const float rstd = rsqrtf((((pp[0] + pp[1]) + (pp[2] + pp[3])) + (kr2[0] + kr2[1])) * (1.f / 192.f) + EPS), s = rs[ai][m] * rstd;
;                 const f32x4 v0 = acc[ai][0][m][0] * s * g0, v1 = acc[ai][0][m][1] * s * g1; u32x4 w;
;                 w.x = cvt_pk_bf16(v0[0], v0[1]); w.y = cvt_pk_bf16(v0[2], v0[3]); w.z = cvt_pk_bf16(v1[0], v1[1]); w.w = cvt_pk_bf16(v1[2], v1[3]);
;                 bf16_t* kp = KM + (size_t)row * 768 + h * 192;
;                 *(u32x4*)(kp + cw) = w;
;                 const f32x4 kr = *(const f32x4*)(KR + (size_t)row * 64 + wc * 16 + fq * 4) * rstd * gr; u32x2 r2; r2.x = cvt_pk_bf16(kr[0], kr[1]); r2.y = cvt_pk_bf16(kr[2], kr[3]);
;                 *(u32x2*)(kp + 128 + wc * 16 + fq * 4) = r2; }
	v_mov_b32_e32 v51, v52
	v_mov_b32_e32 v52, v49
	v_add_f32_e32 v48, v50, v52
	v_add_f32_e32 v49, v51, v53
	v_lshl_add_u64 v[50:51], v[56:57], 0, s[8:9]
	v_add_f32_e32 v48, v48, v58
	v_add_f32_e32 v48, v48, v49
	v_fmamk_f32 v48, v48, 0x3baaaaab, v174
	v_mul_f32_e32 v49, 0x4b800000, v48
	v_cmp_gt_f32_e32 vcc, s87, v48
	v_lshl_add_u64 v[52:53], v[50:51], 0, v[160:161]
	s_nop 0
	v_cndmask_b32_e32 v48, v48, v49, vcc
	v_rsq_f32_e32 v58, v48
	v_lshl_add_u64 v[48:49], v[162:163], 0, v[54:55]
	v_mul_f32_e32 v54, 0x45800000, v58
	v_cndmask_b32_e32 v54, v58, v54, vcc
	v_mul_f32_e32 v56, v112, v54
	v_mul_f32_e32 v40, v40, v56
	v_mul_f32_e32 v41, v41, v56
	v_mul_f32_e32 v42, v42, v56
	v_mul_f32_e32 v43, v43, v56
	v_mul_f32_e32 v44, v44, v56
	v_mul_f32_e32 v45, v45, v56
	v_mul_f32_e32 v46, v46, v56
	v_mul_f32_e32 v47, v47, v56
	v_mul_f32_e32 v56, v70, v42
	v_mul_f32_e32 v57, v71, v43
	v_mul_f32_e32 v42, v68, v40
	v_mul_f32_e32 v43, v69, v41
	v_mul_f32_e32 v46, v74, v46
	v_mul_f32_e32 v47, v75, v47
	v_mul_f32_e32 v44, v72, v44
	v_mul_f32_e32 v45, v73, v45
	s_nop 0
	v_cvt_pk_bf16_f32 v40, v44, v45
	v_cvt_pk_bf16_f32 v41, v46, v47
	v_cvt_pk_bf16_f32 v42, v42, v43
	v_cvt_pk_bf16_f32 v43, v56, v57
	global_store_dwordx4 v[52:53], v[40:43], off
	global_load_dwordx4 v[40:43], v[48:49], off
	v_lshl_add_u64 v[46:47], v[50:51], 0, s[48:49]
	v_lshl_add_u64 v[46:47], v[46:47], 0, v[176:177]
	v_lshl_add_u64 v[44:45], v[186:187], 3, s[24:25]
	v_mad_i64_i32 v[48:49], s[0:1], v186, s88, v[78:79]
	s_waitcnt vmcnt(0)
	v_mul_f32_e32 v40, v40, v54
	v_mul_f32_e32 v41, v41, v54
	v_mul_f32_e32 v42, v42, v54
	v_mul_f32_e32 v43, v43, v54
	v_mul_f32_e32 v40, v64, v40
	v_mul_f32_e32 v41, v65, v41
	v_mul_f32_e32 v42, v66, v42
	v_mul_f32_e32 v43, v67, v43
	v_cvt_pk_bf16_f32 v40, v40, v41
	s_nop 0
	v_cvt_pk_bf16_f32 v41, v42, v43
	global_store_dwordx2 v[46:47], v[40:41], off offset:256
	global_load_dwordx2 v[44:45], v[44:45], off
	ds_read_b128 v[40:43], v200 offset:768
	v_lshlrev_b64 v[46:47], 8, v[186:187]
	s_waitcnt lgkmcnt(0)
	v_add_f32_e32 v50, v42, v43
	v_mov_b32_e32 v42, v40
	s_waitcnt vmcnt(0)
	v_mov_b32_e32 v43, v44
	v_mov_b32_e32 v44, v41
	v_add_f32_e32 v40, v42, v44
	v_add_f32_e32 v41, v43, v45
	v_lshl_add_u64 v[42:43], v[48:49], 0, s[8:9]
	v_add_f32_e32 v40, v40, v50
	v_add_f32_e32 v40, v40, v41
	v_fmamk_f32 v40, v40, 0x3baaaaab, v174
	v_mul_f32_e32 v41, 0x4b800000, v40
	v_cmp_gt_f32_e32 vcc, s87, v40
	v_lshl_add_u64 v[44:45], v[42:43], 0, v[160:161]
	s_nop 0
	v_cndmask_b32_e32 v40, v40, v41, vcc
	v_rsq_f32_e32 v50, v40
	v_lshl_add_u64 v[40:41], v[162:163], 0, v[46:47]
	v_mul_f32_e32 v46, 0x45800000, v50
	v_cndmask_b32_e32 v46, v50, v46, vcc
	v_mul_f32_e32 v48, v104, v46
	v_mul_f32_e32 v32, v32, v48
	v_mul_f32_e32 v33, v33, v48
	v_mul_f32_e32 v34, v34, v48
	v_mul_f32_e32 v35, v35, v48
	v_mul_f32_e32 v36, v36, v48
	v_mul_f32_e32 v37, v37, v48
	v_mul_f32_e32 v38, v38, v48
	v_mul_f32_e32 v39, v39, v48
	v_mul_f32_e32 v48, v70, v34
	v_mul_f32_e32 v49, v71, v35
	v_mul_f32_e32 v34, v68, v32
	v_mul_f32_e32 v35, v69, v33
	v_mul_f32_e32 v38, v74, v38
	v_mul_f32_e32 v39, v75, v39
	v_mul_f32_e32 v36, v72, v36
	v_mul_f32_e32 v37, v73, v37
	s_nop 0
	v_cvt_pk_bf16_f32 v32, v36, v37
	v_cvt_pk_bf16_f32 v33, v38, v39
	v_cvt_pk_bf16_f32 v34, v34, v35
	v_cvt_pk_bf16_f32 v35, v48, v49
	global_store_dwordx4 v[44:45], v[32:35], off
	global_load_dwordx4 v[32:35], v[40:41], off
	v_lshl_add_u64 v[38:39], v[42:43], 0, s[48:49]
	v_lshl_add_u64 v[38:39], v[38:39], 0, v[176:177]
	v_lshl_add_u64 v[36:37], v[184:185], 3, s[24:25]
	v_mad_i64_i32 v[40:41], s[0:1], v184, s88, v[78:79]
	s_waitcnt vmcnt(0)
	v_mul_f32_e32 v32, v32, v46
	v_mul_f32_e32 v33, v33, v46
	v_mul_f32_e32 v34, v34, v46
	v_mul_f32_e32 v35, v35, v46
	v_mul_f32_e32 v32, v64, v32
	v_mul_f32_e32 v33, v65, v33
	v_mul_f32_e32 v34, v66, v34
	v_mul_f32_e32 v35, v67, v35
	v_cvt_pk_bf16_f32 v32, v32, v33
	s_nop 0
	v_cvt_pk_bf16_f32 v33, v34, v35
	global_store_dwordx2 v[38:39], v[32:33], off offset:256
	global_load_dwordx2 v[36:37], v[36:37], off
	ds_read_b128 v[32:35], v200 offset:2048
	v_lshlrev_b64 v[38:39], 8, v[184:185]
	s_waitcnt lgkmcnt(0)
	v_add_f32_e32 v42, v34, v35
	v_mov_b32_e32 v34, v32
	s_waitcnt vmcnt(0)
	v_mov_b32_e32 v35, v36
	v_mov_b32_e32 v36, v33
	v_add_f32_e32 v32, v34, v36
	v_add_f32_e32 v33, v35, v37
	v_lshl_add_u64 v[34:35], v[40:41], 0, s[8:9]
	v_add_f32_e32 v32, v32, v42
	v_add_f32_e32 v32, v32, v33
	v_fmamk_f32 v32, v32, 0x3baaaaab, v174
	v_mul_f32_e32 v33, 0x4b800000, v32
	v_cmp_gt_f32_e32 vcc, s87, v32
	v_lshl_add_u64 v[36:37], v[34:35], 0, v[160:161]
	s_nop 0
	v_cndmask_b32_e32 v32, v32, v33, vcc
	v_rsq_f32_e32 v42, v32
	v_lshl_add_u64 v[32:33], v[162:163], 0, v[38:39]
	v_mul_f32_e32 v38, 0x45800000, v42
	v_cndmask_b32_e32 v38, v42, v38, vcc
	v_mul_f32_e32 v40, v96, v38
	v_mul_f32_e32 v24, v24, v40
	v_mul_f32_e32 v25, v25, v40
	v_mul_f32_e32 v26, v26, v40
	v_mul_f32_e32 v27, v27, v40
	v_mul_f32_e32 v28, v28, v40
	v_mul_f32_e32 v29, v29, v40
	v_mul_f32_e32 v30, v30, v40
	v_mul_f32_e32 v31, v31, v40
	v_mul_f32_e32 v40, v70, v26
	v_mul_f32_e32 v41, v71, v27
	v_mul_f32_e32 v26, v68, v24
	v_mul_f32_e32 v27, v69, v25
	v_mul_f32_e32 v30, v74, v30
	v_mul_f32_e32 v31, v75, v31
	v_mul_f32_e32 v28, v72, v28
	v_mul_f32_e32 v29, v73, v29
	s_nop 0
	v_cvt_pk_bf16_f32 v24, v28, v29
	v_cvt_pk_bf16_f32 v25, v30, v31
	v_cvt_pk_bf16_f32 v26, v26, v27
	v_cvt_pk_bf16_f32 v27, v40, v41
	global_store_dwordx4 v[36:37], v[24:27], off
	global_load_dwordx4 v[24:27], v[32:33], off
	v_lshl_add_u64 v[30:31], v[34:35], 0, s[48:49]
	v_lshl_add_u64 v[30:31], v[30:31], 0, v[176:177]
	v_lshl_add_u64 v[28:29], v[182:183], 3, s[24:25]
	v_mad_i64_i32 v[32:33], s[0:1], v182, s88, v[78:79]
	s_waitcnt vmcnt(0)
; #define LAS __attribute__((address_space(3)))
; __device__ __forceinline__ unsigned cvt_pk_bf16(float lo, float hi) { unsigned r; asm volatile("v_cvt_pk_bf16_f32 %0, %1, %2" : "=v"(r) : "v"(lo), "v"(hi)); return r; }
; #define PG8_BAR __builtin_amdgcn_s_barrier()
; template <class Epi, class Sched, bool ALIGN_EPI = false, bool SP2 = false>
; __device__ __forceinline__ void gemm_phase(PG8_LAS unsigned char* lds, const Gemm g, const Sched& S, const Epi& E, int wv) {
;     ...
;         cur = nxt; cA = nA; cB = nB; ++ui;
;         if constexpr (ALIGN_EPI) { if (wr == 1) PG8_BAR; }
;     DI void operator()(const f32x4 (&acc)[2][2][4][2], const Unit& u, int wr, int wc, int fr, int fq) const {
;     ...
;             for (int m = 0; m < 4; ++m) { const int row = row0 + ai * 128 + m * 16; const f32x4 pp = *(const LAS f32x4*)(part + (ai * 128 + wr * 64 + m * 16 + fr) * 4);
;                 const f32x2_ kr2 = *(const f32x2_*)(sskr2 + (size_t)row * 2);
;                 const float rstd = rsqrtf((((pp[0] + pp[1]) + (pp[2] + pp[3])) + (kr2[0] + kr2[1])) * (1.f / 192.f) + EPS), s = rs[ai][m] * rstd;
;                 const f32x4 v0 = acc[ai][0][m][0] * s * g0, v1 = acc[ai][0][m][1] * s * g1; u32x4 w;
;                 w.x = cvt_pk_bf16(v0[0], v0[1]); w.y = cvt_pk_bf16(v0[2], v0[3]); w.z = cvt_pk_bf16(v1[0], v1[1]); w.w = cvt_pk_bf16(v1[2], v1[3]);
;                 bf16_t* kp = KM + (size_t)row * 768 + h * 192;
;                 *(u32x4*)(kp + cw) = w;
;                 const f32x4 kr = *(const f32x4*)(KR + (size_t)row * 64 + wc * 16 + fq * 4) * rstd * gr; u32x2 r2; r2.x = cvt_pk_bf16(kr[0], kr[1]); r2.y = cvt_pk_bf16(kr[2], kr[3]);
;                 *(u32x2*)(kp + 128 + wc * 16 + fq * 4) = r2; }
	v_mul_f32_e32 v24, v24, v38
	v_mul_f32_e32 v25, v25, v38
	v_mul_f32_e32 v26, v26, v38
	v_mul_f32_e32 v27, v27, v38
	v_mul_f32_e32 v24, v64, v24
	v_mul_f32_e32 v25, v65, v25
	v_mul_f32_e32 v26, v66, v26
	v_mul_f32_e32 v27, v67, v27
	v_cvt_pk_bf16_f32 v24, v24, v25
	s_nop 0
	v_cvt_pk_bf16_f32 v25, v26, v27
	global_store_dwordx2 v[30:31], v[24:25], off offset:256
	global_load_dwordx2 v[28:29], v[28:29], off
	ds_read_b128 v[24:27], v200 offset:2304
	v_lshlrev_b64 v[30:31], 8, v[182:183]
	s_waitcnt lgkmcnt(0)
	v_add_f32_e32 v34, v26, v27
	v_mov_b32_e32 v26, v24
	s_waitcnt vmcnt(0)
	v_mov_b32_e32 v27, v28
	v_mov_b32_e32 v28, v25
	v_add_f32_e32 v24, v26, v28
	v_add_f32_e32 v25, v27, v29
	v_lshl_add_u64 v[26:27], v[32:33], 0, s[8:9]
	v_add_f32_e32 v24, v24, v34
	v_add_f32_e32 v24, v24, v25
	v_fmamk_f32 v24, v24, 0x3baaaaab, v174
	v_mul_f32_e32 v25, 0x4b800000, v24
	v_cmp_gt_f32_e32 vcc, s87, v24
	v_lshl_add_u64 v[28:29], v[26:27], 0, v[160:161]
	s_nop 0
	v_cndmask_b32_e32 v24, v24, v25, vcc
	v_rsq_f32_e32 v34, v24
	v_lshl_add_u64 v[24:25], v[162:163], 0, v[30:31]
	v_mul_f32_e32 v30, 0x45800000, v34
	v_cndmask_b32_e32 v30, v34, v30, vcc
	v_mul_f32_e32 v32, v88, v30
	v_mul_f32_e32 v16, v16, v32
	v_mul_f32_e32 v17, v17, v32
	v_mul_f32_e32 v18, v18, v32
	v_mul_f32_e32 v19, v19, v32
	v_mul_f32_e32 v20, v20, v32
	v_mul_f32_e32 v21, v21, v32
	v_mul_f32_e32 v22, v22, v32
	v_mul_f32_e32 v23, v23, v32
	v_mul_f32_e32 v32, v70, v18
	v_mul_f32_e32 v33, v71, v19
	v_mul_f32_e32 v18, v68, v16
	v_mul_f32_e32 v19, v69, v17
	v_mul_f32_e32 v22, v74, v22
	v_mul_f32_e32 v23, v75, v23
	v_mul_f32_e32 v20, v72, v20
	v_mul_f32_e32 v21, v73, v21
	s_nop 0
	v_cvt_pk_bf16_f32 v16, v20, v21
	v_cvt_pk_bf16_f32 v17, v22, v23
	v_cvt_pk_bf16_f32 v18, v18, v19
	v_cvt_pk_bf16_f32 v19, v32, v33
	global_store_dwordx4 v[28:29], v[16:19], off
	global_load_dwordx4 v[16:19], v[24:25], off
	v_lshl_add_u64 v[22:23], v[26:27], 0, s[48:49]
	v_lshl_add_u64 v[22:23], v[22:23], 0, v[176:177]
	v_lshl_add_u64 v[20:21], v[180:181], 3, s[24:25]
	v_mad_i64_i32 v[24:25], s[0:1], v180, s88, v[78:79]
	s_waitcnt vmcnt(0)
	v_mul_f32_e32 v16, v16, v30
	v_mul_f32_e32 v17, v17, v30
	v_mul_f32_e32 v18, v18, v30
	v_mul_f32_e32 v19, v19, v30
	v_mul_f32_e32 v16, v64, v16
	v_mul_f32_e32 v17, v65, v17
	v_mul_f32_e32 v18, v66, v18
	v_mul_f32_e32 v19, v67, v19
	v_cvt_pk_bf16_f32 v16, v16, v17
	s_nop 0
	v_cvt_pk_bf16_f32 v17, v18, v19
	global_store_dwordx2 v[22:23], v[16:17], off offset:256
	global_load_dwordx2 v[20:21], v[20:21], off
	ds_read_b128 v[16:19], v200 offset:2560
	v_lshlrev_b64 v[22:23], 8, v[180:181]
	s_waitcnt lgkmcnt(0)
	v_add_f32_e32 v26, v18, v19
	v_mov_b32_e32 v18, v16
	s_waitcnt vmcnt(0)
	v_mov_b32_e32 v19, v20
	v_mov_b32_e32 v20, v17
	v_add_f32_e32 v16, v18, v20
	v_add_f32_e32 v17, v19, v21
	v_lshl_add_u64 v[18:19], v[24:25], 0, s[8:9]
	v_add_f32_e32 v16, v16, v26
	v_add_f32_e32 v16, v16, v17
	v_fmamk_f32 v16, v16, 0x3baaaaab, v174
	v_mul_f32_e32 v17, 0x4b800000, v16
	v_cmp_gt_f32_e32 vcc, s87, v16
	v_lshl_add_u64 v[20:21], v[18:19], 0, v[160:161]
	s_nop 0
	v_cndmask_b32_e32 v16, v16, v17, vcc
	v_rsq_f32_e32 v26, v16
	v_lshl_add_u64 v[16:17], v[162:163], 0, v[22:23]
	v_mul_f32_e32 v22, 0x45800000, v26
	v_cndmask_b32_e32 v22, v26, v22, vcc
	v_mul_f32_e32 v24, v80, v22
	v_mul_f32_e32 v8, v8, v24
	v_mul_f32_e32 v9, v9, v24
	v_mul_f32_e32 v10, v10, v24
	v_mul_f32_e32 v11, v11, v24
	v_mul_f32_e32 v12, v12, v24
	v_mul_f32_e32 v13, v13, v24
	v_mul_f32_e32 v14, v14, v24
	v_mul_f32_e32 v15, v15, v24
	v_mul_f32_e32 v24, v70, v10
	v_mul_f32_e32 v25, v71, v11
	v_mul_f32_e32 v10, v68, v8
	v_mul_f32_e32 v11, v69, v9
	v_mul_f32_e32 v14, v74, v14
	v_mul_f32_e32 v15, v75, v15
	v_mul_f32_e32 v12, v72, v12
	v_mul_f32_e32 v13, v73, v13
	s_nop 0
	v_cvt_pk_bf16_f32 v8, v12, v13
	v_cvt_pk_bf16_f32 v9, v14, v15
	v_cvt_pk_bf16_f32 v10, v10, v11
	v_cvt_pk_bf16_f32 v11, v24, v25
	global_store_dwordx4 v[20:21], v[8:11], off
	global_load_dwordx4 v[8:11], v[16:17], off
	v_lshl_add_u64 v[14:15], v[18:19], 0, s[48:49]
	v_lshl_add_u64 v[14:15], v[14:15], 0, v[176:177]
	v_lshl_add_u64 v[12:13], v[178:179], 3, s[24:25]
	v_mad_i64_i32 v[16:17], s[0:1], v178, s88, v[78:79]
	s_waitcnt vmcnt(0)
	v_mul_f32_e32 v8, v8, v22
	v_mul_f32_e32 v9, v9, v22
	v_mul_f32_e32 v10, v10, v22
	v_mul_f32_e32 v11, v11, v22
	v_mul_f32_e32 v8, v64, v8
	v_mul_f32_e32 v9, v65, v9
	v_mul_f32_e32 v10, v66, v10
	v_mul_f32_e32 v11, v67, v11
	v_cvt_pk_bf16_f32 v8, v8, v9
	s_nop 0
	v_cvt_pk_bf16_f32 v9, v10, v11
	global_store_dwordx2 v[14:15], v[8:9], off offset:256
	global_load_dwordx2 v[12:13], v[12:13], off
	ds_read_b128 v[8:11], v200 offset:2816
	v_lshlrev_b64 v[14:15], 8, v[178:179]
	s_waitcnt lgkmcnt(0)
	v_add_f32_e32 v18, v10, v11
	v_mov_b32_e32 v10, v8
	s_waitcnt vmcnt(0)
	v_mov_b32_e32 v11, v12
	v_mov_b32_e32 v12, v9
	v_add_f32_e32 v8, v10, v12
	v_add_f32_e32 v9, v11, v13
	v_lshl_add_u64 v[10:11], v[16:17], 0, s[8:9]
	v_add_f32_e32 v8, v8, v18
	v_add_f32_e32 v8, v8, v9
	v_fmamk_f32 v8, v8, 0x3baaaaab, v174
	v_mul_f32_e32 v9, 0x4b800000, v8
	v_cmp_gt_f32_e32 vcc, s87, v8
	v_lshl_add_u64 v[12:13], v[10:11], 0, v[160:161]
	s_nop 0
	v_cndmask_b32_e32 v8, v8, v9, vcc
	v_rsq_f32_e32 v18, v8
	v_lshl_add_u64 v[8:9], v[162:163], 0, v[14:15]
	v_mul_f32_e32 v14, 0x45800000, v18
	v_cndmask_b32_e32 v14, v18, v14, vcc
	v_mul_f32_e32 v16, v76, v14
	v_mul_f32_e32 v0, v0, v16
	v_mul_f32_e32 v1, v1, v16
	v_mul_f32_e32 v2, v2, v16
	v_mul_f32_e32 v3, v3, v16
	v_mul_f32_e32 v4, v4, v16
	v_mul_f32_e32 v5, v5, v16
	v_mul_f32_e32 v6, v6, v16
	v_mul_f32_e32 v7, v7, v16
	v_mul_f32_e32 v16, v70, v2
	v_mul_f32_e32 v17, v71, v3
	v_mul_f32_e32 v2, v68, v0
	v_mul_f32_e32 v3, v69, v1
	v_mul_f32_e32 v6, v74, v6
	v_mul_f32_e32 v7, v75, v7
	v_mul_f32_e32 v4, v72, v4
	v_mul_f32_e32 v5, v73, v5
	s_and_b64 vcc, exec, s[6:7]
	v_cvt_pk_bf16_f32 v0, v4, v5
	v_cvt_pk_bf16_f32 v1, v6, v7
	v_cvt_pk_bf16_f32 v2, v2, v3
	v_cvt_pk_bf16_f32 v3, v16, v17
	global_store_dwordx4 v[12:13], v[0:3], off
	global_load_dwordx4 v[0:3], v[8:9], off
	v_lshl_add_u64 v[4:5], v[10:11], 0, s[48:49]
	v_lshl_add_u64 v[4:5], v[4:5], 0, v[176:177]
	s_mov_b64 s[6:7], -1
	s_waitcnt vmcnt(0)
	v_mul_f32_e32 v0, v0, v14
	v_mul_f32_e32 v1, v1, v14
	v_mul_f32_e32 v2, v2, v14
	v_mul_f32_e32 v3, v3, v14
	v_mul_f32_e32 v0, v64, v0
	v_mul_f32_e32 v1, v65, v1
	v_mul_f32_e32 v2, v66, v2
	v_mul_f32_e32 v3, v67, v3
	v_cvt_pk_bf16_f32 v0, v0, v1
	s_nop 0
	v_cvt_pk_bf16_f32 v1, v2, v3
	global_store_dwordx2 v[4:5], v[0:1], off offset:256
	s_cbranch_vccnz .LBB0_1865
	s_andn2_b64 vcc, exec, s[52:53]
	s_cbranch_vccnz .LBB0_1864
	s_barrier
	s_branch .LBB0_1864

; __device__ __forceinline__ unsigned cvt_pk_bf16(float lo, float hi) { unsigned r; asm volatile("v_cvt_pk_bf16_f32 %0, %1, %2" : "=v"(r) : "v"(lo), "v"(hi)); return r; }
; DI float shx(float v, int mask, int lane) { return __int_as_float(__builtin_amdgcn_ds_bpermute((lane ^ mask) << 2, __float_as_int(v))); }
;     DI void operator()(const f32x4 (&acc)[2][2][4][2], const Unit& u, int wr, int wc, int fr, int fq) const {
;     ...
;             for (int m = 0; m < 4; ++m) { const int row = row0 + ai * 128 + m * 16; const size_t off = (size_t)row * 1024 + col0; float ss = 0.f;
; #pragma unroll
;                 for (int bj = 0; bj < 2; ++bj) { const size_t o = off + bj * 128; const u32x4 r_ = *(const u32x4*)(x1b + o); f32x4 v0, v1;
;                     v0[0] = __uint_as_float(r_.x << 16); v0[1] = __uint_as_float(r_.x & 0xffff0000u); v0[2] = __uint_as_float(r_.y << 16); v0[3] = __uint_as_float(r_.y & 0xffff0000u);
;                     v1[0] = __uint_as_float(r_.z << 16); v1[1] = __uint_as_float(r_.z & 0xffff0000u); v1[2] = __uint_as_float(r_.w << 16); v1[3] = __uint_as_float(r_.w & 0xffff0000u);
;                     v0 = v0 + acc[ai][bj][m][0]; v1 = v1 + acc[ai][bj][m][1];
;                     ss += ((v0[0] * v0[0] + v0[1] * v0[1]) + (v0[2] * v0[2] + v0[3] * v0[3])) + ((v1[0] * v1[0] + v1[1] * v1[1]) + (v1[2] * v1[2] + v1[3] * v1[3]));
;                     u32x4 w; w.x = cvt_pk_bf16(v0[0], v0[1]); w.y = cvt_pk_bf16(v0[2], v0[3]); w.z = cvt_pk_bf16(v1[0], v1[1]); w.w = cvt_pk_bf16(v1[2], v1[3]); *(u32x4*)(x1b + o) = w; }
;                 { const int ln_ = fq * 16 + fr; ss += shx(ss, 16, ln_); ss += shx(ss, 32, ln_); }
;                 if (fq == 0) unsafeAtomicAdd(ssum2 + row, ss); }
.LBB0_2019:
	v_lshl_add_u32 v146, s28, 8, v148
	v_ashrrev_i32_e32 v147, 31, v146
	v_lshl_or_b32 v144, s36, 8, v152
	v_lshlrev_b64 v[156:157], 11, v[146:147]
	v_ashrrev_i32_e32 v145, 31, v144
	v_lshl_add_u64 v[156:157], s[34:35], 0, v[156:157]
	v_lshl_add_u64 v[160:161], v[144:145], 1, v[156:157]
	global_load_dwordx4 v[156:159], v[160:161], off
	s_waitcnt vmcnt(0)
	v_lshlrev_b32_e32 v162, 16, v156
	v_and_b32_e32 v163, 0xffff0000, v156
	v_lshlrev_b32_e32 v156, 16, v157
	v_and_b32_e32 v157, 0xffff0000, v157
	v_lshlrev_b32_e32 v164, 16, v158
	v_and_b32_e32 v165, 0xffff0000, v158
	v_lshlrev_b32_e32 v158, 16, v159
	v_and_b32_e32 v159, 0xffff0000, v159
	v_add_f32_e32 v156, v126, v156
	v_add_f32_e32 v157, v127, v157
	v_add_f32_e32 v162, v124, v162
	v_add_f32_e32 v163, v125, v163
	v_add_f32_e32 v158, v122, v158
	v_add_f32_e32 v159, v123, v159
	v_add_f32_e32 v164, v120, v164
	v_add_f32_e32 v165, v121, v165
	v_cvt_pk_bf16_f32 v120, v162, v163
	v_cvt_pk_bf16_f32 v121, v156, v157
	v_mul_f32_e32 v163, v163, v163
	v_cvt_pk_bf16_f32 v122, v164, v165
	v_cvt_pk_bf16_f32 v123, v158, v159
	global_load_dwordx4 v[124:127], v[160:161], off offset:256
	v_mul_f32_e32 v157, v157, v157
	v_mul_f32_e32 v165, v165, v165
	v_mul_f32_e32 v159, v159, v159
	v_fmac_f32_e32 v163, v162, v162
	v_fmac_f32_e32 v157, v156, v156
	v_fmac_f32_e32 v165, v164, v164
	v_fmac_f32_e32 v159, v158, v158
	v_add_f32_e32 v156, v163, v157
	v_add_f32_e32 v157, v165, v159
	v_add_f32_e32 v162, v156, v157
	global_store_dwordx4 v[160:161], v[120:123], off
	s_waitcnt vmcnt(1)
	v_lshlrev_b32_e32 v156, 16, v124
	v_and_b32_e32 v157, 0xffff0000, v124
	v_lshlrev_b32_e32 v124, 16, v125
	v_and_b32_e32 v125, 0xffff0000, v125
	v_lshlrev_b32_e32 v158, 16, v126
	v_and_b32_e32 v159, 0xffff0000, v126
	v_lshlrev_b32_e32 v126, 16, v127
	v_and_b32_e32 v127, 0xffff0000, v127
	v_add_f32_e32 v118, v118, v124
	v_add_f32_e32 v119, v119, v125
	v_add_f32_e32 v116, v116, v156
	v_add_f32_e32 v117, v117, v157
	v_add_f32_e32 v124, v114, v126
	v_add_f32_e32 v125, v115, v127
	v_add_f32_e32 v126, v112, v158
	v_add_f32_e32 v127, v113, v159
	v_mul_f32_e32 v112, v117, v117
	v_mul_f32_e32 v113, v119, v119
	v_mul_f32_e32 v114, v127, v127
	v_mul_f32_e32 v115, v125, v125
	v_fmac_f32_e32 v112, v116, v116
	v_fmac_f32_e32 v113, v118, v118
	v_fmac_f32_e32 v114, v126, v126
	v_fmac_f32_e32 v115, v124, v124
	v_add_f32_e32 v112, v112, v113
	v_add_f32_e32 v113, v114, v115
	v_add_f32_e32 v112, v112, v113
	v_add_f32_e32 v112, v162, v112
	ds_bpermute_b32 v113, v150, v112
	v_cvt_pk_bf16_f32 v114, v116, v117
	v_cvt_pk_bf16_f32 v115, v118, v119
	v_cvt_pk_bf16_f32 v116, v126, v127
	v_cvt_pk_bf16_f32 v117, v124, v125
	s_waitcnt lgkmcnt(0)
	v_add_f32_e32 v112, v112, v113
	ds_bpermute_b32 v113, v151, v112
	global_store_dwordx4 v[160:161], v[114:117], off offset:256
	s_and_saveexec_b64 s[28:29], s[4:5]
	s_cbranch_execz .LBB0_2021
	s_waitcnt lgkmcnt(0)
	v_add_f32_e32 v114, v112, v113
	v_lshl_add_u64 v[112:113], v[146:147], 2, s[16:17]
	global_atomic_add_f32 v[112:113], v114, off
.LBB0_2021:
	s_or_b64 exec, exec, s[28:29]
	v_or_b32_e32 v112, 16, v146
	s_waitcnt lgkmcnt(0)
	v_ashrrev_i32_e32 v113, 31, v112
	v_lshlrev_b64 v[114:115], 11, v[112:113]
	v_lshl_add_u64 v[114:115], s[34:35], 0, v[114:115]
	v_lshl_add_u64 v[118:119], v[144:145], 1, v[114:115]
	global_load_dwordx4 v[114:117], v[118:119], off
	s_waitcnt vmcnt(0)
	v_lshlrev_b32_e32 v120, 16, v114
	v_and_b32_e32 v121, 0xffff0000, v114
	v_lshlrev_b32_e32 v114, 16, v115
	v_and_b32_e32 v115, 0xffff0000, v115
	v_lshlrev_b32_e32 v122, 16, v116
	v_and_b32_e32 v123, 0xffff0000, v116
	v_lshlrev_b32_e32 v116, 16, v117
	v_and_b32_e32 v117, 0xffff0000, v117
	v_add_f32_e32 v114, v110, v114
	v_add_f32_e32 v115, v111, v115
	v_add_f32_e32 v120, v108, v120
	v_add_f32_e32 v121, v109, v121
	v_add_f32_e32 v116, v106, v116
	v_add_f32_e32 v117, v107, v117
	v_add_f32_e32 v122, v104, v122
	v_add_f32_e32 v123, v105, v123
	v_cvt_pk_bf16_f32 v104, v120, v121
	v_cvt_pk_bf16_f32 v105, v114, v115
	v_mul_f32_e32 v121, v121, v121
	v_cvt_pk_bf16_f32 v106, v122, v123
	v_cvt_pk_bf16_f32 v107, v116, v117
	global_load_dwordx4 v[108:111], v[118:119], off offset:256
	v_mul_f32_e32 v115, v115, v115
	v_mul_f32_e32 v123, v123, v123
	v_mul_f32_e32 v117, v117, v117
	v_fmac_f32_e32 v121, v120, v120
	v_fmac_f32_e32 v115, v114, v114
	v_fmac_f32_e32 v123, v122, v122
	v_fmac_f32_e32 v117, v116, v116
	v_add_f32_e32 v114, v121, v115
	v_add_f32_e32 v115, v123, v117
	v_add_f32_e32 v120, v114, v115
	global_store_dwordx4 v[118:119], v[104:107], off
	s_waitcnt vmcnt(1)
	v_lshlrev_b32_e32 v114, 16, v108
	v_and_b32_e32 v115, 0xffff0000, v108
	v_lshlrev_b32_e32 v108, 16, v109
	v_and_b32_e32 v109, 0xffff0000, v109
	v_lshlrev_b32_e32 v116, 16, v110
	v_and_b32_e32 v117, 0xffff0000, v110
	v_lshlrev_b32_e32 v110, 16, v111
	v_and_b32_e32 v111, 0xffff0000, v111
	v_add_f32_e32 v102, v102, v108
	v_add_f32_e32 v103, v103, v109
	v_add_f32_e32 v100, v100, v114
	v_add_f32_e32 v101, v101, v115
	v_add_f32_e32 v108, v98, v110
	v_add_f32_e32 v109, v99, v111
	v_add_f32_e32 v110, v96, v116
	v_add_f32_e32 v111, v97, v117
	v_mul_f32_e32 v96, v101, v101
	v_mul_f32_e32 v97, v103, v103
	v_mul_f32_e32 v98, v111, v111
	v_mul_f32_e32 v99, v109, v109
	v_fmac_f32_e32 v96, v100, v100
	v_fmac_f32_e32 v97, v102, v102
	v_fmac_f32_e32 v98, v110, v110
	v_fmac_f32_e32 v99, v108, v108
	v_add_f32_e32 v96, v96, v97
	v_add_f32_e32 v97, v98, v99
	v_add_f32_e32 v96, v96, v97
	v_add_f32_e32 v96, v120, v96
	ds_bpermute_b32 v97, v150, v96
	v_cvt_pk_bf16_f32 v98, v100, v101
	v_cvt_pk_bf16_f32 v99, v102, v103
	v_cvt_pk_bf16_f32 v100, v110, v111
	v_cvt_pk_bf16_f32 v101, v108, v109
	s_waitcnt lgkmcnt(0)
	v_add_f32_e32 v96, v96, v97
	ds_bpermute_b32 v97, v151, v96
	global_store_dwordx4 v[118:119], v[98:101], off offset:256
	s_and_saveexec_b64 s[28:29], s[4:5]
	s_cbranch_execz .LBB0_2023
	s_waitcnt lgkmcnt(0)
	v_add_f32_e32 v98, v96, v97
	v_lshl_add_u64 v[96:97], v[112:113], 2, s[16:17]
	global_atomic_add_f32 v[96:97], v98, off
; __device__ __forceinline__ unsigned cvt_pk_bf16(float lo, float hi) { unsigned r; asm volatile("v_cvt_pk_bf16_f32 %0, %1, %2" : "=v"(r) : "v"(lo), "v"(hi)); return r; }
; DI float shx(float v, int mask, int lane) { return __int_as_float(__builtin_amdgcn_ds_bpermute((lane ^ mask) << 2, __float_as_int(v))); }
;     DI void operator()(const f32x4 (&acc)[2][2][4][2], const Unit& u, int wr, int wc, int fr, int fq) const {
;     ...
;             for (int m = 0; m < 4; ++m) { const int row = row0 + ai * 128 + m * 16; const size_t off = (size_t)row * 1024 + col0; float ss = 0.f;
; #pragma unroll
;                 for (int bj = 0; bj < 2; ++bj) { const size_t o = off + bj * 128; const u32x4 r_ = *(const u32x4*)(x1b + o); f32x4 v0, v1;
;                     v0[0] = __uint_as_float(r_.x << 16); v0[1] = __uint_as_float(r_.x & 0xffff0000u); v0[2] = __uint_as_float(r_.y << 16); v0[3] = __uint_as_float(r_.y & 0xffff0000u);
;                     v1[0] = __uint_as_float(r_.z << 16); v1[1] = __uint_as_float(r_.z & 0xffff0000u); v1[2] = __uint_as_float(r_.w << 16); v1[3] = __uint_as_float(r_.w & 0xffff0000u);
;                     v0 = v0 + acc[ai][bj][m][0]; v1 = v1 + acc[ai][bj][m][1];
;                     ss += ((v0[0] * v0[0] + v0[1] * v0[1]) + (v0[2] * v0[2] + v0[3] * v0[3])) + ((v1[0] * v1[0] + v1[1] * v1[1]) + (v1[2] * v1[2] + v1[3] * v1[3]));
;                     u32x4 w; w.x = cvt_pk_bf16(v0[0], v0[1]); w.y = cvt_pk_bf16(v0[2], v0[3]); w.z = cvt_pk_bf16(v1[0], v1[1]); w.w = cvt_pk_bf16(v1[2], v1[3]); *(u32x4*)(x1b + o) = w; }
;                 { const int ln_ = fq * 16 + fr; ss += shx(ss, 16, ln_); ss += shx(ss, 32, ln_); }
;                 if (fq == 0) unsafeAtomicAdd(ssum2 + row, ss); }
.LBB0_2023:
	s_or_b64 exec, exec, s[28:29]
	v_or_b32_e32 v96, 32, v146
	s_waitcnt lgkmcnt(0)
	v_ashrrev_i32_e32 v97, 31, v96
	v_lshlrev_b64 v[98:99], 11, v[96:97]
	v_lshl_add_u64 v[98:99], s[34:35], 0, v[98:99]
	v_lshl_add_u64 v[102:103], v[144:145], 1, v[98:99]
	global_load_dwordx4 v[98:101], v[102:103], off
	s_waitcnt vmcnt(0)
	v_lshlrev_b32_e32 v104, 16, v98
	v_and_b32_e32 v105, 0xffff0000, v98
	v_lshlrev_b32_e32 v98, 16, v99
	v_and_b32_e32 v99, 0xffff0000, v99
	v_lshlrev_b32_e32 v106, 16, v100
	v_and_b32_e32 v107, 0xffff0000, v100
	v_lshlrev_b32_e32 v100, 16, v101
	v_and_b32_e32 v101, 0xffff0000, v101
	v_add_f32_e32 v98, v94, v98
	v_add_f32_e32 v99, v95, v99
	v_add_f32_e32 v104, v92, v104
	v_add_f32_e32 v105, v93, v105
	v_add_f32_e32 v100, v90, v100
	v_add_f32_e32 v101, v91, v101
	v_add_f32_e32 v106, v88, v106
	v_add_f32_e32 v107, v89, v107
	v_cvt_pk_bf16_f32 v88, v104, v105
	v_cvt_pk_bf16_f32 v89, v98, v99
	v_mul_f32_e32 v105, v105, v105
	v_cvt_pk_bf16_f32 v90, v106, v107
	v_cvt_pk_bf16_f32 v91, v100, v101
	global_load_dwordx4 v[92:95], v[102:103], off offset:256
	v_mul_f32_e32 v99, v99, v99
	v_mul_f32_e32 v107, v107, v107
	v_mul_f32_e32 v101, v101, v101
	v_fmac_f32_e32 v105, v104, v104
	v_fmac_f32_e32 v99, v98, v98
	v_fmac_f32_e32 v107, v106, v106
	v_fmac_f32_e32 v101, v100, v100
	v_add_f32_e32 v98, v105, v99
	v_add_f32_e32 v99, v107, v101
	v_add_f32_e32 v104, v98, v99
	global_store_dwordx4 v[102:103], v[88:91], off
	s_waitcnt vmcnt(1)
	v_lshlrev_b32_e32 v98, 16, v92
	v_and_b32_e32 v99, 0xffff0000, v92
	v_lshlrev_b32_e32 v92, 16, v93
	v_and_b32_e32 v93, 0xffff0000, v93
	v_lshlrev_b32_e32 v100, 16, v94
	v_and_b32_e32 v101, 0xffff0000, v94
	v_lshlrev_b32_e32 v94, 16, v95
	v_and_b32_e32 v95, 0xffff0000, v95
	v_add_f32_e32 v86, v86, v92
	v_add_f32_e32 v87, v87, v93
	v_add_f32_e32 v84, v84, v98
	v_add_f32_e32 v85, v85, v99
	v_add_f32_e32 v92, v82, v94
	v_add_f32_e32 v93, v83, v95
	v_add_f32_e32 v94, v80, v100
	v_add_f32_e32 v95, v81, v101
	v_mul_f32_e32 v80, v85, v85
	v_mul_f32_e32 v81, v87, v87
	v_mul_f32_e32 v82, v95, v95
	v_mul_f32_e32 v83, v93, v93
	v_fmac_f32_e32 v80, v84, v84
	v_fmac_f32_e32 v81, v86, v86
	v_fmac_f32_e32 v82, v94, v94
	v_fmac_f32_e32 v83, v92, v92
	v_add_f32_e32 v80, v80, v81
	v_add_f32_e32 v81, v82, v83
	v_add_f32_e32 v80, v80, v81
	v_add_f32_e32 v80, v104, v80
	ds_bpermute_b32 v81, v150, v80
	v_cvt_pk_bf16_f32 v82, v84, v85
	v_cvt_pk_bf16_f32 v83, v86, v87
	v_cvt_pk_bf16_f32 v84, v94, v95
	v_cvt_pk_bf16_f32 v85, v92, v93
	s_waitcnt lgkmcnt(0)
	v_add_f32_e32 v80, v80, v81
	ds_bpermute_b32 v81, v151, v80
	global_store_dwordx4 v[102:103], v[82:85], off offset:256
	s_and_saveexec_b64 s[28:29], s[4:5]
	s_cbranch_execz .LBB0_2025
	s_waitcnt lgkmcnt(0)
	v_add_f32_e32 v82, v80, v81
	v_lshl_add_u64 v[80:81], v[96:97], 2, s[16:17]
	global_atomic_add_f32 v[80:81], v82, off
.LBB0_2025:
	s_or_b64 exec, exec, s[28:29]
	v_or_b32_e32 v80, 48, v146
	s_waitcnt lgkmcnt(0)
	v_ashrrev_i32_e32 v81, 31, v80
	v_lshlrev_b64 v[82:83], 11, v[80:81]
	v_lshl_add_u64 v[82:83], s[34:35], 0, v[82:83]
	v_lshl_add_u64 v[86:87], v[144:145], 1, v[82:83]
	global_load_dwordx4 v[82:85], v[86:87], off
	s_waitcnt vmcnt(0)
	v_lshlrev_b32_e32 v88, 16, v82
	v_and_b32_e32 v89, 0xffff0000, v82
	v_lshlrev_b32_e32 v82, 16, v83
	v_and_b32_e32 v83, 0xffff0000, v83
	v_lshlrev_b32_e32 v90, 16, v84
	v_and_b32_e32 v91, 0xffff0000, v84
	v_lshlrev_b32_e32 v84, 16, v85
	v_and_b32_e32 v85, 0xffff0000, v85
	v_add_f32_e32 v82, v78, v82
	v_add_f32_e32 v83, v79, v83
	v_add_f32_e32 v88, v76, v88
	v_add_f32_e32 v89, v77, v89
	v_add_f32_e32 v84, v74, v84
	v_add_f32_e32 v85, v75, v85
	v_add_f32_e32 v90, v72, v90
	v_add_f32_e32 v91, v73, v91
	v_cvt_pk_bf16_f32 v72, v88, v89
	v_cvt_pk_bf16_f32 v73, v82, v83
	v_mul_f32_e32 v89, v89, v89
	v_cvt_pk_bf16_f32 v74, v90, v91
	v_cvt_pk_bf16_f32 v75, v84, v85
	global_load_dwordx4 v[76:79], v[86:87], off offset:256
	v_mul_f32_e32 v83, v83, v83
	v_mul_f32_e32 v91, v91, v91
	v_mul_f32_e32 v85, v85, v85
	v_fmac_f32_e32 v89, v88, v88
	v_fmac_f32_e32 v83, v82, v82
	v_fmac_f32_e32 v91, v90, v90
	v_fmac_f32_e32 v85, v84, v84
	v_add_f32_e32 v82, v89, v83
	v_add_f32_e32 v83, v91, v85
	v_add_f32_e32 v88, v82, v83
	global_store_dwordx4 v[86:87], v[72:75], off
	s_waitcnt vmcnt(1)
	v_lshlrev_b32_e32 v82, 16, v76
	v_and_b32_e32 v83, 0xffff0000, v76
	v_lshlrev_b32_e32 v76, 16, v77
	v_and_b32_e32 v77, 0xffff0000, v77
	v_lshlrev_b32_e32 v84, 16, v78
	v_and_b32_e32 v85, 0xffff0000, v78
	v_lshlrev_b32_e32 v78, 16, v79
	v_and_b32_e32 v79, 0xffff0000, v79
	v_add_f32_e32 v70, v70, v76
	v_add_f32_e32 v71, v71, v77
	v_add_f32_e32 v68, v68, v82
	v_add_f32_e32 v69, v69, v83
	v_add_f32_e32 v76, v66, v78
	v_add_f32_e32 v77, v67, v79
	v_add_f32_e32 v78, v64, v84
	v_add_f32_e32 v79, v65, v85
	v_mul_f32_e32 v64, v69, v69
	v_mul_f32_e32 v65, v71, v71
	v_mul_f32_e32 v66, v79, v79
	v_mul_f32_e32 v67, v77, v77
	v_fmac_f32_e32 v64, v68, v68
	v_fmac_f32_e32 v65, v70, v70
	v_fmac_f32_e32 v66, v78, v78
	v_fmac_f32_e32 v67, v76, v76
	v_add_f32_e32 v64, v64, v65
	v_add_f32_e32 v65, v66, v67
	v_add_f32_e32 v64, v64, v65
	v_add_f32_e32 v64, v88, v64
	ds_bpermute_b32 v65, v150, v64
	v_cvt_pk_bf16_f32 v66, v68, v69
	v_cvt_pk_bf16_f32 v67, v70, v71
	v_cvt_pk_bf16_f32 v68, v78, v79
	v_cvt_pk_bf16_f32 v69, v76, v77
	s_waitcnt lgkmcnt(0)
	v_add_f32_e32 v64, v64, v65
	ds_bpermute_b32 v65, v151, v64
	global_store_dwordx4 v[86:87], v[66:69], off offset:256
	s_and_saveexec_b64 s[28:29], s[4:5]
	s_cbranch_execz .LBB0_2027
	s_waitcnt lgkmcnt(0)
	v_add_f32_e32 v66, v64, v65
	v_lshl_add_u64 v[64:65], v[80:81], 2, s[16:17]
	global_atomic_add_f32 v[64:65], v66, off
; __device__ __forceinline__ unsigned cvt_pk_bf16(float lo, float hi) { unsigned r; asm volatile("v_cvt_pk_bf16_f32 %0, %1, %2" : "=v"(r) : "v"(lo), "v"(hi)); return r; }
; DI float shx(float v, int mask, int lane) { return __int_as_float(__builtin_amdgcn_ds_bpermute((lane ^ mask) << 2, __float_as_int(v))); }
;     DI void operator()(const f32x4 (&acc)[2][2][4][2], const Unit& u, int wr, int wc, int fr, int fq) const {
;     ...
;             for (int m = 0; m < 4; ++m) { const int row = row0 + ai * 128 + m * 16; const size_t off = (size_t)row * 1024 + col0; float ss = 0.f;
; #pragma unroll
;                 for (int bj = 0; bj < 2; ++bj) { const size_t o = off + bj * 128; const u32x4 r_ = *(const u32x4*)(x1b + o); f32x4 v0, v1;
;                     v0[0] = __uint_as_float(r_.x << 16); v0[1] = __uint_as_float(r_.x & 0xffff0000u); v0[2] = __uint_as_float(r_.y << 16); v0[3] = __uint_as_float(r_.y & 0xffff0000u);
;                     v1[0] = __uint_as_float(r_.z << 16); v1[1] = __uint_as_float(r_.z & 0xffff0000u); v1[2] = __uint_as_float(r_.w << 16); v1[3] = __uint_as_float(r_.w & 0xffff0000u);
;                     v0 = v0 + acc[ai][bj][m][0]; v1 = v1 + acc[ai][bj][m][1];
;                     ss += ((v0[0] * v0[0] + v0[1] * v0[1]) + (v0[2] * v0[2] + v0[3] * v0[3])) + ((v1[0] * v1[0] + v1[1] * v1[1]) + (v1[2] * v1[2] + v1[3] * v1[3]));
;                     u32x4 w; w.x = cvt_pk_bf16(v0[0], v0[1]); w.y = cvt_pk_bf16(v0[2], v0[3]); w.z = cvt_pk_bf16(v1[0], v1[1]); w.w = cvt_pk_bf16(v1[2], v1[3]); *(u32x4*)(x1b + o) = w; }
;                 { const int ln_ = fq * 16 + fr; ss += shx(ss, 16, ln_); ss += shx(ss, 32, ln_); }
;                 if (fq == 0) unsafeAtomicAdd(ssum2 + row, ss); }
.LBB0_2027:
	s_or_b64 exec, exec, s[28:29]
	v_add_u32_e32 v64, 0x80, v146
	s_waitcnt lgkmcnt(0)
	v_ashrrev_i32_e32 v65, 31, v64
	v_lshlrev_b64 v[66:67], 11, v[64:65]
	v_lshl_add_u64 v[66:67], s[34:35], 0, v[66:67]
	v_lshl_add_u64 v[70:71], v[144:145], 1, v[66:67]
	global_load_dwordx4 v[66:69], v[70:71], off
	s_waitcnt vmcnt(0)
	v_lshlrev_b32_e32 v72, 16, v66
	v_and_b32_e32 v73, 0xffff0000, v66
	v_lshlrev_b32_e32 v66, 16, v67
	v_and_b32_e32 v67, 0xffff0000, v67
	v_lshlrev_b32_e32 v74, 16, v68
	v_and_b32_e32 v75, 0xffff0000, v68
	v_lshlrev_b32_e32 v68, 16, v69
	v_and_b32_e32 v69, 0xffff0000, v69
	v_add_f32_e32 v66, v62, v66
	v_add_f32_e32 v67, v63, v67
	v_add_f32_e32 v72, v60, v72
	v_add_f32_e32 v73, v61, v73
	v_add_f32_e32 v68, v58, v68
	v_add_f32_e32 v69, v59, v69
	v_add_f32_e32 v74, v56, v74
	v_add_f32_e32 v75, v57, v75
	v_cvt_pk_bf16_f32 v56, v72, v73
	v_cvt_pk_bf16_f32 v57, v66, v67
	v_mul_f32_e32 v73, v73, v73
	v_cvt_pk_bf16_f32 v58, v74, v75
	v_cvt_pk_bf16_f32 v59, v68, v69
	global_load_dwordx4 v[60:63], v[70:71], off offset:256
	v_mul_f32_e32 v67, v67, v67
	v_mul_f32_e32 v75, v75, v75
	v_mul_f32_e32 v69, v69, v69
	v_fmac_f32_e32 v73, v72, v72
	v_fmac_f32_e32 v67, v66, v66
	v_fmac_f32_e32 v75, v74, v74
	v_fmac_f32_e32 v69, v68, v68
	v_add_f32_e32 v66, v73, v67
	v_add_f32_e32 v67, v75, v69
	v_add_f32_e32 v72, v66, v67
	global_store_dwordx4 v[70:71], v[56:59], off
	s_waitcnt vmcnt(1)
	v_lshlrev_b32_e32 v66, 16, v60
	v_and_b32_e32 v67, 0xffff0000, v60
	v_lshlrev_b32_e32 v60, 16, v61
	v_and_b32_e32 v61, 0xffff0000, v61
	v_lshlrev_b32_e32 v68, 16, v62
	v_and_b32_e32 v69, 0xffff0000, v62
	v_lshlrev_b32_e32 v62, 16, v63
	v_and_b32_e32 v63, 0xffff0000, v63
	v_add_f32_e32 v54, v54, v60
	v_add_f32_e32 v55, v55, v61
	v_add_f32_e32 v52, v52, v66
	v_add_f32_e32 v53, v53, v67
	v_add_f32_e32 v60, v50, v62
	v_add_f32_e32 v61, v51, v63
	v_add_f32_e32 v62, v48, v68
	v_add_f32_e32 v63, v49, v69
	v_mul_f32_e32 v48, v53, v53
	v_mul_f32_e32 v49, v55, v55
	v_mul_f32_e32 v50, v63, v63
	v_mul_f32_e32 v51, v61, v61
	v_fmac_f32_e32 v48, v52, v52
	v_fmac_f32_e32 v49, v54, v54
	v_fmac_f32_e32 v50, v62, v62
	v_fmac_f32_e32 v51, v60, v60
	v_add_f32_e32 v48, v48, v49
	v_add_f32_e32 v49, v50, v51
	v_add_f32_e32 v48, v48, v49
	v_add_f32_e32 v48, v72, v48
	ds_bpermute_b32 v49, v150, v48
	v_cvt_pk_bf16_f32 v50, v52, v53
	v_cvt_pk_bf16_f32 v51, v54, v55
	v_cvt_pk_bf16_f32 v52, v62, v63
	v_cvt_pk_bf16_f32 v53, v60, v61
	s_waitcnt lgkmcnt(0)
	v_add_f32_e32 v48, v48, v49
	ds_bpermute_b32 v49, v151, v48
	global_store_dwordx4 v[70:71], v[50:53], off offset:256
	s_and_saveexec_b64 s[28:29], s[4:5]
	s_cbranch_execz .LBB0_2029
	s_waitcnt lgkmcnt(0)
	v_add_f32_e32 v50, v48, v49
	v_lshl_add_u64 v[48:49], v[64:65], 2, s[16:17]
	global_atomic_add_f32 v[48:49], v50, off
.LBB0_2029:
	s_or_b64 exec, exec, s[28:29]
	v_add_u32_e32 v48, 0x90, v146
	s_waitcnt lgkmcnt(0)
	v_ashrrev_i32_e32 v49, 31, v48
	v_lshlrev_b64 v[50:51], 11, v[48:49]
	v_lshl_add_u64 v[50:51], s[34:35], 0, v[50:51]
	v_lshl_add_u64 v[54:55], v[144:145], 1, v[50:51]
	global_load_dwordx4 v[50:53], v[54:55], off
	s_waitcnt vmcnt(0)
	v_lshlrev_b32_e32 v56, 16, v50
	v_and_b32_e32 v57, 0xffff0000, v50
	v_lshlrev_b32_e32 v50, 16, v51
	v_and_b32_e32 v51, 0xffff0000, v51
	v_lshlrev_b32_e32 v58, 16, v52
	v_and_b32_e32 v59, 0xffff0000, v52
	v_lshlrev_b32_e32 v52, 16, v53
	v_and_b32_e32 v53, 0xffff0000, v53
	v_add_f32_e32 v50, v46, v50
	v_add_f32_e32 v51, v47, v51
	v_add_f32_e32 v56, v44, v56
	v_add_f32_e32 v57, v45, v57
	v_add_f32_e32 v52, v42, v52
	v_add_f32_e32 v53, v43, v53
	v_add_f32_e32 v58, v40, v58
	v_add_f32_e32 v59, v41, v59
	v_cvt_pk_bf16_f32 v40, v56, v57
	v_cvt_pk_bf16_f32 v41, v50, v51
	v_mul_f32_e32 v57, v57, v57
	v_cvt_pk_bf16_f32 v42, v58, v59
	v_cvt_pk_bf16_f32 v43, v52, v53
	global_load_dwordx4 v[44:47], v[54:55], off offset:256
	v_mul_f32_e32 v51, v51, v51
	v_mul_f32_e32 v59, v59, v59
	v_mul_f32_e32 v53, v53, v53
	v_fmac_f32_e32 v57, v56, v56
	v_fmac_f32_e32 v51, v50, v50
	v_fmac_f32_e32 v59, v58, v58
	v_fmac_f32_e32 v53, v52, v52
	v_add_f32_e32 v50, v57, v51
	v_add_f32_e32 v51, v59, v53
	v_add_f32_e32 v56, v50, v51
	global_store_dwordx4 v[54:55], v[40:43], off
	s_waitcnt vmcnt(1)
	v_lshlrev_b32_e32 v50, 16, v44
	v_and_b32_e32 v51, 0xffff0000, v44
	v_lshlrev_b32_e32 v44, 16, v45
	v_and_b32_e32 v45, 0xffff0000, v45
	v_lshlrev_b32_e32 v52, 16, v46
	v_and_b32_e32 v53, 0xffff0000, v46
	v_lshlrev_b32_e32 v46, 16, v47
	v_and_b32_e32 v47, 0xffff0000, v47
	v_add_f32_e32 v38, v38, v44
	v_add_f32_e32 v39, v39, v45
	v_add_f32_e32 v36, v36, v50
	v_add_f32_e32 v37, v37, v51
	v_add_f32_e32 v44, v34, v46
	v_add_f32_e32 v45, v35, v47
	v_add_f32_e32 v46, v32, v52
	v_add_f32_e32 v47, v33, v53
	v_mul_f32_e32 v32, v37, v37
	v_mul_f32_e32 v33, v39, v39
	v_mul_f32_e32 v34, v47, v47
	v_mul_f32_e32 v35, v45, v45
	v_fmac_f32_e32 v32, v36, v36
	v_fmac_f32_e32 v33, v38, v38
	v_fmac_f32_e32 v34, v46, v46
	v_fmac_f32_e32 v35, v44, v44
	v_add_f32_e32 v32, v32, v33
	v_add_f32_e32 v33, v34, v35
	v_add_f32_e32 v32, v32, v33
	v_add_f32_e32 v32, v56, v32
	ds_bpermute_b32 v33, v150, v32
	v_cvt_pk_bf16_f32 v34, v36, v37
	v_cvt_pk_bf16_f32 v35, v38, v39
	v_cvt_pk_bf16_f32 v36, v46, v47
	v_cvt_pk_bf16_f32 v37, v44, v45
	s_waitcnt lgkmcnt(0)
	v_add_f32_e32 v32, v32, v33
	ds_bpermute_b32 v33, v151, v32
	global_store_dwordx4 v[54:55], v[34:37], off offset:256
	s_and_saveexec_b64 s[28:29], s[4:5]
	s_cbranch_execz .LBB0_2031
	s_waitcnt lgkmcnt(0)
	v_add_f32_e32 v34, v32, v33
	v_lshl_add_u64 v[32:33], v[48:49], 2, s[16:17]
	global_atomic_add_f32 v[32:33], v34, off
; __device__ __forceinline__ unsigned cvt_pk_bf16(float lo, float hi) { unsigned r; asm volatile("v_cvt_pk_bf16_f32 %0, %1, %2" : "=v"(r) : "v"(lo), "v"(hi)); return r; }
; DI float shx(float v, int mask, int lane) { return __int_as_float(__builtin_amdgcn_ds_bpermute((lane ^ mask) << 2, __float_as_int(v))); }
;     DI void operator()(const f32x4 (&acc)[2][2][4][2], const Unit& u, int wr, int wc, int fr, int fq) const {
;     ...
;             for (int m = 0; m < 4; ++m) { const int row = row0 + ai * 128 + m * 16; const size_t off = (size_t)row * 1024 + col0; float ss = 0.f;
; #pragma unroll
;                 for (int bj = 0; bj < 2; ++bj) { const size_t o = off + bj * 128; const u32x4 r_ = *(const u32x4*)(x1b + o); f32x4 v0, v1;
;                     v0[0] = __uint_as_float(r_.x << 16); v0[1] = __uint_as_float(r_.x & 0xffff0000u); v0[2] = __uint_as_float(r_.y << 16); v0[3] = __uint_as_float(r_.y & 0xffff0000u);
;                     v1[0] = __uint_as_float(r_.z << 16); v1[1] = __uint_as_float(r_.z & 0xffff0000u); v1[2] = __uint_as_float(r_.w << 16); v1[3] = __uint_as_float(r_.w & 0xffff0000u);
;                     v0 = v0 + acc[ai][bj][m][0]; v1 = v1 + acc[ai][bj][m][1];
;                     ss += ((v0[0] * v0[0] + v0[1] * v0[1]) + (v0[2] * v0[2] + v0[3] * v0[3])) + ((v1[0] * v1[0] + v1[1] * v1[1]) + (v1[2] * v1[2] + v1[3] * v1[3]));
;                     u32x4 w; w.x = cvt_pk_bf16(v0[0], v0[1]); w.y = cvt_pk_bf16(v0[2], v0[3]); w.z = cvt_pk_bf16(v1[0], v1[1]); w.w = cvt_pk_bf16(v1[2], v1[3]); *(u32x4*)(x1b + o) = w; }
;                 { const int ln_ = fq * 16 + fr; ss += shx(ss, 16, ln_); ss += shx(ss, 32, ln_); }
;                 if (fq == 0) unsafeAtomicAdd(ssum2 + row, ss); }
.LBB0_2031:
	s_or_b64 exec, exec, s[28:29]
	v_add_u32_e32 v32, 0xa0, v146
	s_waitcnt lgkmcnt(0)
	v_ashrrev_i32_e32 v33, 31, v32
	v_lshlrev_b64 v[34:35], 11, v[32:33]
	v_lshl_add_u64 v[34:35], s[34:35], 0, v[34:35]
	v_lshl_add_u64 v[38:39], v[144:145], 1, v[34:35]
	global_load_dwordx4 v[34:37], v[38:39], off
	s_waitcnt vmcnt(0)
	v_lshlrev_b32_e32 v40, 16, v34
	v_and_b32_e32 v41, 0xffff0000, v34
	v_lshlrev_b32_e32 v34, 16, v35
	v_and_b32_e32 v35, 0xffff0000, v35
	v_lshlrev_b32_e32 v42, 16, v36
	v_and_b32_e32 v43, 0xffff0000, v36
	v_lshlrev_b32_e32 v36, 16, v37
	v_and_b32_e32 v37, 0xffff0000, v37
	v_add_f32_e32 v34, v30, v34
	v_add_f32_e32 v35, v31, v35
	v_add_f32_e32 v40, v28, v40
	v_add_f32_e32 v41, v29, v41
	v_add_f32_e32 v36, v26, v36
	v_add_f32_e32 v37, v27, v37
	v_add_f32_e32 v42, v24, v42
	v_add_f32_e32 v43, v25, v43
	v_cvt_pk_bf16_f32 v24, v40, v41
	v_cvt_pk_bf16_f32 v25, v34, v35
	v_mul_f32_e32 v41, v41, v41
	v_cvt_pk_bf16_f32 v26, v42, v43
	v_cvt_pk_bf16_f32 v27, v36, v37
	global_load_dwordx4 v[28:31], v[38:39], off offset:256
	v_mul_f32_e32 v35, v35, v35
	v_mul_f32_e32 v43, v43, v43
	v_mul_f32_e32 v37, v37, v37
	v_fmac_f32_e32 v41, v40, v40
	v_fmac_f32_e32 v35, v34, v34
	v_fmac_f32_e32 v43, v42, v42
	v_fmac_f32_e32 v37, v36, v36
	v_add_f32_e32 v34, v41, v35
	v_add_f32_e32 v35, v43, v37
	v_add_f32_e32 v40, v34, v35
	global_store_dwordx4 v[38:39], v[24:27], off
	s_waitcnt vmcnt(1)
	v_lshlrev_b32_e32 v34, 16, v28
	v_and_b32_e32 v35, 0xffff0000, v28
	v_lshlrev_b32_e32 v28, 16, v29
	v_and_b32_e32 v29, 0xffff0000, v29
	v_lshlrev_b32_e32 v36, 16, v30
	v_and_b32_e32 v37, 0xffff0000, v30
	v_lshlrev_b32_e32 v30, 16, v31
	v_and_b32_e32 v31, 0xffff0000, v31
	v_add_f32_e32 v22, v22, v28
	v_add_f32_e32 v23, v23, v29
	v_add_f32_e32 v20, v20, v34
	v_add_f32_e32 v21, v21, v35
	v_add_f32_e32 v28, v18, v30
	v_add_f32_e32 v29, v19, v31
	v_add_f32_e32 v30, v16, v36
	v_add_f32_e32 v31, v17, v37
	v_mul_f32_e32 v16, v21, v21
	v_mul_f32_e32 v17, v23, v23
	v_mul_f32_e32 v18, v31, v31
	v_mul_f32_e32 v19, v29, v29
	v_fmac_f32_e32 v16, v20, v20
	v_fmac_f32_e32 v17, v22, v22
	v_fmac_f32_e32 v18, v30, v30
	v_fmac_f32_e32 v19, v28, v28
	v_add_f32_e32 v16, v16, v17
	v_add_f32_e32 v17, v18, v19
	v_add_f32_e32 v16, v16, v17
	v_add_f32_e32 v16, v40, v16
	ds_bpermute_b32 v17, v150, v16
	v_cvt_pk_bf16_f32 v18, v20, v21
	v_cvt_pk_bf16_f32 v19, v22, v23
	v_cvt_pk_bf16_f32 v20, v30, v31
	v_cvt_pk_bf16_f32 v21, v28, v29
	s_waitcnt lgkmcnt(0)
	v_add_f32_e32 v16, v16, v17
	ds_bpermute_b32 v17, v151, v16
	global_store_dwordx4 v[38:39], v[18:21], off offset:256
	s_and_saveexec_b64 s[28:29], s[4:5]
	s_cbranch_execz .LBB0_2033
	s_waitcnt lgkmcnt(0)
	v_add_f32_e32 v18, v16, v17
	v_lshl_add_u64 v[16:17], v[32:33], 2, s[16:17]
	global_atomic_add_f32 v[16:17], v18, off
.LBB0_2033:
	s_or_b64 exec, exec, s[28:29]
	v_add_u32_e32 v16, 0xb0, v146
	s_waitcnt lgkmcnt(0)
	v_ashrrev_i32_e32 v17, 31, v16
	v_lshlrev_b64 v[18:19], 11, v[16:17]
	v_lshl_add_u64 v[18:19], s[34:35], 0, v[18:19]
	v_lshl_add_u64 v[22:23], v[144:145], 1, v[18:19]
	global_load_dwordx4 v[18:21], v[22:23], off
	s_waitcnt vmcnt(0)
	v_lshlrev_b32_e32 v24, 16, v18
	v_and_b32_e32 v25, 0xffff0000, v18
	v_lshlrev_b32_e32 v18, 16, v19
	v_and_b32_e32 v19, 0xffff0000, v19
	v_lshlrev_b32_e32 v26, 16, v20
	v_and_b32_e32 v27, 0xffff0000, v20
	v_lshlrev_b32_e32 v20, 16, v21
	v_and_b32_e32 v21, 0xffff0000, v21
	v_add_f32_e32 v18, v14, v18
	v_add_f32_e32 v19, v15, v19
	v_add_f32_e32 v24, v12, v24
	v_add_f32_e32 v25, v13, v25
	v_add_f32_e32 v20, v10, v20
	v_add_f32_e32 v21, v11, v21
	v_add_f32_e32 v26, v8, v26
	v_add_f32_e32 v27, v9, v27
	v_cvt_pk_bf16_f32 v8, v24, v25
	v_cvt_pk_bf16_f32 v9, v18, v19
	v_mul_f32_e32 v25, v25, v25
	v_cvt_pk_bf16_f32 v10, v26, v27
	v_cvt_pk_bf16_f32 v11, v20, v21
	global_load_dwordx4 v[12:15], v[22:23], off offset:256
	v_mul_f32_e32 v19, v19, v19
	v_mul_f32_e32 v27, v27, v27
	v_mul_f32_e32 v21, v21, v21
	v_fmac_f32_e32 v25, v24, v24
	v_fmac_f32_e32 v19, v18, v18
	v_fmac_f32_e32 v27, v26, v26
	v_fmac_f32_e32 v21, v20, v20
	v_add_f32_e32 v18, v25, v19
	v_add_f32_e32 v19, v27, v21
	v_add_f32_e32 v24, v18, v19
	global_store_dwordx4 v[22:23], v[8:11], off
	s_waitcnt vmcnt(1)
	v_lshlrev_b32_e32 v18, 16, v12
	v_and_b32_e32 v19, 0xffff0000, v12
	v_lshlrev_b32_e32 v12, 16, v13
	v_and_b32_e32 v13, 0xffff0000, v13
	v_lshlrev_b32_e32 v20, 16, v14
	v_and_b32_e32 v21, 0xffff0000, v14
	v_lshlrev_b32_e32 v14, 16, v15
	v_and_b32_e32 v15, 0xffff0000, v15
	v_add_f32_e32 v6, v6, v12
	v_add_f32_e32 v7, v7, v13
	v_add_f32_e32 v4, v4, v18
	v_add_f32_e32 v5, v5, v19
	v_add_f32_e32 v12, v2, v14
	v_add_f32_e32 v13, v3, v15
	v_add_f32_e32 v14, v0, v20
	v_add_f32_e32 v15, v1, v21
	v_mul_f32_e32 v0, v5, v5
	v_mul_f32_e32 v1, v7, v7
	v_mul_f32_e32 v2, v15, v15
	v_mul_f32_e32 v3, v13, v13
	v_fmac_f32_e32 v0, v4, v4
	v_fmac_f32_e32 v1, v6, v6
	v_fmac_f32_e32 v2, v14, v14
	v_fmac_f32_e32 v3, v12, v12
	v_add_f32_e32 v0, v0, v1
	v_add_f32_e32 v1, v2, v3
	v_add_f32_e32 v0, v0, v1
	v_add_f32_e32 v0, v24, v0
	ds_bpermute_b32 v1, v150, v0
	v_cvt_pk_bf16_f32 v2, v4, v5
	v_cvt_pk_bf16_f32 v3, v6, v7
	v_cvt_pk_bf16_f32 v4, v14, v15
	v_cvt_pk_bf16_f32 v5, v12, v13
	s_waitcnt lgkmcnt(0)
	v_add_f32_e32 v0, v0, v1
	ds_bpermute_b32 v1, v151, v0
	global_store_dwordx4 v[22:23], v[2:5], off offset:256
	s_and_saveexec_b64 s[28:29], s[4:5]
	s_cbranch_execz .LBB0_2035
	s_waitcnt lgkmcnt(0)
	v_add_f32_e32 v2, v0, v1
	v_lshl_add_u64 v[0:1], v[16:17], 2, s[16:17]
	global_atomic_add_f32 v[0:1], v2, off

; __device__ __forceinline__ unsigned cvt_pk_bf16(float lo, float hi) { unsigned r; asm volatile("v_cvt_pk_bf16_f32 %0, %1, %2" : "=v"(r) : "v"(lo), "v"(hi)); return r; }
;     DI void operator()(const f32x4 (&acc)[2][2][4][2], const Unit& u, int wr, int wc, int fr, int fq) const {
;     ...
;             for (int m = 0; m < 4; ++m) { const int row = row0 + ai * 128 + m * 16; const float s = rsqrtf(ssum2[row] * (1.f / 1024.f) + EPS);
;                 bf16_t* rowp = U + (size_t)row * 4096 + col0;
; #pragma unroll
;                 for (int bj = 0; bj < 2; ++bj) { f32x4 v0 = acc[ai][bj][m][0] * s, v1 = acc[ai][bj][m][1] * s;
; #pragma unroll
;                     for (int j = 0; j < 4; ++j) { const float a = fmaxf(v0[j], 0.f), b = fmaxf(v1[j], 0.f); v0[j] = a * a; v1[j] = b * b; }
;                     u32x4 w; w.x = cvt_pk_bf16(v0[0], v0[1]); w.y = cvt_pk_bf16(v0[2], v0[3]); w.z = cvt_pk_bf16(v1[0], v1[1]); w.w = cvt_pk_bf16(v1[2], v1[3]);
;                     __builtin_nontemporal_store(w, (u32x4*)(rowp + bj * 128)); } }
.LBB0_2070:
	v_lshl_add_u32 v148, s6, 8, v152
	v_ashrrev_i32_e32 v149, 31, v148
	v_lshl_add_u64 v[144:145], v[148:149], 2, s[16:17]
	global_load_dword v159, v[144:145], off
	v_lshl_or_b32 v146, s7, 8, v154
	v_ashrrev_i32_e32 v147, 31, v146
	v_lshlrev_b64 v[150:151], 1, v[146:147]
	v_lshlrev_b64 v[162:163], 13, v[148:149]
	v_or_b32_e32 v160, 16, v148
	v_ashrrev_i32_e32 v161, 31, v160
	s_waitcnt vmcnt(0)
	v_fmamk_f32 v146, v159, 0x3a800000, v158
	v_mul_f32_e32 v147, 0x4b800000, v146
	v_cmp_gt_f32_e32 vcc, s62, v146
	s_nop 1
	v_cndmask_b32_e32 v146, v146, v147, vcc
	v_rsq_f32_e32 v149, v146
	v_lshl_add_u64 v[146:147], s[14:15], 0, v[162:163]
	v_lshl_add_u64 v[146:147], v[146:147], 0, v[150:151]
	v_lshl_add_u64 v[162:163], v[160:161], 2, s[16:17]
	v_mul_f32_e32 v159, 0x45800000, v149
	v_cndmask_b32_e32 v164, v149, v159, vcc
	v_mul_f32_e32 v126, v126, v164
	v_mul_f32_e32 v127, v127, v164
	v_mul_f32_e32 v124, v124, v164
	v_mul_f32_e32 v125, v125, v164
	v_mul_f32_e32 v122, v122, v164
	v_mul_f32_e32 v123, v123, v164
	v_mul_f32_e32 v120, v120, v164
	v_mul_f32_e32 v121, v121, v164
	v_mul_f32_e32 v114, v114, v164
	v_mul_f32_e32 v115, v115, v164
	v_mul_f32_e32 v112, v112, v164
	v_mul_f32_e32 v113, v113, v164
	v_mul_f32_e32 v118, v118, v164
	v_mul_f32_e32 v119, v119, v164
	v_mul_f32_e32 v116, v116, v164
	v_mul_f32_e32 v117, v117, v164
	v_max_f32_e32 v124, 0, v124
	v_max_f32_e32 v120, 0, v120
	v_max_f32_e32 v125, 0, v125
	v_max_f32_e32 v121, 0, v121
	v_max_f32_e32 v126, 0, v126
	v_max_f32_e32 v122, 0, v122
	v_max_f32_e32 v127, 0, v127
	v_max_f32_e32 v123, 0, v123
	v_max_f32_e32 v112, 0, v112
	v_max_f32_e32 v113, 0, v113
	v_max_f32_e32 v114, 0, v114
	v_max_f32_e32 v115, 0, v115
	v_max_f32_e32 v116, 0, v116
	v_max_f32_e32 v117, 0, v117
	v_max_f32_e32 v118, 0, v118
	v_max_f32_e32 v119, 0, v119
	v_mul_f32_e32 v124, v124, v124
	v_mul_f32_e32 v120, v120, v120
	v_mul_f32_e32 v125, v125, v125
	v_mul_f32_e32 v121, v121, v121
	v_mul_f32_e32 v126, v126, v126
	v_mul_f32_e32 v122, v122, v122
	v_mul_f32_e32 v127, v127, v127
	v_mul_f32_e32 v123, v123, v123
	v_mul_f32_e32 v149, v112, v112
	v_mul_f32_e32 v159, v113, v113
	v_mul_f32_e32 v164, v114, v114
	v_mul_f32_e32 v165, v115, v115
	v_cvt_pk_bf16_f32 v112, v124, v125
	v_cvt_pk_bf16_f32 v113, v126, v127
	v_cvt_pk_bf16_f32 v114, v120, v121
	v_cvt_pk_bf16_f32 v115, v122, v123
	v_mul_f32_e32 v116, v116, v116
	v_mul_f32_e32 v117, v117, v117
	v_mul_f32_e32 v118, v118, v118
	v_mul_f32_e32 v119, v119, v119
	global_store_dwordx4 v[146:147], v[112:115], off nt
	s_nop 1
	v_cvt_pk_bf16_f32 v112, v116, v117
	v_cvt_pk_bf16_f32 v113, v118, v119
	v_cvt_pk_bf16_f32 v114, v149, v159
	v_cvt_pk_bf16_f32 v115, v164, v165
	global_store_dwordx4 v[146:147], v[112:115], off offset:256 nt
	global_load_dword v116, v[162:163], off
	s_waitcnt vmcnt(0)
	v_fmamk_f32 v116, v116, 0x3a800000, v158
	v_mul_f32_e32 v117, 0x4b800000, v116
	v_cmp_gt_f32_e32 vcc, s62, v116
	v_lshlrev_b64 v[114:115], 13, v[160:161]
	v_or_b32_e32 v112, 32, v148
	v_cndmask_b32_e32 v116, v116, v117, vcc
	v_rsq_f32_e32 v118, v116
	v_lshl_add_u64 v[114:115], s[14:15], 0, v[114:115]
	v_ashrrev_i32_e32 v113, 31, v112
	v_lshl_add_u64 v[114:115], v[114:115], 0, v[150:151]
	v_mul_f32_e32 v119, 0x45800000, v118
	v_cndmask_b32_e32 v118, v118, v119, vcc
	v_mul_f32_e32 v110, v110, v118
	v_mul_f32_e32 v111, v111, v118
	v_mul_f32_e32 v108, v108, v118
	v_mul_f32_e32 v109, v109, v118
	v_mul_f32_e32 v106, v106, v118
	v_mul_f32_e32 v107, v107, v118
	v_mul_f32_e32 v104, v104, v118
	v_mul_f32_e32 v105, v105, v118
	v_mul_f32_e32 v98, v98, v118
	v_mul_f32_e32 v99, v99, v118
	v_mul_f32_e32 v96, v96, v118
	v_mul_f32_e32 v97, v97, v118
	v_mul_f32_e32 v102, v102, v118
	v_mul_f32_e32 v103, v103, v118
	v_mul_f32_e32 v100, v100, v118
	v_mul_f32_e32 v101, v101, v118
	v_max_f32_e32 v108, 0, v108
	v_max_f32_e32 v104, 0, v104
	v_max_f32_e32 v109, 0, v109
	v_max_f32_e32 v105, 0, v105
	v_max_f32_e32 v110, 0, v110
	v_max_f32_e32 v106, 0, v106
	v_max_f32_e32 v111, 0, v111
	v_max_f32_e32 v107, 0, v107
	v_max_f32_e32 v96, 0, v96
	v_max_f32_e32 v97, 0, v97
	v_max_f32_e32 v98, 0, v98
	v_max_f32_e32 v99, 0, v99
	v_max_f32_e32 v100, 0, v100
	v_max_f32_e32 v101, 0, v101
	v_max_f32_e32 v102, 0, v102
	v_max_f32_e32 v103, 0, v103
	v_mul_f32_e32 v108, v108, v108
	v_mul_f32_e32 v104, v104, v104
	v_mul_f32_e32 v109, v109, v109
	v_mul_f32_e32 v105, v105, v105
	v_mul_f32_e32 v110, v110, v110
	v_mul_f32_e32 v106, v106, v106
	v_mul_f32_e32 v111, v111, v111
	v_mul_f32_e32 v107, v107, v107
	v_mul_f32_e32 v118, v96, v96
	v_mul_f32_e32 v119, v97, v97
	v_mul_f32_e32 v120, v98, v98
	v_mul_f32_e32 v121, v99, v99
	v_cvt_pk_bf16_f32 v96, v108, v109
	v_cvt_pk_bf16_f32 v97, v110, v111
	v_cvt_pk_bf16_f32 v98, v104, v105
	v_cvt_pk_bf16_f32 v99, v106, v107
	v_lshl_add_u64 v[116:117], v[112:113], 2, s[16:17]
	v_mul_f32_e32 v100, v100, v100
	v_mul_f32_e32 v101, v101, v101
	v_mul_f32_e32 v102, v102, v102
	v_mul_f32_e32 v103, v103, v103
	global_store_dwordx4 v[114:115], v[96:99], off nt
	s_nop 1
	v_cvt_pk_bf16_f32 v96, v100, v101
	v_cvt_pk_bf16_f32 v97, v102, v103
	v_cvt_pk_bf16_f32 v98, v118, v119
	v_cvt_pk_bf16_f32 v99, v120, v121
	global_store_dwordx4 v[114:115], v[96:99], off offset:256 nt
	global_load_dword v100, v[116:117], off
	s_waitcnt vmcnt(0)
; __device__ __forceinline__ unsigned cvt_pk_bf16(float lo, float hi) { unsigned r; asm volatile("v_cvt_pk_bf16_f32 %0, %1, %2" : "=v"(r) : "v"(lo), "v"(hi)); return r; }
;     DI void operator()(const f32x4 (&acc)[2][2][4][2], const Unit& u, int wr, int wc, int fr, int fq) const {
;     ...
;             for (int m = 0; m < 4; ++m) { const int row = row0 + ai * 128 + m * 16; const float s = rsqrtf(ssum2[row] * (1.f / 1024.f) + EPS);
;                 bf16_t* rowp = U + (size_t)row * 4096 + col0;
; #pragma unroll
;                 for (int bj = 0; bj < 2; ++bj) { f32x4 v0 = acc[ai][bj][m][0] * s, v1 = acc[ai][bj][m][1] * s;
; #pragma unroll
;                     for (int j = 0; j < 4; ++j) { const float a = fmaxf(v0[j], 0.f), b = fmaxf(v1[j], 0.f); v0[j] = a * a; v1[j] = b * b; }
;                     u32x4 w; w.x = cvt_pk_bf16(v0[0], v0[1]); w.y = cvt_pk_bf16(v0[2], v0[3]); w.z = cvt_pk_bf16(v1[0], v1[1]); w.w = cvt_pk_bf16(v1[2], v1[3]);
;                     __builtin_nontemporal_store(w, (u32x4*)(rowp + bj * 128)); } }
	v_fmamk_f32 v100, v100, 0x3a800000, v158
	v_mul_f32_e32 v101, 0x4b800000, v100
	v_cmp_gt_f32_e32 vcc, s62, v100
	v_lshlrev_b64 v[98:99], 13, v[112:113]
	v_or_b32_e32 v96, 48, v148
	v_cndmask_b32_e32 v100, v100, v101, vcc
	v_rsq_f32_e32 v102, v100
	v_lshl_add_u64 v[98:99], s[14:15], 0, v[98:99]
	v_ashrrev_i32_e32 v97, 31, v96
	v_lshl_add_u64 v[98:99], v[98:99], 0, v[150:151]
	v_mul_f32_e32 v103, 0x45800000, v102
	v_cndmask_b32_e32 v102, v102, v103, vcc
	v_mul_f32_e32 v94, v94, v102
	v_mul_f32_e32 v95, v95, v102
	v_mul_f32_e32 v92, v92, v102
	v_mul_f32_e32 v93, v93, v102
	v_mul_f32_e32 v90, v90, v102
	v_mul_f32_e32 v91, v91, v102
	v_mul_f32_e32 v88, v88, v102
	v_mul_f32_e32 v89, v89, v102
	v_mul_f32_e32 v82, v82, v102
	v_mul_f32_e32 v83, v83, v102
	v_mul_f32_e32 v80, v80, v102
	v_mul_f32_e32 v81, v81, v102
	v_mul_f32_e32 v86, v86, v102
	v_mul_f32_e32 v87, v87, v102
	v_mul_f32_e32 v84, v84, v102
	v_mul_f32_e32 v85, v85, v102
	v_max_f32_e32 v92, 0, v92
	v_max_f32_e32 v88, 0, v88
	v_max_f32_e32 v93, 0, v93
	v_max_f32_e32 v89, 0, v89
	v_max_f32_e32 v94, 0, v94
	v_max_f32_e32 v90, 0, v90
	v_max_f32_e32 v95, 0, v95
	v_max_f32_e32 v91, 0, v91
	v_max_f32_e32 v80, 0, v80
	v_max_f32_e32 v81, 0, v81
	v_max_f32_e32 v82, 0, v82
	v_max_f32_e32 v83, 0, v83
	v_max_f32_e32 v84, 0, v84
	v_max_f32_e32 v85, 0, v85
	v_max_f32_e32 v86, 0, v86
	v_max_f32_e32 v87, 0, v87
	v_mul_f32_e32 v92, v92, v92
	v_mul_f32_e32 v88, v88, v88
	v_mul_f32_e32 v93, v93, v93
	v_mul_f32_e32 v89, v89, v89
	v_mul_f32_e32 v94, v94, v94
	v_mul_f32_e32 v90, v90, v90
	v_mul_f32_e32 v95, v95, v95
	v_mul_f32_e32 v91, v91, v91
	v_mul_f32_e32 v102, v80, v80
	v_mul_f32_e32 v103, v81, v81
	v_mul_f32_e32 v104, v82, v82
	v_mul_f32_e32 v105, v83, v83
	v_cvt_pk_bf16_f32 v80, v92, v93
	v_cvt_pk_bf16_f32 v81, v94, v95
	v_cvt_pk_bf16_f32 v82, v88, v89
	v_cvt_pk_bf16_f32 v83, v90, v91
	v_lshl_add_u64 v[100:101], v[96:97], 2, s[16:17]
	v_mul_f32_e32 v84, v84, v84
	v_mul_f32_e32 v85, v85, v85
	v_mul_f32_e32 v86, v86, v86
	v_mul_f32_e32 v87, v87, v87
	global_store_dwordx4 v[98:99], v[80:83], off nt
	s_nop 1
	v_cvt_pk_bf16_f32 v80, v84, v85
	v_cvt_pk_bf16_f32 v81, v86, v87
	v_cvt_pk_bf16_f32 v82, v102, v103
	v_cvt_pk_bf16_f32 v83, v104, v105
	global_store_dwordx4 v[98:99], v[80:83], off offset:256 nt
	global_load_dword v80, v[100:101], off
	s_waitcnt vmcnt(0)
	v_fmamk_f32 v80, v80, 0x3a800000, v158
	v_mul_f32_e32 v81, 0x4b800000, v80
	v_cmp_gt_f32_e32 vcc, s62, v80
	s_nop 1
	v_cndmask_b32_e32 v80, v80, v81, vcc
	v_rsq_f32_e32 v82, v80
	v_lshlrev_b64 v[80:81], 13, v[96:97]
	v_lshl_add_u64 v[80:81], s[14:15], 0, v[80:81]
	v_lshl_add_u64 v[80:81], v[80:81], 0, v[150:151]
	v_mul_f32_e32 v83, 0x45800000, v82
	v_cndmask_b32_e32 v82, v82, v83, vcc
	v_mul_f32_e32 v78, v78, v82
	v_mul_f32_e32 v79, v79, v82
	v_mul_f32_e32 v76, v76, v82
	v_mul_f32_e32 v77, v77, v82
	v_mul_f32_e32 v74, v74, v82
	v_mul_f32_e32 v75, v75, v82
	v_mul_f32_e32 v72, v72, v82
	v_mul_f32_e32 v73, v73, v82
	v_mul_f32_e32 v66, v66, v82
	v_mul_f32_e32 v67, v67, v82
	v_mul_f32_e32 v64, v64, v82
	v_mul_f32_e32 v65, v65, v82
	v_mul_f32_e32 v70, v70, v82
	v_mul_f32_e32 v71, v71, v82
	v_mul_f32_e32 v68, v68, v82
	v_mul_f32_e32 v69, v69, v82
	v_max_f32_e32 v76, 0, v76
	v_max_f32_e32 v72, 0, v72
	v_max_f32_e32 v77, 0, v77
	v_max_f32_e32 v73, 0, v73
	v_max_f32_e32 v78, 0, v78
	v_max_f32_e32 v74, 0, v74
	v_max_f32_e32 v79, 0, v79
	v_max_f32_e32 v75, 0, v75
	v_max_f32_e32 v64, 0, v64
	v_max_f32_e32 v65, 0, v65
	v_max_f32_e32 v66, 0, v66
	v_max_f32_e32 v67, 0, v67
	v_max_f32_e32 v68, 0, v68
	v_max_f32_e32 v69, 0, v69
	v_max_f32_e32 v70, 0, v70
	v_max_f32_e32 v71, 0, v71
	v_mul_f32_e32 v76, v76, v76
	v_mul_f32_e32 v72, v72, v72
	v_mul_f32_e32 v77, v77, v77
	v_mul_f32_e32 v73, v73, v73
	v_mul_f32_e32 v78, v78, v78
	v_mul_f32_e32 v74, v74, v74
	v_mul_f32_e32 v79, v79, v79
	v_mul_f32_e32 v75, v75, v75
	v_mul_f32_e32 v82, v64, v64
	v_mul_f32_e32 v83, v65, v65
	v_mul_f32_e32 v84, v66, v66
	v_mul_f32_e32 v85, v67, v67
	v_cvt_pk_bf16_f32 v64, v76, v77
	v_cvt_pk_bf16_f32 v65, v78, v79
	v_cvt_pk_bf16_f32 v66, v72, v73
	v_cvt_pk_bf16_f32 v67, v74, v75
	v_mul_f32_e32 v68, v68, v68
	v_mul_f32_e32 v69, v69, v69
	v_mul_f32_e32 v70, v70, v70
	v_mul_f32_e32 v71, v71, v71
	global_store_dwordx4 v[80:81], v[64:67], off nt
	s_nop 1
	v_cvt_pk_bf16_f32 v64, v68, v69
	v_cvt_pk_bf16_f32 v65, v70, v71
	v_cvt_pk_bf16_f32 v66, v82, v83
	v_cvt_pk_bf16_f32 v67, v84, v85
	global_store_dwordx4 v[80:81], v[64:67], off offset:256 nt
	global_load_dword v66, v[144:145], off offset:512
	s_nop 0
	v_lshl_add_u64 v[64:65], v[146:147], 0, s[20:21]
	s_waitcnt vmcnt(0)
; __device__ __forceinline__ unsigned cvt_pk_bf16(float lo, float hi) { unsigned r; asm volatile("v_cvt_pk_bf16_f32 %0, %1, %2" : "=v"(r) : "v"(lo), "v"(hi)); return r; }
;     DI void operator()(const f32x4 (&acc)[2][2][4][2], const Unit& u, int wr, int wc, int fr, int fq) const {
;     ...
;             for (int m = 0; m < 4; ++m) { const int row = row0 + ai * 128 + m * 16; const float s = rsqrtf(ssum2[row] * (1.f / 1024.f) + EPS);
;                 bf16_t* rowp = U + (size_t)row * 4096 + col0;
; #pragma unroll
;                 for (int bj = 0; bj < 2; ++bj) { f32x4 v0 = acc[ai][bj][m][0] * s, v1 = acc[ai][bj][m][1] * s;
; #pragma unroll
;                     for (int j = 0; j < 4; ++j) { const float a = fmaxf(v0[j], 0.f), b = fmaxf(v1[j], 0.f); v0[j] = a * a; v1[j] = b * b; }
;                     u32x4 w; w.x = cvt_pk_bf16(v0[0], v0[1]); w.y = cvt_pk_bf16(v0[2], v0[3]); w.z = cvt_pk_bf16(v1[0], v1[1]); w.w = cvt_pk_bf16(v1[2], v1[3]);
;                     __builtin_nontemporal_store(w, (u32x4*)(rowp + bj * 128)); } }
	v_fmamk_f32 v66, v66, 0x3a800000, v158
	v_mul_f32_e32 v67, 0x4b800000, v66
	v_cmp_gt_f32_e32 vcc, s62, v66
	s_nop 1
	v_cndmask_b32_e32 v66, v66, v67, vcc
	v_rsq_f32_e32 v68, v66
	v_add_co_u32_e64 v66, s[6:7], s63, v146
	v_mul_f32_e32 v69, 0x45800000, v68
	v_cndmask_b32_e32 v68, v68, v69, vcc
	v_mul_f32_e32 v62, v62, v68
	v_mul_f32_e32 v63, v63, v68
	v_mul_f32_e32 v60, v60, v68
	v_mul_f32_e32 v61, v61, v68
	v_mul_f32_e32 v58, v58, v68
	v_mul_f32_e32 v59, v59, v68
	v_mul_f32_e32 v56, v56, v68
	v_mul_f32_e32 v57, v57, v68
	v_mul_f32_e32 v50, v50, v68
	v_mul_f32_e32 v51, v51, v68
	v_mul_f32_e32 v48, v48, v68
	v_mul_f32_e32 v49, v49, v68
	v_mul_f32_e32 v54, v54, v68
	v_mul_f32_e32 v55, v55, v68
	v_mul_f32_e32 v52, v52, v68
	v_mul_f32_e32 v53, v53, v68
	v_max_f32_e32 v60, 0, v60
	v_max_f32_e32 v56, 0, v56
	v_max_f32_e32 v61, 0, v61
	v_max_f32_e32 v57, 0, v57
	v_max_f32_e32 v62, 0, v62
	v_max_f32_e32 v58, 0, v58
	v_max_f32_e32 v63, 0, v63
	v_max_f32_e32 v59, 0, v59
	v_max_f32_e32 v48, 0, v48
	v_max_f32_e32 v49, 0, v49
	v_max_f32_e32 v50, 0, v50
	v_max_f32_e32 v51, 0, v51
	v_addc_co_u32_e64 v67, s[6:7], 0, v147, s[6:7]
	v_max_f32_e32 v52, 0, v52
	v_max_f32_e32 v53, 0, v53
	v_max_f32_e32 v54, 0, v54
	v_max_f32_e32 v55, 0, v55
	v_mul_f32_e32 v60, v60, v60
	v_mul_f32_e32 v56, v56, v56
	v_mul_f32_e32 v61, v61, v61
	v_mul_f32_e32 v57, v57, v57
	v_mul_f32_e32 v62, v62, v62
	v_mul_f32_e32 v58, v58, v58
	v_mul_f32_e32 v63, v63, v63
	v_mul_f32_e32 v59, v59, v59
	v_mul_f32_e32 v68, v48, v48
	v_mul_f32_e32 v69, v49, v49
	v_mul_f32_e32 v70, v50, v50
	v_mul_f32_e32 v71, v51, v51
	v_cvt_pk_bf16_f32 v48, v60, v61
	v_cvt_pk_bf16_f32 v49, v62, v63
	v_cvt_pk_bf16_f32 v50, v56, v57
	v_cvt_pk_bf16_f32 v51, v58, v59
	v_mul_f32_e32 v52, v52, v52
	v_mul_f32_e32 v53, v53, v53
	v_mul_f32_e32 v54, v54, v54
	v_mul_f32_e32 v55, v55, v55
	global_store_dwordx4 v[66:67], v[48:51], off nt
	s_nop 1
	v_cvt_pk_bf16_f32 v48, v52, v53
	v_cvt_pk_bf16_f32 v49, v54, v55
	v_cvt_pk_bf16_f32 v50, v68, v69
	v_cvt_pk_bf16_f32 v51, v70, v71
	global_store_dwordx4 v[64:65], v[48:51], off offset:256 nt
	global_load_dword v50, v[144:145], off offset:576
	s_nop 0
	v_lshl_add_u64 v[48:49], v[146:147], 0, s[22:23]
	s_waitcnt vmcnt(0)
	v_fmamk_f32 v50, v50, 0x3a800000, v158
	v_mul_f32_e32 v51, 0x4b800000, v50
	v_cmp_gt_f32_e32 vcc, s62, v50
	s_nop 1
	v_cndmask_b32_e32 v50, v50, v51, vcc
	v_rsq_f32_e32 v52, v50
	v_add_co_u32_e64 v50, s[6:7], s64, v146
	v_mul_f32_e32 v53, 0x45800000, v52
	v_cndmask_b32_e32 v52, v52, v53, vcc
	v_mul_f32_e32 v46, v46, v52
	v_mul_f32_e32 v47, v47, v52
	v_mul_f32_e32 v44, v44, v52
	v_mul_f32_e32 v45, v45, v52
	v_mul_f32_e32 v42, v42, v52
	v_mul_f32_e32 v43, v43, v52
	v_mul_f32_e32 v40, v40, v52
	v_mul_f32_e32 v41, v41, v52
	v_mul_f32_e32 v34, v34, v52
	v_mul_f32_e32 v35, v35, v52
	v_mul_f32_e32 v32, v32, v52
	v_mul_f32_e32 v33, v33, v52
	v_mul_f32_e32 v38, v38, v52
	v_mul_f32_e32 v39, v39, v52
	v_mul_f32_e32 v36, v36, v52
	v_mul_f32_e32 v37, v37, v52
	v_max_f32_e32 v44, 0, v44
	v_max_f32_e32 v40, 0, v40
	v_max_f32_e32 v45, 0, v45
	v_max_f32_e32 v41, 0, v41
	v_max_f32_e32 v46, 0, v46
	v_max_f32_e32 v42, 0, v42
	v_max_f32_e32 v47, 0, v47
	v_max_f32_e32 v43, 0, v43
	v_max_f32_e32 v32, 0, v32
	v_max_f32_e32 v33, 0, v33
	v_max_f32_e32 v34, 0, v34
	v_max_f32_e32 v35, 0, v35
	v_addc_co_u32_e64 v51, s[6:7], 0, v147, s[6:7]
	v_max_f32_e32 v36, 0, v36
	v_max_f32_e32 v37, 0, v37
	v_max_f32_e32 v38, 0, v38
	v_max_f32_e32 v39, 0, v39
	v_mul_f32_e32 v44, v44, v44
	v_mul_f32_e32 v40, v40, v40
	v_mul_f32_e32 v45, v45, v45
	v_mul_f32_e32 v41, v41, v41
	v_mul_f32_e32 v46, v46, v46
	v_mul_f32_e32 v42, v42, v42
	v_mul_f32_e32 v47, v47, v47
	v_mul_f32_e32 v43, v43, v43
	v_mul_f32_e32 v52, v32, v32
	v_mul_f32_e32 v53, v33, v33
	v_mul_f32_e32 v54, v34, v34
	v_mul_f32_e32 v55, v35, v35
	v_cvt_pk_bf16_f32 v32, v44, v45
	v_cvt_pk_bf16_f32 v33, v46, v47
	v_cvt_pk_bf16_f32 v34, v40, v41
	v_cvt_pk_bf16_f32 v35, v42, v43
	v_mul_f32_e32 v36, v36, v36
	v_mul_f32_e32 v37, v37, v37
	v_mul_f32_e32 v38, v38, v38
	v_mul_f32_e32 v39, v39, v39
	global_store_dwordx4 v[50:51], v[32:35], off nt
	s_nop 1
	v_cvt_pk_bf16_f32 v32, v36, v37
	v_cvt_pk_bf16_f32 v33, v38, v39
	v_cvt_pk_bf16_f32 v34, v52, v53
	v_cvt_pk_bf16_f32 v35, v54, v55
	global_store_dwordx4 v[48:49], v[32:35], off offset:256 nt
	global_load_dword v34, v[144:145], off offset:640
	s_nop 0
	v_lshl_add_u64 v[32:33], v[146:147], 0, s[24:25]
	s_waitcnt vmcnt(0)
; __device__ __forceinline__ unsigned cvt_pk_bf16(float lo, float hi) { unsigned r; asm volatile("v_cvt_pk_bf16_f32 %0, %1, %2" : "=v"(r) : "v"(lo), "v"(hi)); return r; }
; #define PG8_BAR __builtin_amdgcn_s_barrier()
; template <class Epi, class Sched, bool ALIGN_EPI = false, bool SP2 = false>
; __device__ __forceinline__ void gemm_phase(PG8_LAS unsigned char* lds, const Gemm g, const Sched& S, const Epi& E, int wv) {
;     ...
;         cur = nxt; cA = nA; cB = nB; ++ui;
;         if constexpr (ALIGN_EPI) { if (wr == 1) PG8_BAR; }
;     DI void operator()(const f32x4 (&acc)[2][2][4][2], const Unit& u, int wr, int wc, int fr, int fq) const {
;     ...
;             for (int m = 0; m < 4; ++m) { const int row = row0 + ai * 128 + m * 16; const float s = rsqrtf(ssum2[row] * (1.f / 1024.f) + EPS);
;                 bf16_t* rowp = U + (size_t)row * 4096 + col0;
; #pragma unroll
;                 for (int bj = 0; bj < 2; ++bj) { f32x4 v0 = acc[ai][bj][m][0] * s, v1 = acc[ai][bj][m][1] * s;
; #pragma unroll
;                     for (int j = 0; j < 4; ++j) { const float a = fmaxf(v0[j], 0.f), b = fmaxf(v1[j], 0.f); v0[j] = a * a; v1[j] = b * b; }
;                     u32x4 w; w.x = cvt_pk_bf16(v0[0], v0[1]); w.y = cvt_pk_bf16(v0[2], v0[3]); w.z = cvt_pk_bf16(v1[0], v1[1]); w.w = cvt_pk_bf16(v1[2], v1[3]);
;                     __builtin_nontemporal_store(w, (u32x4*)(rowp + bj * 128)); } }
	v_fmamk_f32 v34, v34, 0x3a800000, v158
	v_mul_f32_e32 v35, 0x4b800000, v34
	v_cmp_gt_f32_e32 vcc, s62, v34
	s_nop 1
	v_cndmask_b32_e32 v34, v34, v35, vcc
	v_rsq_f32_e32 v36, v34
	v_add_co_u32_e64 v34, s[6:7], s65, v146
	v_mul_f32_e32 v37, 0x45800000, v36
	v_cndmask_b32_e32 v36, v36, v37, vcc
	v_mul_f32_e32 v30, v30, v36
	v_mul_f32_e32 v31, v31, v36
	v_mul_f32_e32 v28, v28, v36
	v_mul_f32_e32 v29, v29, v36
	v_mul_f32_e32 v26, v26, v36
	v_mul_f32_e32 v27, v27, v36
	v_mul_f32_e32 v24, v24, v36
	v_mul_f32_e32 v25, v25, v36
	v_mul_f32_e32 v18, v18, v36
	v_mul_f32_e32 v19, v19, v36
	v_mul_f32_e32 v16, v16, v36
	v_mul_f32_e32 v17, v17, v36
	v_mul_f32_e32 v22, v22, v36
	v_mul_f32_e32 v23, v23, v36
	v_mul_f32_e32 v20, v20, v36
	v_mul_f32_e32 v21, v21, v36
	v_max_f32_e32 v28, 0, v28
	v_max_f32_e32 v24, 0, v24
	v_max_f32_e32 v29, 0, v29
	v_max_f32_e32 v25, 0, v25
	v_max_f32_e32 v30, 0, v30
	v_max_f32_e32 v26, 0, v26
	v_max_f32_e32 v31, 0, v31
	v_max_f32_e32 v27, 0, v27
	v_max_f32_e32 v16, 0, v16
	v_max_f32_e32 v17, 0, v17
	v_max_f32_e32 v18, 0, v18
	v_max_f32_e32 v19, 0, v19
	v_addc_co_u32_e64 v35, s[6:7], 0, v147, s[6:7]
	v_max_f32_e32 v20, 0, v20
	v_max_f32_e32 v21, 0, v21
	v_max_f32_e32 v22, 0, v22
	v_max_f32_e32 v23, 0, v23
	v_mul_f32_e32 v28, v28, v28
	v_mul_f32_e32 v24, v24, v24
	v_mul_f32_e32 v29, v29, v29
	v_mul_f32_e32 v25, v25, v25
	v_mul_f32_e32 v30, v30, v30
	v_mul_f32_e32 v26, v26, v26
	v_mul_f32_e32 v31, v31, v31
	v_mul_f32_e32 v27, v27, v27
	v_mul_f32_e32 v36, v16, v16
	v_mul_f32_e32 v37, v17, v17
	v_mul_f32_e32 v38, v18, v18
	v_mul_f32_e32 v39, v19, v19
	v_cvt_pk_bf16_f32 v16, v28, v29
	v_cvt_pk_bf16_f32 v17, v30, v31
	v_cvt_pk_bf16_f32 v18, v24, v25
	v_cvt_pk_bf16_f32 v19, v26, v27
	v_mul_f32_e32 v20, v20, v20
	v_mul_f32_e32 v21, v21, v21
	v_mul_f32_e32 v22, v22, v22
	v_mul_f32_e32 v23, v23, v23
	global_store_dwordx4 v[34:35], v[16:19], off nt
	s_andn2_b64 vcc, exec, s[4:5]
	s_nop 0
	v_cvt_pk_bf16_f32 v16, v20, v21
	v_cvt_pk_bf16_f32 v17, v22, v23
	v_cvt_pk_bf16_f32 v18, v36, v37
	v_cvt_pk_bf16_f32 v19, v38, v39
	global_store_dwordx4 v[32:33], v[16:19], off offset:256 nt
	global_load_dword v18, v[144:145], off offset:704
	s_nop 0
	v_lshl_add_u64 v[16:17], v[146:147], 0, s[26:27]
	s_waitcnt vmcnt(0)
	v_fmamk_f32 v18, v18, 0x3a800000, v158
	v_mul_f32_e32 v19, 0x4b800000, v18
	v_cmp_gt_f32_e64 s[4:5], s62, v18
	s_nop 1
	v_cndmask_b32_e64 v18, v18, v19, s[4:5]
	v_rsq_f32_e32 v20, v18
	v_add_co_u32_e64 v18, s[6:7], s66, v146
	v_mul_f32_e32 v21, 0x45800000, v20
	v_cndmask_b32_e64 v20, v20, v21, s[4:5]
	v_mul_f32_e32 v14, v14, v20
	v_mul_f32_e32 v15, v15, v20
	v_mul_f32_e32 v12, v12, v20
	v_mul_f32_e32 v13, v13, v20
	v_mul_f32_e32 v10, v10, v20
	v_mul_f32_e32 v11, v11, v20
	v_mul_f32_e32 v8, v8, v20
	v_mul_f32_e32 v9, v9, v20
	v_mul_f32_e32 v2, v2, v20
	v_mul_f32_e32 v3, v3, v20
	v_mul_f32_e32 v0, v0, v20
	v_mul_f32_e32 v1, v1, v20
	v_mul_f32_e32 v6, v6, v20
	v_mul_f32_e32 v7, v7, v20
	v_mul_f32_e32 v4, v4, v20
	v_mul_f32_e32 v5, v5, v20
	v_max_f32_e32 v12, 0, v12
	v_max_f32_e32 v8, 0, v8
	v_max_f32_e32 v13, 0, v13
	v_max_f32_e32 v9, 0, v9
	v_max_f32_e32 v14, 0, v14
	v_max_f32_e32 v10, 0, v10
	v_max_f32_e32 v15, 0, v15
	v_max_f32_e32 v11, 0, v11
	v_max_f32_e32 v0, 0, v0
	v_max_f32_e32 v1, 0, v1
	v_max_f32_e32 v2, 0, v2
	v_max_f32_e32 v3, 0, v3
	v_addc_co_u32_e64 v19, s[6:7], 0, v147, s[6:7]
	v_max_f32_e32 v4, 0, v4
	v_max_f32_e32 v5, 0, v5
	v_max_f32_e32 v6, 0, v6
	v_max_f32_e32 v7, 0, v7
	v_mul_f32_e32 v12, v12, v12
	v_mul_f32_e32 v8, v8, v8
	v_mul_f32_e32 v13, v13, v13
	v_mul_f32_e32 v9, v9, v9
	v_mul_f32_e32 v14, v14, v14
	v_mul_f32_e32 v10, v10, v10
	v_mul_f32_e32 v15, v15, v15
	v_mul_f32_e32 v11, v11, v11
	v_mul_f32_e32 v20, v0, v0
	v_mul_f32_e32 v21, v1, v1
	v_mul_f32_e32 v22, v2, v2
	v_mul_f32_e32 v23, v3, v3
	v_cvt_pk_bf16_f32 v0, v12, v13
	v_cvt_pk_bf16_f32 v1, v14, v15
	v_cvt_pk_bf16_f32 v2, v8, v9
	v_cvt_pk_bf16_f32 v3, v10, v11
	s_mov_b64 s[4:5], -1
	v_mul_f32_e32 v4, v4, v4
	v_mul_f32_e32 v5, v5, v5
	v_mul_f32_e32 v6, v6, v6
	v_mul_f32_e32 v7, v7, v7
	global_store_dwordx4 v[18:19], v[0:3], off nt
	s_nop 1
	v_cvt_pk_bf16_f32 v0, v4, v5
	v_cvt_pk_bf16_f32 v1, v6, v7
	v_cvt_pk_bf16_f32 v2, v20, v21
	v_cvt_pk_bf16_f32 v3, v22, v23
	global_store_dwordx4 v[16:17], v[0:3], off offset:256 nt
	s_cbranch_vccnz .LBB0_2059
	s_andn2_b64 vcc, exec, s[8:9]
	s_cbranch_vccnz .LBB0_2058
	s_barrier
	s_branch .LBB0_2058

;     DI void operator()(const f32x4 (&acc)[2][2][4][2], const Unit& u, int wr, int wc, int fr, int fq) const {
;     ...
;             for (int m = 0; m < 4; ++m) { const size_t off = (size_t)(row0 + ai * 128 + m * 16) * 1024 + col0;
; #pragma unroll
;                 for (int bj = 0; bj < 2; ++bj) { const size_t o = off + bj * 128; const u32x4 r = *(const u32x4*)(x1b + o); f32x4 v0, v1;
;                     v0[0] = __uint_as_float(r.x << 16); v0[1] = __uint_as_float(r.x & 0xffff0000u); v0[2] = __uint_as_float(r.y << 16); v0[3] = __uint_as_float(r.y & 0xffff0000u);
;                     v1[0] = __uint_as_float(r.z << 16); v1[1] = __uint_as_float(r.z & 0xffff0000u); v1[2] = __uint_as_float(r.w << 16); v1[3] = __uint_as_float(r.w & 0xffff0000u);
;                     __builtin_nontemporal_store(v0 + acc[ai][bj][m][0], (f32x4*)(out + o)); __builtin_nontemporal_store(v1 + acc[ai][bj][m][1], (f32x4*)(out + o + 4)); } }
.LBB0_2105:
	v_lshl_add_u32 v148, s28, 8, v150
	v_lshl_or_b32 v146, s54, 8, v152
	v_ashrrev_i32_e32 v149, 31, v148
	v_ashrrev_i32_e32 v147, 31, v146
	v_lshlrev_b64 v[144:145], 10, v[148:149]
	v_lshl_add_u64 v[144:145], v[144:145], 0, v[146:147]
	v_lshl_add_u64 v[160:161], v[144:145], 1, s[34:35]
	global_load_dwordx4 v[156:159], v[160:161], off
	v_lshl_add_u64 v[162:163], v[144:145], 2, s[30:31]
	s_andn2_b64 vcc, exec, s[0:1]
	s_mov_b64 s[0:1], -1
	s_waitcnt vmcnt(0)
	v_lshlrev_b32_e32 v164, 16, v156
	v_and_b32_e32 v165, 0xffff0000, v156
	v_lshlrev_b32_e32 v156, 16, v157
	v_and_b32_e32 v157, 0xffff0000, v157
	v_lshlrev_b32_e32 v166, 16, v158
	v_and_b32_e32 v167, 0xffff0000, v158
	v_lshlrev_b32_e32 v158, 16, v159
	v_and_b32_e32 v159, 0xffff0000, v159
	v_add_f32_e32 v126, v126, v156
	v_add_f32_e32 v127, v127, v157
	v_add_f32_e32 v124, v124, v164
	v_add_f32_e32 v125, v125, v165
	v_add_f32_e32 v122, v122, v158
	v_add_f32_e32 v123, v123, v159
	v_add_f32_e32 v120, v120, v166
	v_add_f32_e32 v121, v121, v167
	global_store_dwordx4 v[162:163], v[124:127], off nt
	global_store_dwordx4 v[162:163], v[120:123], off offset:16 nt
	global_load_dwordx4 v[120:123], v[160:161], off offset:256
	v_or_b32_e32 v124, 16, v148
	v_ashrrev_i32_e32 v125, 31, v124
	v_lshlrev_b64 v[124:125], 10, v[124:125]
	v_lshl_add_u64 v[124:125], v[124:125], 0, v[146:147]
	v_lshl_add_u64 v[126:127], v[124:125], 1, s[34:35]
	s_waitcnt vmcnt(0)
	v_lshlrev_b32_e32 v156, 16, v120
	v_and_b32_e32 v157, 0xffff0000, v120
	v_lshlrev_b32_e32 v120, 16, v121
	v_and_b32_e32 v121, 0xffff0000, v121
	v_lshlrev_b32_e32 v158, 16, v122
	v_and_b32_e32 v159, 0xffff0000, v122
	v_lshlrev_b32_e32 v122, 16, v123
	v_and_b32_e32 v123, 0xffff0000, v123
	v_add_f32_e32 v118, v118, v120
	v_add_f32_e32 v119, v119, v121
	v_add_f32_e32 v116, v116, v156
	v_add_f32_e32 v117, v117, v157
	v_add_f32_e32 v114, v114, v122
	v_add_f32_e32 v115, v115, v123
	v_add_f32_e32 v112, v112, v158
	v_add_f32_e32 v113, v113, v159
	global_store_dwordx4 v[162:163], v[116:119], off offset:512 nt
	global_store_dwordx4 v[162:163], v[112:115], off offset:528 nt
	global_load_dwordx4 v[112:115], v[126:127], off
	v_lshl_add_u64 v[116:117], v[124:125], 2, s[30:31]
	s_waitcnt vmcnt(0)
	v_lshlrev_b32_e32 v118, 16, v112
	v_and_b32_e32 v119, 0xffff0000, v112
	v_lshlrev_b32_e32 v112, 16, v113
	v_and_b32_e32 v113, 0xffff0000, v113
	v_lshlrev_b32_e32 v120, 16, v114
	v_and_b32_e32 v121, 0xffff0000, v114
	v_lshlrev_b32_e32 v114, 16, v115
	v_and_b32_e32 v115, 0xffff0000, v115
	v_add_f32_e32 v110, v110, v112
	v_add_f32_e32 v111, v111, v113
	v_add_f32_e32 v108, v108, v118
	v_add_f32_e32 v109, v109, v119
	v_add_f32_e32 v106, v106, v114
	v_add_f32_e32 v107, v107, v115
	v_add_f32_e32 v104, v104, v120
	v_add_f32_e32 v105, v105, v121
	global_store_dwordx4 v[116:117], v[108:111], off nt
	global_store_dwordx4 v[116:117], v[104:107], off offset:16 nt
	global_load_dwordx4 v[104:107], v[126:127], off offset:256
	v_or_b32_e32 v108, 32, v148
	v_ashrrev_i32_e32 v109, 31, v108
	v_lshlrev_b64 v[108:109], 10, v[108:109]
	v_lshl_add_u64 v[108:109], v[108:109], 0, v[146:147]
	v_lshl_add_u64 v[110:111], v[108:109], 1, s[34:35]
	s_waitcnt vmcnt(0)
	v_lshlrev_b32_e32 v112, 16, v104
	v_and_b32_e32 v113, 0xffff0000, v104
	v_lshlrev_b32_e32 v104, 16, v105
	v_and_b32_e32 v105, 0xffff0000, v105
	v_lshlrev_b32_e32 v114, 16, v106
	v_and_b32_e32 v115, 0xffff0000, v106
	v_lshlrev_b32_e32 v106, 16, v107
	v_and_b32_e32 v107, 0xffff0000, v107
	v_add_f32_e32 v102, v102, v104
	v_add_f32_e32 v103, v103, v105
	v_add_f32_e32 v100, v100, v112
	v_add_f32_e32 v101, v101, v113
	v_add_f32_e32 v98, v98, v106
	v_add_f32_e32 v99, v99, v107
	v_add_f32_e32 v96, v96, v114
	v_add_f32_e32 v97, v97, v115
	global_store_dwordx4 v[116:117], v[100:103], off offset:512 nt
	global_store_dwordx4 v[116:117], v[96:99], off offset:528 nt
	global_load_dwordx4 v[96:99], v[110:111], off
	v_lshl_add_u64 v[100:101], v[108:109], 2, s[30:31]
	s_waitcnt vmcnt(0)
	v_lshlrev_b32_e32 v102, 16, v96
	v_and_b32_e32 v103, 0xffff0000, v96
	v_lshlrev_b32_e32 v96, 16, v97
	v_and_b32_e32 v97, 0xffff0000, v97
	v_lshlrev_b32_e32 v104, 16, v98
	v_and_b32_e32 v105, 0xffff0000, v98
	v_lshlrev_b32_e32 v98, 16, v99
	v_and_b32_e32 v99, 0xffff0000, v99
	v_add_f32_e32 v94, v94, v96
	v_add_f32_e32 v95, v95, v97
	v_add_f32_e32 v92, v92, v102
	v_add_f32_e32 v93, v93, v103
	v_add_f32_e32 v90, v90, v98
	v_add_f32_e32 v91, v91, v99
	v_add_f32_e32 v88, v88, v104
	v_add_f32_e32 v89, v89, v105
	global_store_dwordx4 v[100:101], v[92:95], off nt
	global_store_dwordx4 v[100:101], v[88:91], off offset:16 nt
	global_load_dwordx4 v[88:91], v[110:111], off offset:256
	v_or_b32_e32 v92, 48, v148
	v_ashrrev_i32_e32 v93, 31, v92
	v_lshlrev_b64 v[92:93], 10, v[92:93]
	v_lshl_add_u64 v[92:93], v[92:93], 0, v[146:147]
	v_lshl_add_u64 v[94:95], v[92:93], 1, s[34:35]
	s_waitcnt vmcnt(0)
	v_lshlrev_b32_e32 v96, 16, v88
	v_and_b32_e32 v97, 0xffff0000, v88
	v_lshlrev_b32_e32 v88, 16, v89
	v_and_b32_e32 v89, 0xffff0000, v89
	v_lshlrev_b32_e32 v98, 16, v90
	v_and_b32_e32 v99, 0xffff0000, v90
	v_lshlrev_b32_e32 v90, 16, v91
	v_and_b32_e32 v91, 0xffff0000, v91
	v_add_f32_e32 v86, v86, v88
	v_add_f32_e32 v87, v87, v89
	v_add_f32_e32 v84, v84, v96
	v_add_f32_e32 v85, v85, v97
	v_add_f32_e32 v82, v82, v90
	v_add_f32_e32 v83, v83, v91
	v_add_f32_e32 v80, v80, v98
	v_add_f32_e32 v81, v81, v99
	global_store_dwordx4 v[100:101], v[84:87], off offset:512 nt
	global_store_dwordx4 v[100:101], v[80:83], off offset:528 nt
	global_load_dwordx4 v[80:83], v[94:95], off
	v_lshl_add_u64 v[84:85], v[92:93], 2, s[30:31]
	s_waitcnt vmcnt(0)
;     DI void operator()(const f32x4 (&acc)[2][2][4][2], const Unit& u, int wr, int wc, int fr, int fq) const {
;     ...
;             for (int m = 0; m < 4; ++m) { const size_t off = (size_t)(row0 + ai * 128 + m * 16) * 1024 + col0;
; #pragma unroll
;                 for (int bj = 0; bj < 2; ++bj) { const size_t o = off + bj * 128; const u32x4 r = *(const u32x4*)(x1b + o); f32x4 v0, v1;
;                     v0[0] = __uint_as_float(r.x << 16); v0[1] = __uint_as_float(r.x & 0xffff0000u); v0[2] = __uint_as_float(r.y << 16); v0[3] = __uint_as_float(r.y & 0xffff0000u);
;                     v1[0] = __uint_as_float(r.z << 16); v1[1] = __uint_as_float(r.z & 0xffff0000u); v1[2] = __uint_as_float(r.w << 16); v1[3] = __uint_as_float(r.w & 0xffff0000u);
;                     __builtin_nontemporal_store(v0 + acc[ai][bj][m][0], (f32x4*)(out + o)); __builtin_nontemporal_store(v1 + acc[ai][bj][m][1], (f32x4*)(out + o + 4)); } }
	v_lshlrev_b32_e32 v86, 16, v80
	v_and_b32_e32 v87, 0xffff0000, v80
	v_lshlrev_b32_e32 v80, 16, v81
	v_and_b32_e32 v81, 0xffff0000, v81
	v_lshlrev_b32_e32 v88, 16, v82
	v_and_b32_e32 v89, 0xffff0000, v82
	v_lshlrev_b32_e32 v82, 16, v83
	v_and_b32_e32 v83, 0xffff0000, v83
	v_add_f32_e32 v78, v78, v80
	v_add_f32_e32 v79, v79, v81
	v_add_f32_e32 v76, v76, v86
	v_add_f32_e32 v77, v77, v87
	v_add_f32_e32 v74, v74, v82
	v_add_f32_e32 v75, v75, v83
	v_add_f32_e32 v72, v72, v88
	v_add_f32_e32 v73, v73, v89
	global_store_dwordx4 v[84:85], v[76:79], off nt
	global_store_dwordx4 v[84:85], v[72:75], off offset:16 nt
	global_load_dwordx4 v[72:75], v[94:95], off offset:256
	v_lshl_add_u64 v[76:77], v[144:145], 0, s[8:9]
	v_lshl_add_u64 v[78:79], v[76:77], 1, s[34:35]
	s_waitcnt vmcnt(0)
	v_lshlrev_b32_e32 v80, 16, v72
	v_and_b32_e32 v81, 0xffff0000, v72
	v_lshlrev_b32_e32 v72, 16, v73
	v_and_b32_e32 v73, 0xffff0000, v73
	v_lshlrev_b32_e32 v82, 16, v74
	v_and_b32_e32 v83, 0xffff0000, v74
	v_lshlrev_b32_e32 v74, 16, v75
	v_and_b32_e32 v75, 0xffff0000, v75
	v_add_f32_e32 v70, v70, v72
	v_add_f32_e32 v71, v71, v73
	v_add_f32_e32 v68, v68, v80
	v_add_f32_e32 v69, v69, v81
	v_add_f32_e32 v66, v66, v74
	v_add_f32_e32 v67, v67, v75
	v_add_f32_e32 v64, v64, v82
	v_add_f32_e32 v65, v65, v83
	global_store_dwordx4 v[84:85], v[68:71], off offset:512 nt
	global_store_dwordx4 v[84:85], v[64:67], off offset:528 nt
	global_load_dwordx4 v[64:67], v[78:79], off
	v_lshl_add_u64 v[68:69], v[76:77], 2, s[30:31]
	s_waitcnt vmcnt(0)
	v_lshlrev_b32_e32 v70, 16, v64
	v_and_b32_e32 v71, 0xffff0000, v64
	v_lshlrev_b32_e32 v64, 16, v65
	v_and_b32_e32 v65, 0xffff0000, v65
	v_lshlrev_b32_e32 v72, 16, v66
	v_and_b32_e32 v73, 0xffff0000, v66
	v_lshlrev_b32_e32 v66, 16, v67
	v_and_b32_e32 v67, 0xffff0000, v67
	v_add_f32_e32 v62, v62, v64
	v_add_f32_e32 v63, v63, v65
	v_add_f32_e32 v60, v60, v70
	v_add_f32_e32 v61, v61, v71
	v_add_f32_e32 v58, v58, v66
	v_add_f32_e32 v59, v59, v67
	v_add_f32_e32 v56, v56, v72
	v_add_f32_e32 v57, v57, v73
	global_store_dwordx4 v[68:69], v[60:63], off nt
	global_store_dwordx4 v[68:69], v[56:59], off offset:16 nt
	global_load_dwordx4 v[56:59], v[78:79], off offset:256
	v_lshl_add_u64 v[60:61], v[144:145], 0, s[12:13]
	v_lshl_add_u64 v[62:63], v[60:61], 1, s[34:35]
	s_waitcnt vmcnt(0)
	v_lshlrev_b32_e32 v64, 16, v56
	v_and_b32_e32 v65, 0xffff0000, v56
	v_lshlrev_b32_e32 v56, 16, v57
	v_and_b32_e32 v57, 0xffff0000, v57
	v_lshlrev_b32_e32 v66, 16, v58
	v_and_b32_e32 v67, 0xffff0000, v58
	v_lshlrev_b32_e32 v58, 16, v59
	v_and_b32_e32 v59, 0xffff0000, v59
	v_add_f32_e32 v54, v54, v56
	v_add_f32_e32 v55, v55, v57
	v_add_f32_e32 v52, v52, v64
	v_add_f32_e32 v53, v53, v65
	v_add_f32_e32 v50, v50, v58
	v_add_f32_e32 v51, v51, v59
	v_add_f32_e32 v48, v48, v66
	v_add_f32_e32 v49, v49, v67
	global_store_dwordx4 v[68:69], v[52:55], off offset:512 nt
	global_store_dwordx4 v[68:69], v[48:51], off offset:528 nt
	global_load_dwordx4 v[48:51], v[62:63], off
	v_lshl_add_u64 v[52:53], v[60:61], 2, s[30:31]
	s_waitcnt vmcnt(0)
	v_lshlrev_b32_e32 v54, 16, v48
	v_and_b32_e32 v55, 0xffff0000, v48
	v_lshlrev_b32_e32 v48, 16, v49
	v_and_b32_e32 v49, 0xffff0000, v49
	v_lshlrev_b32_e32 v56, 16, v50
	v_and_b32_e32 v57, 0xffff0000, v50
	v_lshlrev_b32_e32 v50, 16, v51
	v_and_b32_e32 v51, 0xffff0000, v51
	v_add_f32_e32 v46, v46, v48
	v_add_f32_e32 v47, v47, v49
	v_add_f32_e32 v44, v44, v54
	v_add_f32_e32 v45, v45, v55
	v_add_f32_e32 v42, v42, v50
	v_add_f32_e32 v43, v43, v51
	v_add_f32_e32 v40, v40, v56
	v_add_f32_e32 v41, v41, v57
	global_store_dwordx4 v[52:53], v[44:47], off nt
	global_store_dwordx4 v[52:53], v[40:43], off offset:16 nt
	global_load_dwordx4 v[40:43], v[62:63], off offset:256
	v_lshl_add_u64 v[44:45], v[144:145], 0, s[16:17]
	v_lshl_add_u64 v[46:47], v[44:45], 1, s[34:35]
	s_waitcnt vmcnt(0)
; #define PG8_BAR __builtin_amdgcn_s_barrier()
; template <class Epi, class Sched, bool ALIGN_EPI = false, bool SP2 = false>
; __device__ __forceinline__ void gemm_phase(PG8_LAS unsigned char* lds, const Gemm g, const Sched& S, const Epi& E, int wv) {
;     ...
;         cur = nxt; cA = nA; cB = nB; ++ui;
;         if constexpr (ALIGN_EPI) { if (wr == 1) PG8_BAR; }
;     DI void operator()(const f32x4 (&acc)[2][2][4][2], const Unit& u, int wr, int wc, int fr, int fq) const {
;     ...
;             for (int m = 0; m < 4; ++m) { const size_t off = (size_t)(row0 + ai * 128 + m * 16) * 1024 + col0;
; #pragma unroll
;                 for (int bj = 0; bj < 2; ++bj) { const size_t o = off + bj * 128; const u32x4 r = *(const u32x4*)(x1b + o); f32x4 v0, v1;
;                     v0[0] = __uint_as_float(r.x << 16); v0[1] = __uint_as_float(r.x & 0xffff0000u); v0[2] = __uint_as_float(r.y << 16); v0[3] = __uint_as_float(r.y & 0xffff0000u);
;                     v1[0] = __uint_as_float(r.z << 16); v1[1] = __uint_as_float(r.z & 0xffff0000u); v1[2] = __uint_as_float(r.w << 16); v1[3] = __uint_as_float(r.w & 0xffff0000u);
;                     __builtin_nontemporal_store(v0 + acc[ai][bj][m][0], (f32x4*)(out + o)); __builtin_nontemporal_store(v1 + acc[ai][bj][m][1], (f32x4*)(out + o + 4)); } }
	v_lshlrev_b32_e32 v48, 16, v40
	v_and_b32_e32 v49, 0xffff0000, v40
	v_lshlrev_b32_e32 v40, 16, v41
	v_and_b32_e32 v41, 0xffff0000, v41
	v_lshlrev_b32_e32 v50, 16, v42
	v_and_b32_e32 v51, 0xffff0000, v42
	v_lshlrev_b32_e32 v42, 16, v43
	v_and_b32_e32 v43, 0xffff0000, v43
	v_add_f32_e32 v38, v38, v40
	v_add_f32_e32 v39, v39, v41
	v_add_f32_e32 v36, v36, v48
	v_add_f32_e32 v37, v37, v49
	v_add_f32_e32 v34, v34, v42
	v_add_f32_e32 v35, v35, v43
	v_add_f32_e32 v32, v32, v50
	v_add_f32_e32 v33, v33, v51
	global_store_dwordx4 v[52:53], v[36:39], off offset:512 nt
	global_store_dwordx4 v[52:53], v[32:35], off offset:528 nt
	global_load_dwordx4 v[32:35], v[46:47], off
	v_lshl_add_u64 v[36:37], v[44:45], 2, s[30:31]
	s_waitcnt vmcnt(0)
	v_lshlrev_b32_e32 v38, 16, v32
	v_and_b32_e32 v39, 0xffff0000, v32
	v_lshlrev_b32_e32 v32, 16, v33
	v_and_b32_e32 v33, 0xffff0000, v33
	v_lshlrev_b32_e32 v40, 16, v34
	v_and_b32_e32 v41, 0xffff0000, v34
	v_lshlrev_b32_e32 v34, 16, v35
	v_and_b32_e32 v35, 0xffff0000, v35
	v_add_f32_e32 v30, v30, v32
	v_add_f32_e32 v31, v31, v33
	v_add_f32_e32 v28, v28, v38
	v_add_f32_e32 v29, v29, v39
	v_add_f32_e32 v26, v26, v34
	v_add_f32_e32 v27, v27, v35
	v_add_f32_e32 v24, v24, v40
	v_add_f32_e32 v25, v25, v41
	global_store_dwordx4 v[36:37], v[28:31], off nt
	global_store_dwordx4 v[36:37], v[24:27], off offset:16 nt
	global_load_dwordx4 v[24:27], v[46:47], off offset:256
	v_lshl_add_u64 v[28:29], v[144:145], 0, s[18:19]
	v_lshl_add_u64 v[30:31], v[28:29], 1, s[34:35]
	s_waitcnt vmcnt(0)
	v_lshlrev_b32_e32 v32, 16, v24
	v_and_b32_e32 v33, 0xffff0000, v24
	v_lshlrev_b32_e32 v24, 16, v25
	v_and_b32_e32 v25, 0xffff0000, v25
	v_lshlrev_b32_e32 v34, 16, v26
	v_and_b32_e32 v35, 0xffff0000, v26
	v_lshlrev_b32_e32 v26, 16, v27
	v_and_b32_e32 v27, 0xffff0000, v27
	v_add_f32_e32 v22, v22, v24
	v_add_f32_e32 v23, v23, v25
	v_add_f32_e32 v20, v20, v32
	v_add_f32_e32 v21, v21, v33
	v_add_f32_e32 v18, v18, v26
	v_add_f32_e32 v19, v19, v27
	v_add_f32_e32 v16, v16, v34
	v_add_f32_e32 v17, v17, v35
	global_store_dwordx4 v[36:37], v[20:23], off offset:512 nt
	global_store_dwordx4 v[36:37], v[16:19], off offset:528 nt
	global_load_dwordx4 v[16:19], v[30:31], off
	v_lshl_add_u64 v[20:21], v[28:29], 2, s[30:31]
	s_waitcnt vmcnt(0)
	v_lshlrev_b32_e32 v22, 16, v16
	v_and_b32_e32 v23, 0xffff0000, v16
	v_lshlrev_b32_e32 v16, 16, v17
	v_and_b32_e32 v17, 0xffff0000, v17
	v_lshlrev_b32_e32 v24, 16, v18
	v_and_b32_e32 v25, 0xffff0000, v18
	v_lshlrev_b32_e32 v18, 16, v19
	v_and_b32_e32 v19, 0xffff0000, v19
	v_add_f32_e32 v14, v14, v16
	v_add_f32_e32 v15, v15, v17
	v_add_f32_e32 v12, v12, v22
	v_add_f32_e32 v13, v13, v23
	v_add_f32_e32 v10, v10, v18
	v_add_f32_e32 v11, v11, v19
	v_add_f32_e32 v8, v8, v24
	v_add_f32_e32 v9, v9, v25
	global_store_dwordx4 v[20:21], v[12:15], off nt
	global_store_dwordx4 v[20:21], v[8:11], off offset:16 nt
	global_load_dwordx4 v[8:11], v[30:31], off offset:256
	s_waitcnt vmcnt(0)
	v_lshlrev_b32_e32 v12, 16, v8
	v_and_b32_e32 v13, 0xffff0000, v8
	v_lshlrev_b32_e32 v8, 16, v9
	v_and_b32_e32 v9, 0xffff0000, v9
	v_lshlrev_b32_e32 v14, 16, v10
	v_and_b32_e32 v15, 0xffff0000, v10
	v_lshlrev_b32_e32 v10, 16, v11
	v_and_b32_e32 v11, 0xffff0000, v11
	v_add_f32_e32 v6, v6, v8
	v_add_f32_e32 v7, v7, v9
	v_add_f32_e32 v4, v4, v12
	v_add_f32_e32 v5, v5, v13
	v_add_f32_e32 v2, v2, v10
	v_add_f32_e32 v3, v3, v11
	v_add_f32_e32 v0, v0, v14
	v_add_f32_e32 v1, v1, v15
	global_store_dwordx4 v[20:21], v[4:7], off offset:512 nt
	global_store_dwordx4 v[20:21], v[0:3], off offset:528 nt
	s_cbranch_vccnz .LBB0_2094
	s_andn2_b64 vcc, exec, s[2:3]
	s_cbranch_vccnz .LBB0_2093
	s_barrier
	s_branch .LBB0_2093
